# v8: + GEMM K-loops: first trip peeled with C=0 MFMAs, 256 accumulator-zeroing moves per tile removed
# speedup vs baseline: 1.0266x; 1.0127x over previous
; #define PG8_STAGE(bufoff, gbase, voff) do { _Pragma("unroll") for (int _i = 0; _i < 2; ++_i) \
;         __builtin_amdgcn_global_load_lds((const unsigned*)((const char*)(gbase) + (voff)[_i]), (LAS unsigned*)(lds + (bufoff) + ldsw + _i * 8192), 16, 0, 0); } while (0)
; #define PG8_LDA(dst, b, h) do { _Pragma("unroll") for (int m = 0; m < 4; ++m) _Pragma("unroll") for (int k = 0; k < 2; ++k) dst[m][k] = *(const LAS bf16x8*)(lds + PG8_SA(b, h) + aoff + m * 2048 + k * 1024); } while (0)
; #define PG8_LDB(dst, b, h) do { _Pragma("unroll") for (int n = 0; n < 2; ++n) _Pragma("unroll") for (int k = 0; k < 2; ++k) dst[n][k] = *(const LAS bf16x8*)(lds + PG8_SB(b, h) + boff + n * 2048 + k * 1024); } while (0)
; #define PG8_MMA(ai, bj, At, Bt) do { __builtin_amdgcn_s_setprio(1); _Pragma("unroll") for (int m = 0; m < 4; ++m) _Pragma("unroll") for (int n = 0; n < 2; ++n) _Pragma("unroll") for (int k = 0; k < 2; ++k) \
;         acc[ai][bj][m][n] = __builtin_amdgcn_mfma_f32_16x16x32_bf16(Bt[n][k], At[m][k], acc[ai][bj][m][n], 0, 0, 0); __builtin_amdgcn_s_setprio(0); } while (0)
; #define PG8_WAIT_L(n) asm volatile("s_waitcnt lgkmcnt(" #n ")" ::: "memory")
; #define PG8_BAR __builtin_amdgcn_s_barrier()
; #define PG8_SCHED __builtin_amdgcn_sched_barrier(0)
; template <class Epi>
; DI void gemm_phase(LAS unsigned char* lds, const Gemm g, const StaticOrder& S, const Epi& E) {
;     ...
;             const bool last = (t == nt - 2);
;             const char* a1 = cA + (size_t)(t + 1) * kstep;
;             const char* a2 = last ? nA : cA + (size_t)(t + 2) * kstep; const char* b2 = last ? nB : cB + (size_t)(t + 2) * kstep;
;             const char* a3 = a2 + kstep; const char* b3 = b2 + kstep;
;             PG8_LDB(B0, 0, 0); PG8_SCHED; PG8_LDA(At, 0, 0); PG8_STAGE(PG8_SA(1, 1), a1 + hstep, voffA);
;             PG8_WAIT_L(8); PG8_BAR; PG8_WAIT_L(0); PG8_MMA(0, 0, At, B0); PG8_BAR; PG8_SCHED;
;             PG8_LDB(B1, 0, 1); PG8_STAGE(PG8_SB(0, 0), b2, voffB);
;             PG8_BAR; PG8_WAIT_L(0); PG8_MMA(0, 1, At, B1); PG8_BAR;
;             PG8_LDA(At, 0, 1); PG8_STAGE(PG8_SA(0, 0), a2, voffA);
;             PG8_BAR; PG8_WAIT_L(0); PG8_MMA(1, 0, At, B0); PG8_BAR; PG8_SCHED;
.LBB0_397:
	s_andn2_b64 vcc, exec, s[72:73]
	s_waitcnt lgkmcnt(0)
	s_cbranch_vccnz .LBB0_400
	s_add_u32 s2, s2, 0x80
	s_addc_u32 s3, s3, 0
	s_add_u32 s14, s10, 0x100
	s_addc_u32 s15, s11, 0
	s_mov_b32 s4, 0
	s_mov_b32 s33, 0x1c000
	s_add_i32 s5, s4, 2
	s_add_u32 s10, s2, 0x80
	s_addc_u32 s11, s3, 0
	s_add_i32 s17, s56, 0x100
	v_add_u32_e32 v140, s17, v190
	ds_read_b128 v[128:131], v140
	ds_read_b128 v[132:135], v140 offset:1024
	ds_read_b128 v[136:139], v140 offset:2048
	ds_read_b128 v[140:143], v140 offset:3072
	s_cmp_eq_u32 s70, s4
	s_cselect_b32 s11, s53, s11
	s_cselect_b32 s10, s52, s10
	s_cselect_b32 s13, s59, s15
	s_cselect_b32 s12, s58, s14
	v_lshl_add_u64 v[162:163], s[2:3], 0, v[150:151]
	s_add_i32 m0, s87, 0xc000
	ds_read_b128 v[154:157], v191
	ds_read_b128 v[158:161], v191 offset:1024
	ds_read_b128 v[170:173], v191 offset:2048
	ds_read_b128 v[174:177], v191 offset:3072
	ds_read_b128 v[178:181], v191 offset:4096
	ds_read_b128 v[192:195], v191 offset:5120
	ds_read_b128 v[196:199], v191 offset:6144
	ds_read_b128 v[200:203], v191 offset:7168
	global_load_lds_dwordx4 v[162:163], off
	v_lshl_add_u64 v[162:163], s[2:3], 0, v[152:153]
	s_add_i32 m0, s87, 0xe000
	s_nop 0
	global_load_lds_dwordx4 v[162:163], off
	s_waitcnt lgkmcnt(8)
	s_barrier
	s_waitcnt lgkmcnt(0)
	s_setprio 1
	s_waitcnt lgkmcnt(0)
	v_mfma_f32_16x16x32_bf16 v[124:127], v[128:131], v[154:157], 0
	v_mfma_f32_16x16x32_bf16 v[120:123], v[136:139], v[154:157], 0
	v_mfma_f32_16x16x32_bf16 v[108:111], v[128:131], v[170:173], 0
	v_mfma_f32_16x16x32_bf16 v[104:107], v[136:139], v[170:173], 0
	v_mfma_f32_16x16x32_bf16 v[92:95], v[128:131], v[178:181], 0
	v_mfma_f32_16x16x32_bf16 v[88:91], v[136:139], v[178:181], 0
	v_mfma_f32_16x16x32_bf16 v[76:79], v[128:131], v[196:199], 0
	v_mfma_f32_16x16x32_bf16 v[72:75], v[136:139], v[196:199], 0
	v_mfma_f32_16x16x32_bf16 v[124:127], v[132:135], v[158:161], v[124:127]
	v_mfma_f32_16x16x32_bf16 v[120:123], v[140:143], v[158:161], v[120:123]
	v_mfma_f32_16x16x32_bf16 v[108:111], v[132:135], v[174:177], v[108:111]
	v_mfma_f32_16x16x32_bf16 v[104:107], v[140:143], v[174:177], v[104:107]
	v_mfma_f32_16x16x32_bf16 v[92:95], v[132:135], v[192:195], v[92:95]
	v_mfma_f32_16x16x32_bf16 v[88:91], v[140:143], v[192:195], v[88:91]
	v_mfma_f32_16x16x32_bf16 v[76:79], v[132:135], v[200:203], v[76:79]
	v_mfma_f32_16x16x32_bf16 v[72:75], v[140:143], v[200:203], v[72:75]
	s_setprio 0
	s_barrier
	s_add_i32 s4, s57, 0x100
	v_add_u32_e32 v162, s4, v190
	s_add_i32 s17, s17, s37
	ds_read_b128 v[204:207], v162
	ds_read_b128 v[208:211], v162 offset:1024
	ds_read_b128 v[212:215], v162 offset:2048
	ds_read_b128 v[216:219], v162 offset:3072
	v_lshl_add_u64 v[162:163], s[12:13], 0, v[166:167]
	s_mov_b32 m0, s17
	v_lshl_add_u64 v[182:183], s[12:13], 0, v[148:149]
	global_load_lds_dwordx4 v[162:163], off
	s_add_i32 m0, s17, 0x2000
	s_nop 0
	global_load_lds_dwordx4 v[182:183], off
	s_barrier
	s_waitcnt lgkmcnt(0)
	s_setprio 1
	s_waitcnt lgkmcnt(0)
	v_mfma_f32_16x16x32_bf16 v[116:119], v[204:207], v[154:157], 0
	v_mfma_f32_16x16x32_bf16 v[112:115], v[212:215], v[154:157], 0
	v_mfma_f32_16x16x32_bf16 v[100:103], v[204:207], v[170:173], 0
	v_mfma_f32_16x16x32_bf16 v[96:99], v[212:215], v[170:173], 0
	v_mfma_f32_16x16x32_bf16 v[84:87], v[204:207], v[178:181], 0
	v_mfma_f32_16x16x32_bf16 v[80:83], v[212:215], v[178:181], 0
	v_mfma_f32_16x16x32_bf16 v[68:71], v[204:207], v[196:199], 0
	v_mfma_f32_16x16x32_bf16 v[64:67], v[212:215], v[196:199], 0
	v_mfma_f32_16x16x32_bf16 v[116:119], v[208:211], v[158:161], v[116:119]
	v_mfma_f32_16x16x32_bf16 v[112:115], v[216:219], v[158:161], v[112:115]
	v_mfma_f32_16x16x32_bf16 v[100:103], v[208:211], v[174:177], v[100:103]
	v_mfma_f32_16x16x32_bf16 v[96:99], v[216:219], v[174:177], v[96:99]
	v_mfma_f32_16x16x32_bf16 v[84:87], v[208:211], v[192:195], v[84:87]
	v_mfma_f32_16x16x32_bf16 v[80:83], v[216:219], v[192:195], v[80:83]
	v_mfma_f32_16x16x32_bf16 v[68:71], v[208:211], v[200:203], v[68:71]
	v_mfma_f32_16x16x32_bf16 v[64:67], v[216:219], v[200:203], v[64:67]
	s_setprio 0
	s_mov_b32 m0, s87
	v_lshl_add_u64 v[220:221], s[10:11], 0, v[144:145]
	s_barrier
	ds_read_b128 v[154:157], v191 offset:16384
	ds_read_b128 v[158:161], v191 offset:17408
	ds_read_b128 v[170:173], v191 offset:18432
	ds_read_b128 v[174:177], v191 offset:19456
	ds_read_b128 v[178:181], v191 offset:20480
	ds_read_b128 v[192:195], v191 offset:21504
	ds_read_b128 v[196:199], v191 offset:22528
	ds_read_b128 v[200:203], v191 offset:23552
	global_load_lds_dwordx4 v[220:221], off
	v_lshl_add_u64 v[222:223], s[10:11], 0, v[146:147]
	s_mov_b32 m0, s77
	s_nop 0
	global_load_lds_dwordx4 v[222:223], off
	s_barrier
	s_waitcnt lgkmcnt(0)
	s_setprio 1
	s_waitcnt lgkmcnt(0)
	v_mfma_f32_16x16x32_bf16 v[60:63], v[128:131], v[154:157], 0
	v_mfma_f32_16x16x32_bf16 v[56:59], v[136:139], v[154:157], 0
	v_mfma_f32_16x16x32_bf16 v[44:47], v[128:131], v[170:173], 0
	v_mfma_f32_16x16x32_bf16 v[40:43], v[136:139], v[170:173], 0
	v_mfma_f32_16x16x32_bf16 v[28:31], v[128:131], v[178:181], 0
	v_mfma_f32_16x16x32_bf16 v[24:27], v[136:139], v[178:181], 0
	v_mfma_f32_16x16x32_bf16 v[12:15], v[128:131], v[196:199], 0
	v_mfma_f32_16x16x32_bf16 v[8:11], v[136:139], v[196:199], 0
	v_mfma_f32_16x16x32_bf16 v[60:63], v[132:135], v[158:161], v[60:63]
	v_mfma_f32_16x16x32_bf16 v[56:59], v[140:143], v[158:161], v[56:59]
	v_mfma_f32_16x16x32_bf16 v[44:47], v[132:135], v[174:177], v[44:47]
	v_mfma_f32_16x16x32_bf16 v[40:43], v[140:143], v[174:177], v[40:43]
	v_mfma_f32_16x16x32_bf16 v[28:31], v[132:135], v[192:195], v[28:31]
	v_mfma_f32_16x16x32_bf16 v[24:27], v[140:143], v[192:195], v[24:27]
	v_mfma_f32_16x16x32_bf16 v[12:15], v[132:135], v[200:203], v[12:15]
	v_mfma_f32_16x16x32_bf16 v[8:11], v[140:143], v[200:203], v[8:11]
	s_setprio 0
	s_barrier
; #define PG8_STAGE(bufoff, gbase, voff) do { _Pragma("unroll") for (int _i = 0; _i < 2; ++_i) \
;         __builtin_amdgcn_global_load_lds((const unsigned*)((const char*)(gbase) + (voff)[_i]), (LAS unsigned*)(lds + (bufoff) + ldsw + _i * 8192), 16, 0, 0); } while (0)
; #define PG8_LDA(dst, b, h) do { _Pragma("unroll") for (int m = 0; m < 4; ++m) _Pragma("unroll") for (int k = 0; k < 2; ++k) dst[m][k] = *(const LAS bf16x8*)(lds + PG8_SA(b, h) + aoff + m * 2048 + k * 1024); } while (0)
; #define PG8_LDB(dst, b, h) do { _Pragma("unroll") for (int n = 0; n < 2; ++n) _Pragma("unroll") for (int k = 0; k < 2; ++k) dst[n][k] = *(const LAS bf16x8*)(lds + PG8_SB(b, h) + boff + n * 2048 + k * 1024); } while (0)
; #define PG8_MMA(ai, bj, At, Bt) do { __builtin_amdgcn_s_setprio(1); _Pragma("unroll") for (int m = 0; m < 4; ++m) _Pragma("unroll") for (int n = 0; n < 2; ++n) _Pragma("unroll") for (int k = 0; k < 2; ++k) \
;         acc[ai][bj][m][n] = __builtin_amdgcn_mfma_f32_16x16x32_bf16(Bt[n][k], At[m][k], acc[ai][bj][m][n], 0, 0, 0); __builtin_amdgcn_s_setprio(0); } while (0)
; #define PG8_WAIT_V(n) asm volatile("s_waitcnt vmcnt(" #n ")" ::: "memory")
; #define PG8_WAIT_L(n) asm volatile("s_waitcnt lgkmcnt(" #n ")" ::: "memory")
; #define PG8_BAR __builtin_amdgcn_s_barrier()
; #define PG8_SCHED __builtin_amdgcn_sched_barrier(0)
; template <class Epi>
; DI void gemm_phase(LAS unsigned char* lds, const Gemm g, const StaticOrder& S, const Epi& E) {
;     ...
;             PG8_STAGE(PG8_SB(0, 1), b2 + hstep, voffB);
;             PG8_WAIT_V(6); PG8_BAR; PG8_MMA(1, 1, At, B1); PG8_BAR;
;             PG8_LDB(B0, 1, 0); PG8_SCHED; PG8_LDA(At, 1, 0); PG8_STAGE(PG8_SA(0, 1), a2 + hstep, voffA);
;             PG8_WAIT_L(8); PG8_BAR; PG8_WAIT_L(0); PG8_MMA(0, 0, At, B0); PG8_BAR; PG8_SCHED;
;             PG8_LDB(B1, 1, 1); PG8_STAGE(PG8_SB(1, 0), b3, voffB);
	s_add_u32 s12, s12, s48
	s_addc_u32 s13, s13, s49
	s_add_i32 s4, s4, s37
	v_lshl_add_u64 v[224:225], s[12:13], 0, v[166:167]
	s_mov_b32 m0, s4
	v_lshl_add_u64 v[226:227], s[12:13], 0, v[148:149]
	global_load_lds_dwordx4 v[224:225], off
	s_add_i32 m0, s4, 0x2000
	s_nop 0
	global_load_lds_dwordx4 v[226:227], off
	s_waitcnt vmcnt(6)
	s_barrier
	s_setprio 1
	v_mfma_f32_16x16x32_bf16 v[52:55], v[204:207], v[154:157], 0
	v_mfma_f32_16x16x32_bf16 v[48:51], v[212:215], v[154:157], 0
	v_mfma_f32_16x16x32_bf16 v[36:39], v[204:207], v[170:173], 0
	v_mfma_f32_16x16x32_bf16 v[32:35], v[212:215], v[170:173], 0
	v_mfma_f32_16x16x32_bf16 v[20:23], v[204:207], v[178:181], 0
	v_mfma_f32_16x16x32_bf16 v[16:19], v[212:215], v[178:181], 0
	v_mfma_f32_16x16x32_bf16 v[4:7], v[204:207], v[196:199], 0
	v_mfma_f32_16x16x32_bf16 v[0:3], v[212:215], v[196:199], 0
	v_mfma_f32_16x16x32_bf16 v[52:55], v[208:211], v[158:161], v[52:55]
	v_mfma_f32_16x16x32_bf16 v[48:51], v[216:219], v[158:161], v[48:51]
	v_mfma_f32_16x16x32_bf16 v[36:39], v[208:211], v[174:177], v[36:39]
	v_mfma_f32_16x16x32_bf16 v[32:35], v[216:219], v[174:177], v[32:35]
	v_mfma_f32_16x16x32_bf16 v[20:23], v[208:211], v[192:195], v[20:23]
	v_mfma_f32_16x16x32_bf16 v[16:19], v[216:219], v[192:195], v[16:19]
	v_mfma_f32_16x16x32_bf16 v[4:7], v[208:211], v[200:203], v[4:7]
	v_mfma_f32_16x16x32_bf16 v[0:3], v[216:219], v[200:203], v[0:3]
	s_setprio 0
	s_add_i32 s4, s64, 0x100
	v_add_u32_e32 v140, s4, v190
	s_barrier
	ds_read_b128 v[128:131], v140
	ds_read_b128 v[132:135], v140 offset:1024
	ds_read_b128 v[136:139], v140 offset:2048
	ds_read_b128 v[140:143], v140 offset:3072
	s_add_u32 s10, s10, s48
	s_addc_u32 s11, s11, s49
	s_mov_b32 m0, s80
	v_lshl_add_u64 v[204:205], s[10:11], 0, v[144:145]
	ds_read_b128 v[154:157], v191 offset:32768
	ds_read_b128 v[158:161], v191 offset:33792
	ds_read_b128 v[170:173], v191 offset:34816
	ds_read_b128 v[174:177], v191 offset:35840
	ds_read_b128 v[178:181], v191 offset:36864
	ds_read_b128 v[192:195], v191 offset:37888
	ds_read_b128 v[196:199], v191 offset:38912
	ds_read_b128 v[200:203], v191 offset:39936
	global_load_lds_dwordx4 v[204:205], off
	v_lshl_add_u64 v[204:205], s[10:11], 0, v[146:147]
	s_mov_b32 m0, s81
	s_nop 0
	global_load_lds_dwordx4 v[204:205], off
	s_waitcnt lgkmcnt(8)
	s_barrier
	s_waitcnt lgkmcnt(0)
	s_setprio 1
	s_waitcnt lgkmcnt(0)
	v_mfma_f32_16x16x32_bf16 v[124:127], v[128:131], v[154:157], v[124:127]
	v_mfma_f32_16x16x32_bf16 v[120:123], v[136:139], v[154:157], v[120:123]
	v_mfma_f32_16x16x32_bf16 v[108:111], v[128:131], v[170:173], v[108:111]
	v_mfma_f32_16x16x32_bf16 v[104:107], v[136:139], v[170:173], v[104:107]
	v_mfma_f32_16x16x32_bf16 v[92:95], v[128:131], v[178:181], v[92:95]
	v_mfma_f32_16x16x32_bf16 v[88:91], v[136:139], v[178:181], v[88:91]
	v_mfma_f32_16x16x32_bf16 v[76:79], v[128:131], v[196:199], v[76:79]
	v_mfma_f32_16x16x32_bf16 v[72:75], v[136:139], v[196:199], v[72:75]
	v_mfma_f32_16x16x32_bf16 v[124:127], v[132:135], v[158:161], v[124:127]
	v_mfma_f32_16x16x32_bf16 v[120:123], v[140:143], v[158:161], v[120:123]
	v_mfma_f32_16x16x32_bf16 v[108:111], v[132:135], v[174:177], v[108:111]
	v_mfma_f32_16x16x32_bf16 v[104:107], v[140:143], v[174:177], v[104:107]
	v_mfma_f32_16x16x32_bf16 v[92:95], v[132:135], v[192:195], v[92:95]
	v_mfma_f32_16x16x32_bf16 v[88:91], v[140:143], v[192:195], v[88:91]
	v_mfma_f32_16x16x32_bf16 v[76:79], v[132:135], v[200:203], v[76:79]
	v_mfma_f32_16x16x32_bf16 v[72:75], v[140:143], v[200:203], v[72:75]
	s_setprio 0
	s_barrier
	s_add_i32 s10, s33, 0x100
	s_add_i32 s4, s4, s37
	v_add_u32_e32 v216, s10, v190
	v_lshl_add_u64 v[162:163], v[162:163], 0, s[66:67]
	s_mov_b32 m0, s4
	ds_read_b128 v[204:207], v216
	ds_read_b128 v[208:211], v216 offset:1024
	ds_read_b128 v[212:215], v216 offset:2048
	ds_read_b128 v[216:219], v216 offset:3072
	global_load_lds_dwordx4 v[162:163], off
	v_lshl_add_u64 v[162:163], v[182:183], 0, s[66:67]
	s_add_i32 m0, s4, 0x2000
	s_nop 0
	global_load_lds_dwordx4 v[162:163], off
	s_barrier
; #define PG8_STAGE(bufoff, gbase, voff) do { _Pragma("unroll") for (int _i = 0; _i < 2; ++_i) \
;         __builtin_amdgcn_global_load_lds((const unsigned*)((const char*)(gbase) + (voff)[_i]), (LAS unsigned*)(lds + (bufoff) + ldsw + _i * 8192), 16, 0, 0); } while (0)
; #define PG8_LDA(dst, b, h) do { _Pragma("unroll") for (int m = 0; m < 4; ++m) _Pragma("unroll") for (int k = 0; k < 2; ++k) dst[m][k] = *(const LAS bf16x8*)(lds + PG8_SA(b, h) + aoff + m * 2048 + k * 1024); } while (0)
; #define PG8_MMA(ai, bj, At, Bt) do { __builtin_amdgcn_s_setprio(1); _Pragma("unroll") for (int m = 0; m < 4; ++m) _Pragma("unroll") for (int n = 0; n < 2; ++n) _Pragma("unroll") for (int k = 0; k < 2; ++k) \
;         acc[ai][bj][m][n] = __builtin_amdgcn_mfma_f32_16x16x32_bf16(Bt[n][k], At[m][k], acc[ai][bj][m][n], 0, 0, 0); __builtin_amdgcn_s_setprio(0); } while (0)
; #define PG8_WAIT_V(n) asm volatile("s_waitcnt vmcnt(" #n ")" ::: "memory")
; #define PG8_WAIT_L(n) asm volatile("s_waitcnt lgkmcnt(" #n ")" ::: "memory")
; #define PG8_BAR __builtin_amdgcn_s_barrier()
; #define PG8_SCHED __builtin_amdgcn_sched_barrier(0)
; template <class Epi>
; DI void gemm_phase(LAS unsigned char* lds, const Gemm g, const StaticOrder& S, const Epi& E) {
;     ...
;             PG8_BAR; PG8_WAIT_L(0); PG8_MMA(0, 1, At, B1); PG8_BAR;
;             PG8_LDA(At, 1, 1); PG8_STAGE(PG8_SA(1, 0), a3, voffA);
;             PG8_BAR; PG8_WAIT_L(0); PG8_MMA(1, 0, At, B0); PG8_BAR; PG8_SCHED;
;             PG8_STAGE(PG8_SB(1, 1), b3 + hstep, voffB);
;             PG8_WAIT_V(6); PG8_BAR; PG8_MMA(1, 1, At, B1); PG8_BAR;
	s_waitcnt lgkmcnt(0)
	s_setprio 1
	s_waitcnt lgkmcnt(0)
	v_mfma_f32_16x16x32_bf16 v[116:119], v[204:207], v[154:157], v[116:119]
	v_mfma_f32_16x16x32_bf16 v[112:115], v[212:215], v[154:157], v[112:115]
	v_mfma_f32_16x16x32_bf16 v[100:103], v[204:207], v[170:173], v[100:103]
	v_mfma_f32_16x16x32_bf16 v[96:99], v[212:215], v[170:173], v[96:99]
	v_mfma_f32_16x16x32_bf16 v[84:87], v[204:207], v[178:181], v[84:87]
	v_mfma_f32_16x16x32_bf16 v[80:83], v[212:215], v[178:181], v[80:83]
	v_mfma_f32_16x16x32_bf16 v[68:71], v[204:207], v[196:199], v[68:71]
	v_mfma_f32_16x16x32_bf16 v[64:67], v[212:215], v[196:199], v[64:67]
	v_mfma_f32_16x16x32_bf16 v[116:119], v[208:211], v[158:161], v[116:119]
	v_mfma_f32_16x16x32_bf16 v[112:115], v[216:219], v[158:161], v[112:115]
	v_mfma_f32_16x16x32_bf16 v[100:103], v[208:211], v[174:177], v[100:103]
	v_mfma_f32_16x16x32_bf16 v[96:99], v[216:219], v[174:177], v[96:99]
	v_mfma_f32_16x16x32_bf16 v[84:87], v[208:211], v[192:195], v[84:87]
	v_mfma_f32_16x16x32_bf16 v[80:83], v[216:219], v[192:195], v[80:83]
	v_mfma_f32_16x16x32_bf16 v[68:71], v[208:211], v[200:203], v[68:71]
	v_mfma_f32_16x16x32_bf16 v[64:67], v[216:219], v[200:203], v[64:67]
	s_setprio 0
	s_mov_b32 m0, s82
	v_lshl_add_u64 v[162:163], v[220:221], 0, s[66:67]
	s_barrier
	ds_read_b128 v[154:157], v191 offset:49152
	ds_read_b128 v[158:161], v191 offset:50176
	ds_read_b128 v[170:173], v191 offset:51200
	ds_read_b128 v[174:177], v191 offset:52224
	ds_read_b128 v[178:181], v191 offset:53248
	ds_read_b128 v[192:195], v191 offset:54272
	ds_read_b128 v[196:199], v191 offset:55296
	ds_read_b128 v[200:203], v191 offset:56320
	global_load_lds_dwordx4 v[162:163], off
	v_lshl_add_u64 v[162:163], v[222:223], 0, s[66:67]
	s_mov_b32 m0, s83
	s_nop 0
	global_load_lds_dwordx4 v[162:163], off
	s_barrier
	s_waitcnt lgkmcnt(0)
	s_setprio 1
	s_waitcnt lgkmcnt(0)
	v_mfma_f32_16x16x32_bf16 v[60:63], v[128:131], v[154:157], v[60:63]
	v_mfma_f32_16x16x32_bf16 v[56:59], v[136:139], v[154:157], v[56:59]
	v_mfma_f32_16x16x32_bf16 v[44:47], v[128:131], v[170:173], v[44:47]
	v_mfma_f32_16x16x32_bf16 v[40:43], v[136:139], v[170:173], v[40:43]
	v_mfma_f32_16x16x32_bf16 v[28:31], v[128:131], v[178:181], v[28:31]
	v_mfma_f32_16x16x32_bf16 v[24:27], v[136:139], v[178:181], v[24:27]
	v_mfma_f32_16x16x32_bf16 v[12:15], v[128:131], v[196:199], v[12:15]
	v_mfma_f32_16x16x32_bf16 v[8:11], v[136:139], v[196:199], v[8:11]
	v_mfma_f32_16x16x32_bf16 v[60:63], v[132:135], v[158:161], v[60:63]
	v_mfma_f32_16x16x32_bf16 v[56:59], v[140:143], v[158:161], v[56:59]
	v_mfma_f32_16x16x32_bf16 v[44:47], v[132:135], v[174:177], v[44:47]
	v_mfma_f32_16x16x32_bf16 v[40:43], v[140:143], v[174:177], v[40:43]
	v_mfma_f32_16x16x32_bf16 v[28:31], v[132:135], v[192:195], v[28:31]
	v_mfma_f32_16x16x32_bf16 v[24:27], v[140:143], v[192:195], v[24:27]
	v_mfma_f32_16x16x32_bf16 v[12:15], v[132:135], v[200:203], v[12:15]
	v_mfma_f32_16x16x32_bf16 v[8:11], v[140:143], v[200:203], v[8:11]
	s_setprio 0
	s_barrier
	s_add_i32 s4, s10, s37
	v_lshl_add_u64 v[128:129], v[224:225], 0, s[66:67]
	s_mov_b32 m0, s4
	s_nop 0
	global_load_lds_dwordx4 v[128:129], off
	v_lshl_add_u64 v[128:129], v[226:227], 0, s[66:67]
	s_add_i32 m0, s4, 0x2000
	s_nop 0
	global_load_lds_dwordx4 v[128:129], off
	s_waitcnt vmcnt(6)
	s_barrier
	s_setprio 1
	v_mfma_f32_16x16x32_bf16 v[52:55], v[204:207], v[154:157], v[52:55]
	v_mfma_f32_16x16x32_bf16 v[48:51], v[212:215], v[154:157], v[48:51]
	v_mfma_f32_16x16x32_bf16 v[36:39], v[204:207], v[170:173], v[36:39]
	v_mfma_f32_16x16x32_bf16 v[32:35], v[212:215], v[170:173], v[32:35]
	v_mfma_f32_16x16x32_bf16 v[20:23], v[204:207], v[178:181], v[20:23]
	v_mfma_f32_16x16x32_bf16 v[16:19], v[212:215], v[178:181], v[16:19]
	v_mfma_f32_16x16x32_bf16 v[4:7], v[204:207], v[196:199], v[4:7]
	v_mfma_f32_16x16x32_bf16 v[0:3], v[212:215], v[196:199], v[0:3]
	v_mfma_f32_16x16x32_bf16 v[52:55], v[208:211], v[158:161], v[52:55]
	v_mfma_f32_16x16x32_bf16 v[48:51], v[216:219], v[158:161], v[48:51]
	v_mfma_f32_16x16x32_bf16 v[36:39], v[208:211], v[174:177], v[36:39]
	v_mfma_f32_16x16x32_bf16 v[32:35], v[216:219], v[174:177], v[32:35]
	v_mfma_f32_16x16x32_bf16 v[20:23], v[208:211], v[192:195], v[20:23]
	v_mfma_f32_16x16x32_bf16 v[16:19], v[216:219], v[192:195], v[16:19]
	v_mfma_f32_16x16x32_bf16 v[4:7], v[208:211], v[200:203], v[4:7]
	v_mfma_f32_16x16x32_bf16 v[0:3], v[216:219], v[200:203], v[0:3]
	s_setprio 0
	s_add_u32 s2, s2, 0x100
	s_addc_u32 s3, s3, 0
	s_add_u32 s14, s14, 0x100
	s_addc_u32 s15, s15, 0
	s_cmp_ge_i32 s5, s95
	s_mov_b32 s4, s5
	s_barrier
	s_cbranch_scc0 .LBB0_399
	s_branch .Lpeel_exit_0

; DI u32x4 pk8(f32x4 a, f32x4 b) { u32x4 r; r.x = pk2(a[0], a[1]); r.y = pk2(a[2], a[3]); r.z = pk2(b[0], b[1]); r.w = pk2(b[2], b[3]); return r; }
;     DI void operator()(const Acc& acc, const pg8::Unit& u, int wr, int wc, int fr, int fq) const {
;     ...
;                 for (int m = 0; m < 4; ++m) { const int row = row0 + ai * 128 + m * 16;
;                     { const f32x4 v0 = acc[ai][0][m][0], v1 = acc[ai][0][m][1];
;                       *(u32x4*)(cq + (size_t)row * 384 + 256 + cw) = pk8(v0, v1);
;                       float ss = v0[0] * v0[0] + v0[1] * v0[1] + v0[2] * v0[2] + v0[3] * v0[3] + v1[0] * v1[0] + v1[1] * v1[1] + v1[2] * v1[2] + v1[3] * v1[3];
;                       ss += __shfl_xor(ss, 16); ss += __shfl_xor(ss, 32);
;                       if (fq == 0) ssq_kv[row * 4 + wc] = ss; }
.Lpeel_exit_0:
.LBB0_400:
	v_mov_b32_e32 v128, v189
	v_mov_b32_e32 v192, v188
	s_lshl_b32 s0, s0, 8
	s_add_i32 s0, s0, s68
	v_add_u32_e32 v156, s0, v128
	v_lshlrev_b32_e32 v128, 3, v192
	v_add_u32_e32 v154, s69, v128
	s_mov_b64 s[12:13], -1
	s_mov_b64 s[2:3], 0
	s_cmp_lt_i32 s16, 1
	s_mov_b64 s[10:11], 0
	s_cbranch_scc1 .LBB0_443
	s_cmp_eq_u32 s16, 1
	s_mov_b64 s[10:11], -1
	s_cbranch_scc0 .LBB0_435
	v_and_b32_e32 v130, 64, v184
	v_xor_b32_e32 v129, 16, v184
	v_add_u32_e32 v130, 64, v130
	v_cmp_lt_i32_e32 vcc, v129, v130
	v_ashrrev_i32_e32 v155, 31, v154
	v_cvt_pk_bf16_f32 v134, v124, v125
	v_cndmask_b32_e32 v129, v184, v129, vcc
	v_lshlrev_b32_e32 v133, 2, v129
	v_xor_b32_e32 v129, 32, v184
	v_cmp_lt_i32_e32 vcc, v129, v130
	v_mov_b64_e32 v[130:131], s[54:55]
	v_mad_i64_i32 v[130:131], s[4:5], v156, s60, v[130:131]
	v_cndmask_b32_e32 v129, v184, v129, vcc
	v_lshlrev_b32_e32 v132, 2, v129
	v_mul_f32_e32 v129, v125, v125
	v_fmac_f32_e32 v129, v124, v124
	v_fmac_f32_e32 v129, v126, v126
	v_fmac_f32_e32 v129, v127, v127
	v_fmac_f32_e32 v129, v120, v120
	v_fmac_f32_e32 v129, v121, v121
	v_fmac_f32_e32 v129, v122, v122
	v_cvt_pk_bf16_f32 v135, v126, v127
	v_cvt_pk_bf16_f32 v136, v120, v121
	v_cvt_pk_bf16_f32 v137, v122, v123
	v_lshl_add_u64 v[130:131], v[154:155], 1, v[130:131]
	v_fmac_f32_e32 v129, v123, v123
	global_store_dwordx4 v[130:131], v[134:137], off offset:512
	ds_bpermute_b32 v130, v133, v129
	v_cmp_eq_u32_e64 s[40:41], 0, v192
	s_waitcnt lgkmcnt(0)
	v_add_f32_e32 v129, v129, v130
	ds_bpermute_b32 v130, v132, v129
	s_and_saveexec_b64 s[10:11], s[40:41]
	s_cbranch_execz .LBB0_404
	v_lshl_or_b32 v134, v156, 2, s84
	v_readlane_b32 s4, v236, 16
	v_ashrrev_i32_e32 v135, 31, v134
	v_readlane_b32 s5, v236, 17
	s_waitcnt lgkmcnt(0)
	v_add_f32_e32 v129, v129, v130
	v_lshl_add_u64 v[134:135], v[134:135], 2, s[4:5]
	global_store_dword v[134:135], v129, off

; #define PG8_STAGE(bufoff, gbase, voff) do { _Pragma("unroll") for (int _i = 0; _i < 2; ++_i) \
;         __builtin_amdgcn_global_load_lds((const unsigned*)((const char*)(gbase) + (voff)[_i]), (LAS unsigned*)(lds + (bufoff) + ldsw + _i * 8192), 16, 0, 0); } while (0)
; #define PG8_LDA(dst, b, h) do { _Pragma("unroll") for (int m = 0; m < 4; ++m) _Pragma("unroll") for (int k = 0; k < 2; ++k) dst[m][k] = *(const LAS bf16x8*)(lds + PG8_SA(b, h) + aoff + m * 2048 + k * 1024); } while (0)
; #define PG8_LDB(dst, b, h) do { _Pragma("unroll") for (int n = 0; n < 2; ++n) _Pragma("unroll") for (int k = 0; k < 2; ++k) dst[n][k] = *(const LAS bf16x8*)(lds + PG8_SB(b, h) + boff + n * 2048 + k * 1024); } while (0)
; #define PG8_MMA(ai, bj, At, Bt) do { __builtin_amdgcn_s_setprio(1); _Pragma("unroll") for (int m = 0; m < 4; ++m) _Pragma("unroll") for (int n = 0; n < 2; ++n) _Pragma("unroll") for (int k = 0; k < 2; ++k) \
;         acc[ai][bj][m][n] = __builtin_amdgcn_mfma_f32_16x16x32_bf16(Bt[n][k], At[m][k], acc[ai][bj][m][n], 0, 0, 0); __builtin_amdgcn_s_setprio(0); } while (0)
; #define PG8_WAIT_L(n) asm volatile("s_waitcnt lgkmcnt(" #n ")" ::: "memory")
; #define PG8_BAR __builtin_amdgcn_s_barrier()
; #define PG8_SCHED __builtin_amdgcn_sched_barrier(0)
; template <class Epi>
; DI void gemm_phase(LAS unsigned char* lds, const Gemm g, const StaticOrder& S, const Epi& E) {
;     ...
;             const bool last = (t == nt - 2);
;             const char* a1 = cA + (size_t)(t + 1) * kstep;
;             const char* a2 = last ? nA : cA + (size_t)(t + 2) * kstep; const char* b2 = last ? nB : cB + (size_t)(t + 2) * kstep;
;             const char* a3 = a2 + kstep; const char* b3 = b2 + kstep;
;             PG8_LDB(B0, 0, 0); PG8_SCHED; PG8_LDA(At, 0, 0); PG8_STAGE(PG8_SA(1, 1), a1 + hstep, voffA);
;             PG8_WAIT_L(8); PG8_BAR; PG8_WAIT_L(0); PG8_MMA(0, 0, At, B0); PG8_BAR; PG8_SCHED;
;             PG8_LDB(B1, 0, 1); PG8_STAGE(PG8_SB(0, 0), b2, voffB);
;             PG8_BAR; PG8_WAIT_L(0); PG8_MMA(0, 1, At, B1); PG8_BAR;
;             PG8_LDA(At, 0, 1); PG8_STAGE(PG8_SA(0, 0), a2, voffA);
;             PG8_BAR; PG8_WAIT_L(0); PG8_MMA(1, 0, At, B0); PG8_BAR; PG8_SCHED;
.LBB0_643:
	s_andn2_b64 vcc, exec, s[14:15]
	s_cbranch_vccnz .LBB0_646
	s_add_u32 s40, s46, 0x80
	s_addc_u32 s41, s47, 0
	s_add_u32 s0, s44, 0x100
	s_addc_u32 s46, s45, 0
	s_mov_b32 s4, 0
	s_mov_b32 s72, 0x10000
	s_mov_b32 s73, 0x14000
	s_mov_b32 s74, 0x18000
	s_mov_b32 s75, 0x1c000
	s_mov_b64 s[76:77], 0x80
	s_add_i32 s5, s4, 2
	s_add_u32 s42, s40, 0x80
	s_addc_u32 s43, s41, 0
	s_add_i32 s47, s72, 0x100
	v_add_u32_e32 v156, s47, v150
	ds_read_b128 v[140:143], v156
	ds_read_b128 v[144:147], v156 offset:1024
	ds_read_b128 v[152:155], v156 offset:2048
	ds_read_b128 v[156:159], v156 offset:3072
	s_cmp_eq_u32 s63, s4
	s_cselect_b32 s43, s19, s43
	s_cselect_b32 s42, s18, s42
	s_cselect_b32 s45, s37, s46
	s_cselect_b32 s44, s36, s0
	v_lshl_add_u64 v[182:183], s[40:41], 0, v[136:137]
	s_add_i32 m0, s55, 0xc000
	ds_read_b128 v[160:163], v151
	ds_read_b128 v[170:173], v151 offset:1024
	ds_read_b128 v[174:177], v151 offset:2048
	ds_read_b128 v[178:181], v151 offset:3072
	ds_read_b128 v[188:191], v151 offset:4096
	ds_read_b128 v[192:195], v151 offset:5120
	ds_read_b128 v[196:199], v151 offset:6144
	ds_read_b128 v[200:203], v151 offset:7168
	global_load_lds_dwordx4 v[182:183], off
	v_lshl_add_u64 v[182:183], s[40:41], 0, v[138:139]
	s_add_i32 m0, s55, 0xe000
	s_nop 0
	global_load_lds_dwordx4 v[182:183], off
	s_waitcnt lgkmcnt(8)
	s_barrier
	s_waitcnt lgkmcnt(0)
	s_setprio 1
	s_waitcnt lgkmcnt(0)
	v_mfma_f32_16x16x32_bf16 v[120:123], v[140:143], v[160:163], 0
	v_mfma_f32_16x16x32_bf16 v[124:127], v[152:155], v[160:163], 0
	v_mfma_f32_16x16x32_bf16 v[108:111], v[140:143], v[174:177], 0
	v_mfma_f32_16x16x32_bf16 v[104:107], v[152:155], v[174:177], 0
	v_mfma_f32_16x16x32_bf16 v[92:95], v[140:143], v[188:191], 0
	v_mfma_f32_16x16x32_bf16 v[88:91], v[152:155], v[188:191], 0
	v_mfma_f32_16x16x32_bf16 v[76:79], v[140:143], v[196:199], 0
	v_mfma_f32_16x16x32_bf16 v[72:75], v[152:155], v[196:199], 0
	v_mfma_f32_16x16x32_bf16 v[120:123], v[144:147], v[170:173], v[120:123]
	v_mfma_f32_16x16x32_bf16 v[124:127], v[156:159], v[170:173], v[124:127]
	v_mfma_f32_16x16x32_bf16 v[108:111], v[144:147], v[178:181], v[108:111]
	v_mfma_f32_16x16x32_bf16 v[104:107], v[156:159], v[178:181], v[104:107]
	v_mfma_f32_16x16x32_bf16 v[92:95], v[144:147], v[192:195], v[92:95]
	v_mfma_f32_16x16x32_bf16 v[88:91], v[156:159], v[192:195], v[88:91]
	v_mfma_f32_16x16x32_bf16 v[76:79], v[144:147], v[200:203], v[76:79]
	v_mfma_f32_16x16x32_bf16 v[72:75], v[156:159], v[200:203], v[72:75]
	s_setprio 0
	s_barrier
	s_add_i32 s4, s73, 0x100
	s_add_i32 s47, s47, s54
	v_add_u32_e32 v166, s4, v150
	v_lshl_add_u64 v[182:183], s[44:45], 0, v[130:131]
	s_mov_b32 m0, s47
	ds_read_b128 v[204:207], v166
	ds_read_b128 v[208:211], v166 offset:1024
	ds_read_b128 v[212:215], v166 offset:2048
	ds_read_b128 v[216:219], v166 offset:3072
	global_load_lds_dwordx4 v[182:183], off
	v_lshl_add_u64 v[220:221], s[44:45], 0, v[134:135]
	s_add_i32 m0, s47, 0x2000
	s_nop 0
	global_load_lds_dwordx4 v[220:221], off
	s_barrier
	s_waitcnt lgkmcnt(0)
	s_setprio 1
	s_waitcnt lgkmcnt(0)
	v_mfma_f32_16x16x32_bf16 v[116:119], v[204:207], v[160:163], 0
	v_mfma_f32_16x16x32_bf16 v[112:115], v[212:215], v[160:163], 0
	v_mfma_f32_16x16x32_bf16 v[100:103], v[204:207], v[174:177], 0
	v_mfma_f32_16x16x32_bf16 v[96:99], v[212:215], v[174:177], 0
	v_mfma_f32_16x16x32_bf16 v[84:87], v[204:207], v[188:191], 0
	v_mfma_f32_16x16x32_bf16 v[80:83], v[212:215], v[188:191], 0
	v_mfma_f32_16x16x32_bf16 v[68:71], v[204:207], v[196:199], 0
	v_mfma_f32_16x16x32_bf16 v[64:67], v[212:215], v[196:199], 0
	v_mfma_f32_16x16x32_bf16 v[116:119], v[208:211], v[170:173], v[116:119]
	v_mfma_f32_16x16x32_bf16 v[112:115], v[216:219], v[170:173], v[112:115]
	v_mfma_f32_16x16x32_bf16 v[100:103], v[208:211], v[178:181], v[100:103]
	v_mfma_f32_16x16x32_bf16 v[96:99], v[216:219], v[178:181], v[96:99]
	v_mfma_f32_16x16x32_bf16 v[84:87], v[208:211], v[192:195], v[84:87]
	v_mfma_f32_16x16x32_bf16 v[80:83], v[216:219], v[192:195], v[80:83]
	v_mfma_f32_16x16x32_bf16 v[68:71], v[208:211], v[200:203], v[68:71]
	v_mfma_f32_16x16x32_bf16 v[64:67], v[216:219], v[200:203], v[64:67]
	s_setprio 0
	s_mov_b32 m0, s55
	v_lshl_add_u64 v[222:223], s[42:43], 0, v[128:129]
	s_barrier
	ds_read_b128 v[160:163], v151 offset:16384
	ds_read_b128 v[170:173], v151 offset:17408
	ds_read_b128 v[174:177], v151 offset:18432
	ds_read_b128 v[178:181], v151 offset:19456
	ds_read_b128 v[188:191], v151 offset:20480
	ds_read_b128 v[192:195], v151 offset:21504
	ds_read_b128 v[196:199], v151 offset:22528
	ds_read_b128 v[200:203], v151 offset:23552
	global_load_lds_dwordx4 v[222:223], off
	v_lshl_add_u64 v[224:225], s[42:43], 0, v[132:133]
	s_mov_b32 m0, s56
	s_nop 0
	global_load_lds_dwordx4 v[224:225], off
	s_barrier
	s_waitcnt lgkmcnt(0)
	s_setprio 1
	s_waitcnt lgkmcnt(0)
	v_mfma_f32_16x16x32_bf16 v[60:63], v[140:143], v[160:163], 0
	v_mfma_f32_16x16x32_bf16 v[56:59], v[152:155], v[160:163], 0
	v_mfma_f32_16x16x32_bf16 v[44:47], v[140:143], v[174:177], 0
	v_mfma_f32_16x16x32_bf16 v[40:43], v[152:155], v[174:177], 0
	v_mfma_f32_16x16x32_bf16 v[28:31], v[140:143], v[188:191], 0
	v_mfma_f32_16x16x32_bf16 v[24:27], v[152:155], v[188:191], 0
	v_mfma_f32_16x16x32_bf16 v[12:15], v[140:143], v[196:199], 0
	v_mfma_f32_16x16x32_bf16 v[8:11], v[152:155], v[196:199], 0
	v_mfma_f32_16x16x32_bf16 v[60:63], v[144:147], v[170:173], v[60:63]
	v_mfma_f32_16x16x32_bf16 v[56:59], v[156:159], v[170:173], v[56:59]
	v_mfma_f32_16x16x32_bf16 v[44:47], v[144:147], v[178:181], v[44:47]
	v_mfma_f32_16x16x32_bf16 v[40:43], v[156:159], v[178:181], v[40:43]
	v_mfma_f32_16x16x32_bf16 v[28:31], v[144:147], v[192:195], v[28:31]
	v_mfma_f32_16x16x32_bf16 v[24:27], v[156:159], v[192:195], v[24:27]
	v_mfma_f32_16x16x32_bf16 v[12:15], v[144:147], v[200:203], v[12:15]
	v_mfma_f32_16x16x32_bf16 v[8:11], v[156:159], v[200:203], v[8:11]
	s_setprio 0
	s_barrier
; #define PG8_STAGE(bufoff, gbase, voff) do { _Pragma("unroll") for (int _i = 0; _i < 2; ++_i) \
;         __builtin_amdgcn_global_load_lds((const unsigned*)((const char*)(gbase) + (voff)[_i]), (LAS unsigned*)(lds + (bufoff) + ldsw + _i * 8192), 16, 0, 0); } while (0)
; #define PG8_LDA(dst, b, h) do { _Pragma("unroll") for (int m = 0; m < 4; ++m) _Pragma("unroll") for (int k = 0; k < 2; ++k) dst[m][k] = *(const LAS bf16x8*)(lds + PG8_SA(b, h) + aoff + m * 2048 + k * 1024); } while (0)
; #define PG8_LDB(dst, b, h) do { _Pragma("unroll") for (int n = 0; n < 2; ++n) _Pragma("unroll") for (int k = 0; k < 2; ++k) dst[n][k] = *(const LAS bf16x8*)(lds + PG8_SB(b, h) + boff + n * 2048 + k * 1024); } while (0)
; #define PG8_MMA(ai, bj, At, Bt) do { __builtin_amdgcn_s_setprio(1); _Pragma("unroll") for (int m = 0; m < 4; ++m) _Pragma("unroll") for (int n = 0; n < 2; ++n) _Pragma("unroll") for (int k = 0; k < 2; ++k) \
;         acc[ai][bj][m][n] = __builtin_amdgcn_mfma_f32_16x16x32_bf16(Bt[n][k], At[m][k], acc[ai][bj][m][n], 0, 0, 0); __builtin_amdgcn_s_setprio(0); } while (0)
; #define PG8_WAIT_V(n) asm volatile("s_waitcnt vmcnt(" #n ")" ::: "memory")
; #define PG8_WAIT_L(n) asm volatile("s_waitcnt lgkmcnt(" #n ")" ::: "memory")
; #define PG8_BAR __builtin_amdgcn_s_barrier()
; #define PG8_SCHED __builtin_amdgcn_sched_barrier(0)
; template <class Epi>
; DI void gemm_phase(LAS unsigned char* lds, const Gemm g, const StaticOrder& S, const Epi& E) {
;     ...
;             PG8_STAGE(PG8_SB(0, 1), b2 + hstep, voffB);
;             PG8_WAIT_V(6); PG8_BAR; PG8_MMA(1, 1, At, B1); PG8_BAR;
;             PG8_LDB(B0, 1, 0); PG8_SCHED; PG8_LDA(At, 1, 0); PG8_STAGE(PG8_SA(0, 1), a2 + hstep, voffA);
;             PG8_WAIT_L(8); PG8_BAR; PG8_WAIT_L(0); PG8_MMA(0, 0, At, B0); PG8_BAR; PG8_SCHED;
;             PG8_LDB(B1, 1, 1); PG8_STAGE(PG8_SB(1, 0), b3, voffB);
	s_add_u32 s44, s44, s10
	s_addc_u32 s45, s45, s11
	s_add_i32 s4, s4, s54
	v_lshl_add_u64 v[226:227], s[44:45], 0, v[130:131]
	s_mov_b32 m0, s4
	v_lshl_add_u64 v[228:229], s[44:45], 0, v[134:135]
	global_load_lds_dwordx4 v[226:227], off
	s_add_i32 m0, s4, 0x2000
	s_nop 0
	global_load_lds_dwordx4 v[228:229], off
	s_waitcnt vmcnt(6)
	s_barrier
	s_setprio 1
	v_mfma_f32_16x16x32_bf16 v[52:55], v[204:207], v[160:163], 0
	v_mfma_f32_16x16x32_bf16 v[48:51], v[212:215], v[160:163], 0
	v_mfma_f32_16x16x32_bf16 v[36:39], v[204:207], v[174:177], 0
	v_mfma_f32_16x16x32_bf16 v[32:35], v[212:215], v[174:177], 0
	v_mfma_f32_16x16x32_bf16 v[20:23], v[204:207], v[188:191], 0
	v_mfma_f32_16x16x32_bf16 v[16:19], v[212:215], v[188:191], 0
	v_mfma_f32_16x16x32_bf16 v[4:7], v[204:207], v[196:199], 0
	v_mfma_f32_16x16x32_bf16 v[0:3], v[212:215], v[196:199], 0
	v_mfma_f32_16x16x32_bf16 v[52:55], v[208:211], v[170:173], v[52:55]
	v_mfma_f32_16x16x32_bf16 v[48:51], v[216:219], v[170:173], v[48:51]
	v_mfma_f32_16x16x32_bf16 v[36:39], v[208:211], v[178:181], v[36:39]
	v_mfma_f32_16x16x32_bf16 v[32:35], v[216:219], v[178:181], v[32:35]
	v_mfma_f32_16x16x32_bf16 v[20:23], v[208:211], v[192:195], v[20:23]
	v_mfma_f32_16x16x32_bf16 v[16:19], v[216:219], v[192:195], v[16:19]
	v_mfma_f32_16x16x32_bf16 v[4:7], v[208:211], v[200:203], v[4:7]
	v_mfma_f32_16x16x32_bf16 v[0:3], v[216:219], v[200:203], v[0:3]
	s_setprio 0
	s_add_i32 s4, s74, 0x100
	v_add_u32_e32 v156, s4, v150
	s_barrier
	ds_read_b128 v[140:143], v156
	ds_read_b128 v[144:147], v156 offset:1024
	ds_read_b128 v[152:155], v156 offset:2048
	ds_read_b128 v[156:159], v156 offset:3072
	s_add_u32 s42, s42, s10
	s_addc_u32 s43, s43, s11
	s_mov_b32 m0, s57
	v_lshl_add_u64 v[204:205], s[42:43], 0, v[128:129]
	ds_read_b128 v[160:163], v151 offset:32768
	ds_read_b128 v[170:173], v151 offset:33792
	ds_read_b128 v[174:177], v151 offset:34816
	ds_read_b128 v[178:181], v151 offset:35840
	ds_read_b128 v[188:191], v151 offset:36864
	ds_read_b128 v[192:195], v151 offset:37888
	ds_read_b128 v[196:199], v151 offset:38912
	ds_read_b128 v[200:203], v151 offset:39936
	global_load_lds_dwordx4 v[204:205], off
	v_lshl_add_u64 v[204:205], s[42:43], 0, v[132:133]
	s_mov_b32 m0, s58
	s_nop 0
	global_load_lds_dwordx4 v[204:205], off
	s_waitcnt lgkmcnt(8)
	s_barrier
	s_waitcnt lgkmcnt(0)
	s_setprio 1
	s_waitcnt lgkmcnt(0)
	v_mfma_f32_16x16x32_bf16 v[120:123], v[140:143], v[160:163], v[120:123]
	v_mfma_f32_16x16x32_bf16 v[124:127], v[152:155], v[160:163], v[124:127]
	v_mfma_f32_16x16x32_bf16 v[108:111], v[140:143], v[174:177], v[108:111]
	v_mfma_f32_16x16x32_bf16 v[104:107], v[152:155], v[174:177], v[104:107]
	v_mfma_f32_16x16x32_bf16 v[92:95], v[140:143], v[188:191], v[92:95]
	v_mfma_f32_16x16x32_bf16 v[88:91], v[152:155], v[188:191], v[88:91]
	v_mfma_f32_16x16x32_bf16 v[76:79], v[140:143], v[196:199], v[76:79]
	v_mfma_f32_16x16x32_bf16 v[72:75], v[152:155], v[196:199], v[72:75]
	v_mfma_f32_16x16x32_bf16 v[120:123], v[144:147], v[170:173], v[120:123]
	v_mfma_f32_16x16x32_bf16 v[124:127], v[156:159], v[170:173], v[124:127]
	v_mfma_f32_16x16x32_bf16 v[108:111], v[144:147], v[178:181], v[108:111]
	v_mfma_f32_16x16x32_bf16 v[104:107], v[156:159], v[178:181], v[104:107]
	v_mfma_f32_16x16x32_bf16 v[92:95], v[144:147], v[192:195], v[92:95]
	v_mfma_f32_16x16x32_bf16 v[88:91], v[156:159], v[192:195], v[88:91]
	v_mfma_f32_16x16x32_bf16 v[76:79], v[144:147], v[200:203], v[76:79]
	v_mfma_f32_16x16x32_bf16 v[72:75], v[156:159], v[200:203], v[72:75]
	s_setprio 0
	s_barrier
	s_add_i32 s42, s75, 0x100
	s_add_i32 s4, s4, s54
	v_add_u32_e32 v166, s42, v150
	v_lshl_add_u64 v[182:183], v[182:183], 0, s[76:77]
	s_mov_b32 m0, s4
	ds_read_b128 v[204:207], v166
	ds_read_b128 v[208:211], v166 offset:1024
	ds_read_b128 v[212:215], v166 offset:2048
	ds_read_b128 v[216:219], v166 offset:3072
	global_load_lds_dwordx4 v[182:183], off
	v_lshl_add_u64 v[182:183], v[220:221], 0, s[76:77]
	s_add_i32 m0, s4, 0x2000
	s_nop 0
	global_load_lds_dwordx4 v[182:183], off
	s_barrier
; #define PG8_STAGE(bufoff, gbase, voff) do { _Pragma("unroll") for (int _i = 0; _i < 2; ++_i) \
;         __builtin_amdgcn_global_load_lds((const unsigned*)((const char*)(gbase) + (voff)[_i]), (LAS unsigned*)(lds + (bufoff) + ldsw + _i * 8192), 16, 0, 0); } while (0)
; #define PG8_LDA(dst, b, h) do { _Pragma("unroll") for (int m = 0; m < 4; ++m) _Pragma("unroll") for (int k = 0; k < 2; ++k) dst[m][k] = *(const LAS bf16x8*)(lds + PG8_SA(b, h) + aoff + m * 2048 + k * 1024); } while (0)
; #define PG8_MMA(ai, bj, At, Bt) do { __builtin_amdgcn_s_setprio(1); _Pragma("unroll") for (int m = 0; m < 4; ++m) _Pragma("unroll") for (int n = 0; n < 2; ++n) _Pragma("unroll") for (int k = 0; k < 2; ++k) \
;         acc[ai][bj][m][n] = __builtin_amdgcn_mfma_f32_16x16x32_bf16(Bt[n][k], At[m][k], acc[ai][bj][m][n], 0, 0, 0); __builtin_amdgcn_s_setprio(0); } while (0)
; #define PG8_WAIT_V(n) asm volatile("s_waitcnt vmcnt(" #n ")" ::: "memory")
; #define PG8_WAIT_L(n) asm volatile("s_waitcnt lgkmcnt(" #n ")" ::: "memory")
; #define PG8_BAR __builtin_amdgcn_s_barrier()
; #define PG8_SCHED __builtin_amdgcn_sched_barrier(0)
; template <class Epi>
; DI void gemm_phase(LAS unsigned char* lds, const Gemm g, const StaticOrder& S, const Epi& E) {
;     ...
;             PG8_BAR; PG8_WAIT_L(0); PG8_MMA(0, 1, At, B1); PG8_BAR;
;             PG8_LDA(At, 1, 1); PG8_STAGE(PG8_SA(1, 0), a3, voffA);
;             PG8_BAR; PG8_WAIT_L(0); PG8_MMA(1, 0, At, B0); PG8_BAR; PG8_SCHED;
;             PG8_STAGE(PG8_SB(1, 1), b3 + hstep, voffB);
;             PG8_WAIT_V(6); PG8_BAR; PG8_MMA(1, 1, At, B1); PG8_BAR;
	s_waitcnt lgkmcnt(0)
	s_setprio 1
	s_waitcnt lgkmcnt(0)
	v_mfma_f32_16x16x32_bf16 v[116:119], v[204:207], v[160:163], v[116:119]
	v_mfma_f32_16x16x32_bf16 v[112:115], v[212:215], v[160:163], v[112:115]
	v_mfma_f32_16x16x32_bf16 v[100:103], v[204:207], v[174:177], v[100:103]
	v_mfma_f32_16x16x32_bf16 v[96:99], v[212:215], v[174:177], v[96:99]
	v_mfma_f32_16x16x32_bf16 v[84:87], v[204:207], v[188:191], v[84:87]
	v_mfma_f32_16x16x32_bf16 v[80:83], v[212:215], v[188:191], v[80:83]
	v_mfma_f32_16x16x32_bf16 v[68:71], v[204:207], v[196:199], v[68:71]
	v_mfma_f32_16x16x32_bf16 v[64:67], v[212:215], v[196:199], v[64:67]
	v_mfma_f32_16x16x32_bf16 v[116:119], v[208:211], v[170:173], v[116:119]
	v_mfma_f32_16x16x32_bf16 v[112:115], v[216:219], v[170:173], v[112:115]
	v_mfma_f32_16x16x32_bf16 v[100:103], v[208:211], v[178:181], v[100:103]
	v_mfma_f32_16x16x32_bf16 v[96:99], v[216:219], v[178:181], v[96:99]
	v_mfma_f32_16x16x32_bf16 v[84:87], v[208:211], v[192:195], v[84:87]
	v_mfma_f32_16x16x32_bf16 v[80:83], v[216:219], v[192:195], v[80:83]
	v_mfma_f32_16x16x32_bf16 v[68:71], v[208:211], v[200:203], v[68:71]
	v_mfma_f32_16x16x32_bf16 v[64:67], v[216:219], v[200:203], v[64:67]
	s_setprio 0
	s_mov_b32 m0, s61
	v_lshl_add_u64 v[182:183], v[222:223], 0, s[76:77]
	s_barrier
	ds_read_b128 v[160:163], v151 offset:49152
	ds_read_b128 v[170:173], v151 offset:50176
	ds_read_b128 v[174:177], v151 offset:51200
	ds_read_b128 v[178:181], v151 offset:52224
	ds_read_b128 v[188:191], v151 offset:53248
	ds_read_b128 v[192:195], v151 offset:54272
	ds_read_b128 v[196:199], v151 offset:55296
	ds_read_b128 v[200:203], v151 offset:56320
	global_load_lds_dwordx4 v[182:183], off
	v_lshl_add_u64 v[182:183], v[224:225], 0, s[76:77]
	s_mov_b32 m0, s62
	s_nop 0
	global_load_lds_dwordx4 v[182:183], off
	s_barrier
	s_waitcnt lgkmcnt(0)
	s_setprio 1
	s_waitcnt lgkmcnt(0)
	v_mfma_f32_16x16x32_bf16 v[60:63], v[140:143], v[160:163], v[60:63]
	v_mfma_f32_16x16x32_bf16 v[56:59], v[152:155], v[160:163], v[56:59]
	v_mfma_f32_16x16x32_bf16 v[44:47], v[140:143], v[174:177], v[44:47]
	v_mfma_f32_16x16x32_bf16 v[40:43], v[152:155], v[174:177], v[40:43]
	v_mfma_f32_16x16x32_bf16 v[28:31], v[140:143], v[188:191], v[28:31]
	v_mfma_f32_16x16x32_bf16 v[24:27], v[152:155], v[188:191], v[24:27]
	v_mfma_f32_16x16x32_bf16 v[12:15], v[140:143], v[196:199], v[12:15]
	v_mfma_f32_16x16x32_bf16 v[8:11], v[152:155], v[196:199], v[8:11]
	v_mfma_f32_16x16x32_bf16 v[60:63], v[144:147], v[170:173], v[60:63]
	v_mfma_f32_16x16x32_bf16 v[56:59], v[156:159], v[170:173], v[56:59]
	v_mfma_f32_16x16x32_bf16 v[44:47], v[144:147], v[178:181], v[44:47]
	v_mfma_f32_16x16x32_bf16 v[40:43], v[156:159], v[178:181], v[40:43]
	v_mfma_f32_16x16x32_bf16 v[28:31], v[144:147], v[192:195], v[28:31]
	v_mfma_f32_16x16x32_bf16 v[24:27], v[156:159], v[192:195], v[24:27]
	v_mfma_f32_16x16x32_bf16 v[12:15], v[144:147], v[200:203], v[12:15]
	v_mfma_f32_16x16x32_bf16 v[8:11], v[156:159], v[200:203], v[8:11]
	s_setprio 0
	s_barrier
	s_add_i32 s4, s42, s54
	v_lshl_add_u64 v[140:141], v[226:227], 0, s[76:77]
	s_mov_b32 m0, s4
	s_nop 0
	global_load_lds_dwordx4 v[140:141], off
	v_lshl_add_u64 v[140:141], v[228:229], 0, s[76:77]
	s_add_i32 m0, s4, 0x2000
	s_nop 0
	global_load_lds_dwordx4 v[140:141], off
	s_waitcnt vmcnt(6)
	s_barrier
	s_setprio 1
	v_mfma_f32_16x16x32_bf16 v[52:55], v[204:207], v[160:163], v[52:55]
	v_mfma_f32_16x16x32_bf16 v[48:51], v[212:215], v[160:163], v[48:51]
	v_mfma_f32_16x16x32_bf16 v[36:39], v[204:207], v[174:177], v[36:39]
	v_mfma_f32_16x16x32_bf16 v[32:35], v[212:215], v[174:177], v[32:35]
	v_mfma_f32_16x16x32_bf16 v[20:23], v[204:207], v[188:191], v[20:23]
	v_mfma_f32_16x16x32_bf16 v[16:19], v[212:215], v[188:191], v[16:19]
	v_mfma_f32_16x16x32_bf16 v[4:7], v[204:207], v[196:199], v[4:7]
	v_mfma_f32_16x16x32_bf16 v[0:3], v[212:215], v[196:199], v[0:3]
	v_mfma_f32_16x16x32_bf16 v[52:55], v[208:211], v[170:173], v[52:55]
	v_mfma_f32_16x16x32_bf16 v[48:51], v[216:219], v[170:173], v[48:51]
	v_mfma_f32_16x16x32_bf16 v[36:39], v[208:211], v[178:181], v[36:39]
	v_mfma_f32_16x16x32_bf16 v[32:35], v[216:219], v[178:181], v[32:35]
	v_mfma_f32_16x16x32_bf16 v[20:23], v[208:211], v[192:195], v[20:23]
	v_mfma_f32_16x16x32_bf16 v[16:19], v[216:219], v[192:195], v[16:19]
	v_mfma_f32_16x16x32_bf16 v[4:7], v[208:211], v[200:203], v[4:7]
	v_mfma_f32_16x16x32_bf16 v[0:3], v[216:219], v[200:203], v[0:3]
	s_setprio 0
	s_add_u32 s40, s40, 0x100
	s_addc_u32 s41, s41, 0
	s_add_u32 s0, s0, 0x100
	s_addc_u32 s46, s46, 0
	s_cmp_ge_i32 s5, s33
	s_mov_b32 s4, s5
	s_barrier
	s_cbranch_scc0 .LBB0_645
	s_branch .Lpeel_exit_1

; DI u32x4 pk8(f32x4 a, f32x4 b) { u32x4 r; r.x = pk2(a[0], a[1]); r.y = pk2(a[2], a[3]); r.z = pk2(b[0], b[1]); r.w = pk2(b[2], b[3]); return r; }
;     DI void operator()(const Acc& acc, const pg8::Unit& u, int wr, int wc, int fr, int fq) const {
;     ...
;                 } else { const f32x4 sk4 = *(const f32x4*)(ssq_kv + row * 4); const float rk = rsqrtf(((sk4[0] + sk4[1]) + (sk4[2] + sk4[3])) * (1.0f / 128.0f) + EPSN);
;                     bf16_t* dst = pn < 5 ? kn : v; const int cb = ((pn - 3) & 1) * 256;
; #pragma unroll
;                     for (int bj = 0; bj < 2; ++bj) *(u32x4*)(dst + (size_t)row * 512 + cb + bj * 128 + cw) = pk8(acc[ai][bj][m][0] * rk, acc[ai][bj][m][1] * rk);
.Lpeel_exit_1:
.LBB0_646:
	s_lshl_b32 s0, s79, 8
	s_add_i32 s0, s0, s59
	s_cmp_gt_i32 s8, 2
	v_mov_b32_e32 v140, v149
	v_mov_b32_e32 v141, v148
	s_cselect_b64 s[44:45], -1, 0
	s_cmp_lt_u32 s8, 5
	s_cselect_b64 s[46:47], -1, 0
	v_add_u32_e32 v144, s0, v140
	s_lshl_b32 s0, s8, 8
	v_lshlrev_b32_e32 v140, 3, v141
	s_andn2_b32 s79, 0x100, s0
	v_add_u32_e32 v142, s60, v140
	s_cmp_lg_u32 s8, 2
	v_lshlrev_b32_e32 v146, 2, v144
	v_ashrrev_i32_e32 v143, 31, v142
	s_cselect_b64 s[40:41], -1, 0
	v_ashrrev_i32_e32 v147, 31, v146
	s_mov_b64 s[42:43], -1
	s_and_b64 vcc, exec, s[44:45]
	s_cbranch_vccz .LBB0_648
	v_readlane_b32 s4, v236, 16
	v_readlane_b32 s5, v236, 17
	v_readlane_b32 s42, v237, 48
	v_readlane_b32 s43, v237, 49
	v_lshl_add_u64 v[152:153], v[146:147], 2, s[4:5]
	global_load_dwordx4 v[188:191], v[152:153], off offset:256
	global_load_dwordx4 v[192:195], v[152:153], off offset:512
	global_load_dwordx4 v[196:199], v[152:153], off offset:768
	global_load_dwordx4 v[200:203], v[152:153], off offset:2048
	global_load_dwordx4 v[204:207], v[152:153], off offset:2304
	global_load_dwordx4 v[208:211], v[152:153], off offset:2560
	global_load_dwordx4 v[212:215], v[152:153], off offset:2816
	global_load_dwordx4 v[152:155], v[152:153], off
	s_mov_b32 s4, 0x800000
	s_waitcnt vmcnt(0)
	v_mov_b32_e32 v156, v153
	v_mov_b32_e32 v157, v154
	v_mov_b32_e32 v153, v155
	v_pk_add_f32 v[152:153], v[156:157], v[152:153]
	s_nop 0
	v_add_f32_e32 v145, v152, v153
	v_fmamk_f32 v145, v145, 0x3c000000, v168
	v_cmp_gt_f32_e32 vcc, s4, v145
	v_mul_f32_e32 v152, 0x4b800000, v145
	s_and_b64 s[4:5], s[46:47], exec
	v_cndmask_b32_e32 v145, v145, v152, vcc
	v_rsq_f32_e32 v145, v145
	v_readlane_b32 s4, v237, 46
	v_readlane_b32 s5, v237, 47
	s_cselect_b32 s5, s5, s43
	v_mul_f32_e32 v152, 0x45800000, v145
	v_cndmask_b32_e32 v156, v145, v152, vcc
	v_ashrrev_i32_e32 v145, 31, v144
	s_cselect_b32 s4, s4, s42
	v_lshlrev_b64 v[152:153], 10, v[144:145]
	v_lshl_add_u64 v[152:153], s[4:5], 0, v[152:153]
	s_lshl_b32 s8, s79, 1
	v_lshl_add_u64 v[152:153], v[152:153], 0, s[8:9]
	v_lshl_add_u64 v[158:159], v[142:143], 1, v[152:153]
	v_pk_mul_f32 v[154:155], v[122:123], v[156:157] op_sel_hi:[1,0]
	v_pk_mul_f32 v[152:153], v[120:121], v[156:157] op_sel_hi:[1,0]
	v_pk_mul_f32 v[160:161], v[126:127], v[156:157] op_sel_hi:[1,0]
	v_pk_mul_f32 v[162:163], v[124:125], v[156:157] op_sel_hi:[1,0]
	v_cvt_pk_bf16_f32 v152, v152, v153
	v_cvt_pk_bf16_f32 v153, v154, v155
	v_cvt_pk_bf16_f32 v154, v162, v163
	v_cvt_pk_bf16_f32 v155, v160, v161
	global_store_dwordx4 v[158:159], v[152:155], off
	v_pk_mul_f32 v[160:161], v[114:115], v[156:157] op_sel_hi:[1,0]
	s_mov_b64 s[42:43], 0
	v_pk_mul_f32 v[154:155], v[118:119], v[156:157] op_sel_hi:[1,0]
	v_pk_mul_f32 v[152:153], v[116:117], v[156:157] op_sel_hi:[1,0]
	v_pk_mul_f32 v[156:157], v[112:113], v[156:157] op_sel_hi:[1,0]
	v_cvt_pk_bf16_f32 v152, v152, v153
	v_cvt_pk_bf16_f32 v153, v154, v155
	v_cvt_pk_bf16_f32 v154, v156, v157
	v_cvt_pk_bf16_f32 v155, v160, v161
	global_store_dwordx4 v[158:159], v[152:155], off offset:256

; #define PG8_STAGE(bufoff, gbase, voff) do { _Pragma("unroll") for (int _i = 0; _i < 2; ++_i) \
;         __builtin_amdgcn_global_load_lds((const unsigned*)((const char*)(gbase) + (voff)[_i]), (LAS unsigned*)(lds + (bufoff) + ldsw + _i * 8192), 16, 0, 0); } while (0)
; #define PG8_LDA(dst, b, h) do { _Pragma("unroll") for (int m = 0; m < 4; ++m) _Pragma("unroll") for (int k = 0; k < 2; ++k) dst[m][k] = *(const LAS bf16x8*)(lds + PG8_SA(b, h) + aoff + m * 2048 + k * 1024); } while (0)
; #define PG8_LDB(dst, b, h) do { _Pragma("unroll") for (int n = 0; n < 2; ++n) _Pragma("unroll") for (int k = 0; k < 2; ++k) dst[n][k] = *(const LAS bf16x8*)(lds + PG8_SB(b, h) + boff + n * 2048 + k * 1024); } while (0)
; #define PG8_MMA(ai, bj, At, Bt) do { __builtin_amdgcn_s_setprio(1); _Pragma("unroll") for (int m = 0; m < 4; ++m) _Pragma("unroll") for (int n = 0; n < 2; ++n) _Pragma("unroll") for (int k = 0; k < 2; ++k) \
;         acc[ai][bj][m][n] = __builtin_amdgcn_mfma_f32_16x16x32_bf16(Bt[n][k], At[m][k], acc[ai][bj][m][n], 0, 0, 0); __builtin_amdgcn_s_setprio(0); } while (0)
; #define PG8_WAIT_L(n) asm volatile("s_waitcnt lgkmcnt(" #n ")" ::: "memory")
; #define PG8_BAR __builtin_amdgcn_s_barrier()
; #define PG8_SCHED __builtin_amdgcn_sched_barrier(0)
; template <class Epi>
; DI void gemm_phase(LAS unsigned char* lds, const Gemm g, const StaticOrder& S, const Epi& E) {
;     ...
;             const bool last = (t == nt - 2);
;             const char* a1 = cA + (size_t)(t + 1) * kstep;
;             const char* a2 = last ? nA : cA + (size_t)(t + 2) * kstep; const char* b2 = last ? nB : cB + (size_t)(t + 2) * kstep;
;             const char* a3 = a2 + kstep; const char* b3 = b2 + kstep;
;             PG8_LDB(B0, 0, 0); PG8_SCHED; PG8_LDA(At, 0, 0); PG8_STAGE(PG8_SA(1, 1), a1 + hstep, voffA);
;             PG8_WAIT_L(8); PG8_BAR; PG8_WAIT_L(0); PG8_MMA(0, 0, At, B0); PG8_BAR; PG8_SCHED;
;             PG8_LDB(B1, 0, 1); PG8_STAGE(PG8_SB(0, 0), b2, voffB);
;             PG8_BAR; PG8_WAIT_L(0); PG8_MMA(0, 1, At, B1); PG8_BAR;
;             PG8_LDA(At, 0, 1); PG8_STAGE(PG8_SA(0, 0), a2, voffA);
;             PG8_BAR; PG8_WAIT_L(0); PG8_MMA(1, 0, At, B0); PG8_BAR; PG8_SCHED;
.LBB0_1229:
	s_andn2_b64 vcc, exec, s[14:15]
	s_waitcnt lgkmcnt(0)
	s_cbranch_vccnz .LBB0_1232
	s_add_u32 s36, s36, 0x80
	s_addc_u32 s37, s37, 0
	s_add_u32 s0, s44, 0x100
	s_addc_u32 s44, s45, 0
	s_mov_b32 s4, 0
	s_add_i32 s5, s4, 2
	s_add_u32 s40, s36, 0x80
	s_addc_u32 s41, s37, 0
	s_add_i32 s45, s60, 0x100
	v_add_u32_e32 v154, s45, v144
	ds_read_b128 v[138:141], v154
	ds_read_b128 v[146:149], v154 offset:1024
	ds_read_b128 v[150:153], v154 offset:2048
	ds_read_b128 v[154:157], v154 offset:3072
	s_cmp_eq_u32 s76, s4
	s_cselect_b32 s41, s17, s41
	s_cselect_b32 s40, s16, s40
	s_cselect_b32 s43, s19, s44
	s_cselect_b32 s42, s18, s0
	v_lshl_add_u64 v[162:163], s[36:37], 0, v[134:135]
	s_add_i32 m0, s51, 0xc000
	ds_read_b128 v[158:161], v145
	ds_read_b128 v[170:173], v145 offset:1024
	ds_read_b128 v[174:177], v145 offset:2048
	ds_read_b128 v[178:181], v145 offset:3072
	ds_read_b128 v[188:191], v145 offset:4096
	ds_read_b128 v[192:195], v145 offset:5120
	ds_read_b128 v[196:199], v145 offset:6144
	ds_read_b128 v[200:203], v145 offset:7168
	global_load_lds_dwordx4 v[162:163], off
	v_lshl_add_u64 v[162:163], s[36:37], 0, v[136:137]
	s_add_i32 m0, s51, 0xe000
	s_nop 0
	global_load_lds_dwordx4 v[162:163], off
	s_waitcnt lgkmcnt(8)
	s_barrier
	s_waitcnt lgkmcnt(0)
	s_setprio 1
	s_waitcnt lgkmcnt(0)
	v_mfma_f32_16x16x32_bf16 v[124:127], v[138:141], v[158:161], 0
	v_mfma_f32_16x16x32_bf16 v[120:123], v[150:153], v[158:161], 0
	v_mfma_f32_16x16x32_bf16 v[108:111], v[138:141], v[174:177], 0
	v_mfma_f32_16x16x32_bf16 v[104:107], v[150:153], v[174:177], 0
	v_mfma_f32_16x16x32_bf16 v[92:95], v[138:141], v[188:191], 0
	v_mfma_f32_16x16x32_bf16 v[88:91], v[150:153], v[188:191], 0
	v_mfma_f32_16x16x32_bf16 v[76:79], v[138:141], v[196:199], 0
	v_mfma_f32_16x16x32_bf16 v[72:75], v[150:153], v[196:199], 0
	v_mfma_f32_16x16x32_bf16 v[124:127], v[146:149], v[170:173], v[124:127]
	v_mfma_f32_16x16x32_bf16 v[120:123], v[154:157], v[170:173], v[120:123]
	v_mfma_f32_16x16x32_bf16 v[108:111], v[146:149], v[178:181], v[108:111]
	v_mfma_f32_16x16x32_bf16 v[104:107], v[154:157], v[178:181], v[104:107]
	v_mfma_f32_16x16x32_bf16 v[92:95], v[146:149], v[192:195], v[92:95]
	v_mfma_f32_16x16x32_bf16 v[88:91], v[154:157], v[192:195], v[88:91]
	v_mfma_f32_16x16x32_bf16 v[76:79], v[146:149], v[200:203], v[76:79]
	v_mfma_f32_16x16x32_bf16 v[72:75], v[154:157], v[200:203], v[72:75]
	s_setprio 0
	s_barrier
	s_add_i32 s4, s61, 0x100
	v_add_u32_e32 v162, s4, v144
	s_add_i32 s45, s45, s50
	ds_read_b128 v[204:207], v162
	ds_read_b128 v[208:211], v162 offset:1024
	ds_read_b128 v[212:215], v162 offset:2048
	ds_read_b128 v[216:219], v162 offset:3072
	v_lshl_add_u64 v[162:163], s[42:43], 0, v[166:167]
	s_mov_b32 m0, s45
	v_lshl_add_u64 v[182:183], s[42:43], 0, v[132:133]
	global_load_lds_dwordx4 v[162:163], off
	s_add_i32 m0, s45, 0x2000
	s_nop 0
	global_load_lds_dwordx4 v[182:183], off
	s_barrier
	s_waitcnt lgkmcnt(0)
	s_setprio 1
	s_waitcnt lgkmcnt(0)
	v_mfma_f32_16x16x32_bf16 v[116:119], v[204:207], v[158:161], 0
	v_mfma_f32_16x16x32_bf16 v[112:115], v[212:215], v[158:161], 0
	v_mfma_f32_16x16x32_bf16 v[100:103], v[204:207], v[174:177], 0
	v_mfma_f32_16x16x32_bf16 v[96:99], v[212:215], v[174:177], 0
	v_mfma_f32_16x16x32_bf16 v[84:87], v[204:207], v[188:191], 0
	v_mfma_f32_16x16x32_bf16 v[80:83], v[212:215], v[188:191], 0
	v_mfma_f32_16x16x32_bf16 v[68:71], v[204:207], v[196:199], 0
	v_mfma_f32_16x16x32_bf16 v[64:67], v[212:215], v[196:199], 0
	v_mfma_f32_16x16x32_bf16 v[116:119], v[208:211], v[170:173], v[116:119]
	v_mfma_f32_16x16x32_bf16 v[112:115], v[216:219], v[170:173], v[112:115]
	v_mfma_f32_16x16x32_bf16 v[100:103], v[208:211], v[178:181], v[100:103]
	v_mfma_f32_16x16x32_bf16 v[96:99], v[216:219], v[178:181], v[96:99]
	v_mfma_f32_16x16x32_bf16 v[84:87], v[208:211], v[192:195], v[84:87]
	v_mfma_f32_16x16x32_bf16 v[80:83], v[216:219], v[192:195], v[80:83]
	v_mfma_f32_16x16x32_bf16 v[68:71], v[208:211], v[200:203], v[68:71]
	v_mfma_f32_16x16x32_bf16 v[64:67], v[216:219], v[200:203], v[64:67]
	s_setprio 0
	s_mov_b32 m0, s51
	v_lshl_add_u64 v[220:221], s[40:41], 0, v[128:129]
	s_barrier
	ds_read_b128 v[158:161], v145 offset:16384
	ds_read_b128 v[170:173], v145 offset:17408
	ds_read_b128 v[174:177], v145 offset:18432
	ds_read_b128 v[178:181], v145 offset:19456
	ds_read_b128 v[188:191], v145 offset:20480
	ds_read_b128 v[192:195], v145 offset:21504
	ds_read_b128 v[196:199], v145 offset:22528
	ds_read_b128 v[200:203], v145 offset:23552
	global_load_lds_dwordx4 v[220:221], off
	v_lshl_add_u64 v[222:223], s[40:41], 0, v[130:131]
	s_mov_b32 m0, s79
	s_nop 0
	global_load_lds_dwordx4 v[222:223], off
	s_barrier
	s_waitcnt lgkmcnt(0)
	s_setprio 1
	s_waitcnt lgkmcnt(0)
	v_mfma_f32_16x16x32_bf16 v[60:63], v[138:141], v[158:161], 0
	v_mfma_f32_16x16x32_bf16 v[56:59], v[150:153], v[158:161], 0
	v_mfma_f32_16x16x32_bf16 v[44:47], v[138:141], v[174:177], 0
	v_mfma_f32_16x16x32_bf16 v[40:43], v[150:153], v[174:177], 0
	v_mfma_f32_16x16x32_bf16 v[28:31], v[138:141], v[188:191], 0
	v_mfma_f32_16x16x32_bf16 v[24:27], v[150:153], v[188:191], 0
	v_mfma_f32_16x16x32_bf16 v[12:15], v[138:141], v[196:199], 0
	v_mfma_f32_16x16x32_bf16 v[8:11], v[150:153], v[196:199], 0
	v_mfma_f32_16x16x32_bf16 v[60:63], v[146:149], v[170:173], v[60:63]
	v_mfma_f32_16x16x32_bf16 v[56:59], v[154:157], v[170:173], v[56:59]
	v_mfma_f32_16x16x32_bf16 v[44:47], v[146:149], v[178:181], v[44:47]
	v_mfma_f32_16x16x32_bf16 v[40:43], v[154:157], v[178:181], v[40:43]
	v_mfma_f32_16x16x32_bf16 v[28:31], v[146:149], v[192:195], v[28:31]
	v_mfma_f32_16x16x32_bf16 v[24:27], v[154:157], v[192:195], v[24:27]
	v_mfma_f32_16x16x32_bf16 v[12:15], v[146:149], v[200:203], v[12:15]
	v_mfma_f32_16x16x32_bf16 v[8:11], v[154:157], v[200:203], v[8:11]
	s_setprio 0
	s_barrier
; #define PG8_STAGE(bufoff, gbase, voff) do { _Pragma("unroll") for (int _i = 0; _i < 2; ++_i) \
;         __builtin_amdgcn_global_load_lds((const unsigned*)((const char*)(gbase) + (voff)[_i]), (LAS unsigned*)(lds + (bufoff) + ldsw + _i * 8192), 16, 0, 0); } while (0)
; #define PG8_LDA(dst, b, h) do { _Pragma("unroll") for (int m = 0; m < 4; ++m) _Pragma("unroll") for (int k = 0; k < 2; ++k) dst[m][k] = *(const LAS bf16x8*)(lds + PG8_SA(b, h) + aoff + m * 2048 + k * 1024); } while (0)
; #define PG8_LDB(dst, b, h) do { _Pragma("unroll") for (int n = 0; n < 2; ++n) _Pragma("unroll") for (int k = 0; k < 2; ++k) dst[n][k] = *(const LAS bf16x8*)(lds + PG8_SB(b, h) + boff + n * 2048 + k * 1024); } while (0)
; #define PG8_MMA(ai, bj, At, Bt) do { __builtin_amdgcn_s_setprio(1); _Pragma("unroll") for (int m = 0; m < 4; ++m) _Pragma("unroll") for (int n = 0; n < 2; ++n) _Pragma("unroll") for (int k = 0; k < 2; ++k) \
;         acc[ai][bj][m][n] = __builtin_amdgcn_mfma_f32_16x16x32_bf16(Bt[n][k], At[m][k], acc[ai][bj][m][n], 0, 0, 0); __builtin_amdgcn_s_setprio(0); } while (0)
; #define PG8_WAIT_V(n) asm volatile("s_waitcnt vmcnt(" #n ")" ::: "memory")
; #define PG8_WAIT_L(n) asm volatile("s_waitcnt lgkmcnt(" #n ")" ::: "memory")
; #define PG8_BAR __builtin_amdgcn_s_barrier()
; #define PG8_SCHED __builtin_amdgcn_sched_barrier(0)
; template <class Epi>
; DI void gemm_phase(LAS unsigned char* lds, const Gemm g, const StaticOrder& S, const Epi& E) {
;     ...
;             PG8_STAGE(PG8_SB(0, 1), b2 + hstep, voffB);
;             PG8_WAIT_V(6); PG8_BAR; PG8_MMA(1, 1, At, B1); PG8_BAR;
;             PG8_LDB(B0, 1, 0); PG8_SCHED; PG8_LDA(At, 1, 0); PG8_STAGE(PG8_SA(0, 1), a2 + hstep, voffA);
;             PG8_WAIT_L(8); PG8_BAR; PG8_WAIT_L(0); PG8_MMA(0, 0, At, B0); PG8_BAR; PG8_SCHED;
;             PG8_LDB(B1, 1, 1); PG8_STAGE(PG8_SB(1, 0), b3, voffB);
	s_add_u32 s42, s42, s10
	s_addc_u32 s43, s43, s11
	s_add_i32 s4, s4, s50
	v_lshl_add_u64 v[224:225], s[42:43], 0, v[166:167]
	s_mov_b32 m0, s4
	v_lshl_add_u64 v[226:227], s[42:43], 0, v[132:133]
	global_load_lds_dwordx4 v[224:225], off
	s_add_i32 m0, s4, 0x2000
	s_nop 0
	global_load_lds_dwordx4 v[226:227], off
	s_waitcnt vmcnt(6)
	s_barrier
	s_setprio 1
	v_mfma_f32_16x16x32_bf16 v[52:55], v[204:207], v[158:161], 0
	v_mfma_f32_16x16x32_bf16 v[48:51], v[212:215], v[158:161], 0
	v_mfma_f32_16x16x32_bf16 v[36:39], v[204:207], v[174:177], 0
	v_mfma_f32_16x16x32_bf16 v[32:35], v[212:215], v[174:177], 0
	v_mfma_f32_16x16x32_bf16 v[20:23], v[204:207], v[188:191], 0
	v_mfma_f32_16x16x32_bf16 v[16:19], v[212:215], v[188:191], 0
	v_mfma_f32_16x16x32_bf16 v[4:7], v[204:207], v[196:199], 0
	v_mfma_f32_16x16x32_bf16 v[0:3], v[212:215], v[196:199], 0
	v_mfma_f32_16x16x32_bf16 v[52:55], v[208:211], v[170:173], v[52:55]
	v_mfma_f32_16x16x32_bf16 v[48:51], v[216:219], v[170:173], v[48:51]
	v_mfma_f32_16x16x32_bf16 v[36:39], v[208:211], v[178:181], v[36:39]
	v_mfma_f32_16x16x32_bf16 v[32:35], v[216:219], v[178:181], v[32:35]
	v_mfma_f32_16x16x32_bf16 v[20:23], v[208:211], v[192:195], v[20:23]
	v_mfma_f32_16x16x32_bf16 v[16:19], v[216:219], v[192:195], v[16:19]
	v_mfma_f32_16x16x32_bf16 v[4:7], v[208:211], v[200:203], v[4:7]
	v_mfma_f32_16x16x32_bf16 v[0:3], v[216:219], v[200:203], v[0:3]
	s_setprio 0
	s_add_i32 s4, s62, 0x100
	v_add_u32_e32 v154, s4, v144
	s_barrier
	ds_read_b128 v[138:141], v154
	ds_read_b128 v[146:149], v154 offset:1024
	ds_read_b128 v[150:153], v154 offset:2048
	ds_read_b128 v[154:157], v154 offset:3072
	s_add_u32 s40, s40, s10
	s_addc_u32 s41, s41, s11
	s_mov_b32 m0, s88
	v_lshl_add_u64 v[204:205], s[40:41], 0, v[128:129]
	ds_read_b128 v[158:161], v145 offset:32768
	ds_read_b128 v[170:173], v145 offset:33792
	ds_read_b128 v[174:177], v145 offset:34816
	ds_read_b128 v[178:181], v145 offset:35840
	ds_read_b128 v[188:191], v145 offset:36864
	ds_read_b128 v[192:195], v145 offset:37888
	ds_read_b128 v[196:199], v145 offset:38912
	ds_read_b128 v[200:203], v145 offset:39936
	global_load_lds_dwordx4 v[204:205], off
	v_lshl_add_u64 v[204:205], s[40:41], 0, v[130:131]
	s_mov_b32 m0, s89
	s_nop 0
	global_load_lds_dwordx4 v[204:205], off
	s_waitcnt lgkmcnt(8)
	s_barrier
	s_waitcnt lgkmcnt(0)
	s_setprio 1
	s_waitcnt lgkmcnt(0)
	v_mfma_f32_16x16x32_bf16 v[124:127], v[138:141], v[158:161], v[124:127]
	v_mfma_f32_16x16x32_bf16 v[120:123], v[150:153], v[158:161], v[120:123]
	v_mfma_f32_16x16x32_bf16 v[108:111], v[138:141], v[174:177], v[108:111]
	v_mfma_f32_16x16x32_bf16 v[104:107], v[150:153], v[174:177], v[104:107]
	v_mfma_f32_16x16x32_bf16 v[92:95], v[138:141], v[188:191], v[92:95]
	v_mfma_f32_16x16x32_bf16 v[88:91], v[150:153], v[188:191], v[88:91]
	v_mfma_f32_16x16x32_bf16 v[76:79], v[138:141], v[196:199], v[76:79]
	v_mfma_f32_16x16x32_bf16 v[72:75], v[150:153], v[196:199], v[72:75]
	v_mfma_f32_16x16x32_bf16 v[124:127], v[146:149], v[170:173], v[124:127]
	v_mfma_f32_16x16x32_bf16 v[120:123], v[154:157], v[170:173], v[120:123]
	v_mfma_f32_16x16x32_bf16 v[108:111], v[146:149], v[178:181], v[108:111]
	v_mfma_f32_16x16x32_bf16 v[104:107], v[154:157], v[178:181], v[104:107]
	v_mfma_f32_16x16x32_bf16 v[92:95], v[146:149], v[192:195], v[92:95]
	v_mfma_f32_16x16x32_bf16 v[88:91], v[154:157], v[192:195], v[88:91]
	v_mfma_f32_16x16x32_bf16 v[76:79], v[146:149], v[200:203], v[76:79]
	v_mfma_f32_16x16x32_bf16 v[72:75], v[154:157], v[200:203], v[72:75]
	s_setprio 0
	s_barrier
	s_add_i32 s40, s63, 0x100
	s_add_i32 s4, s4, s50
	v_add_u32_e32 v216, s40, v144
	v_lshl_add_u64 v[162:163], v[162:163], 0, s[66:67]
	s_mov_b32 m0, s4
	ds_read_b128 v[204:207], v216
	ds_read_b128 v[208:211], v216 offset:1024
	ds_read_b128 v[212:215], v216 offset:2048
	ds_read_b128 v[216:219], v216 offset:3072
	global_load_lds_dwordx4 v[162:163], off
	v_lshl_add_u64 v[162:163], v[182:183], 0, s[66:67]
	s_add_i32 m0, s4, 0x2000
	s_nop 0
	global_load_lds_dwordx4 v[162:163], off
	s_barrier
; #define PG8_STAGE(bufoff, gbase, voff) do { _Pragma("unroll") for (int _i = 0; _i < 2; ++_i) \
;         __builtin_amdgcn_global_load_lds((const unsigned*)((const char*)(gbase) + (voff)[_i]), (LAS unsigned*)(lds + (bufoff) + ldsw + _i * 8192), 16, 0, 0); } while (0)
; #define PG8_LDA(dst, b, h) do { _Pragma("unroll") for (int m = 0; m < 4; ++m) _Pragma("unroll") for (int k = 0; k < 2; ++k) dst[m][k] = *(const LAS bf16x8*)(lds + PG8_SA(b, h) + aoff + m * 2048 + k * 1024); } while (0)
; #define PG8_MMA(ai, bj, At, Bt) do { __builtin_amdgcn_s_setprio(1); _Pragma("unroll") for (int m = 0; m < 4; ++m) _Pragma("unroll") for (int n = 0; n < 2; ++n) _Pragma("unroll") for (int k = 0; k < 2; ++k) \
;         acc[ai][bj][m][n] = __builtin_amdgcn_mfma_f32_16x16x32_bf16(Bt[n][k], At[m][k], acc[ai][bj][m][n], 0, 0, 0); __builtin_amdgcn_s_setprio(0); } while (0)
; #define PG8_WAIT_V(n) asm volatile("s_waitcnt vmcnt(" #n ")" ::: "memory")
; #define PG8_WAIT_L(n) asm volatile("s_waitcnt lgkmcnt(" #n ")" ::: "memory")
; #define PG8_BAR __builtin_amdgcn_s_barrier()
; #define PG8_SCHED __builtin_amdgcn_sched_barrier(0)
; template <class Epi>
; DI void gemm_phase(LAS unsigned char* lds, const Gemm g, const StaticOrder& S, const Epi& E) {
;     ...
;             PG8_BAR; PG8_WAIT_L(0); PG8_MMA(0, 1, At, B1); PG8_BAR;
;             PG8_LDA(At, 1, 1); PG8_STAGE(PG8_SA(1, 0), a3, voffA);
;             PG8_BAR; PG8_WAIT_L(0); PG8_MMA(1, 0, At, B0); PG8_BAR; PG8_SCHED;
;             PG8_STAGE(PG8_SB(1, 1), b3 + hstep, voffB);
;             PG8_WAIT_V(6); PG8_BAR; PG8_MMA(1, 1, At, B1); PG8_BAR;
	s_waitcnt lgkmcnt(0)
	s_setprio 1
	s_waitcnt lgkmcnt(0)
	v_mfma_f32_16x16x32_bf16 v[116:119], v[204:207], v[158:161], v[116:119]
	v_mfma_f32_16x16x32_bf16 v[112:115], v[212:215], v[158:161], v[112:115]
	v_mfma_f32_16x16x32_bf16 v[100:103], v[204:207], v[174:177], v[100:103]
	v_mfma_f32_16x16x32_bf16 v[96:99], v[212:215], v[174:177], v[96:99]
	v_mfma_f32_16x16x32_bf16 v[84:87], v[204:207], v[188:191], v[84:87]
	v_mfma_f32_16x16x32_bf16 v[80:83], v[212:215], v[188:191], v[80:83]
	v_mfma_f32_16x16x32_bf16 v[68:71], v[204:207], v[196:199], v[68:71]
	v_mfma_f32_16x16x32_bf16 v[64:67], v[212:215], v[196:199], v[64:67]
	v_mfma_f32_16x16x32_bf16 v[116:119], v[208:211], v[170:173], v[116:119]
	v_mfma_f32_16x16x32_bf16 v[112:115], v[216:219], v[170:173], v[112:115]
	v_mfma_f32_16x16x32_bf16 v[100:103], v[208:211], v[178:181], v[100:103]
	v_mfma_f32_16x16x32_bf16 v[96:99], v[216:219], v[178:181], v[96:99]
	v_mfma_f32_16x16x32_bf16 v[84:87], v[208:211], v[192:195], v[84:87]
	v_mfma_f32_16x16x32_bf16 v[80:83], v[216:219], v[192:195], v[80:83]
	v_mfma_f32_16x16x32_bf16 v[68:71], v[208:211], v[200:203], v[68:71]
	v_mfma_f32_16x16x32_bf16 v[64:67], v[216:219], v[200:203], v[64:67]
	s_setprio 0
	s_mov_b32 m0, s90
	v_lshl_add_u64 v[162:163], v[220:221], 0, s[66:67]
	s_barrier
	ds_read_b128 v[158:161], v145 offset:49152
	ds_read_b128 v[170:173], v145 offset:50176
	ds_read_b128 v[174:177], v145 offset:51200
	ds_read_b128 v[178:181], v145 offset:52224
	ds_read_b128 v[188:191], v145 offset:53248
	ds_read_b128 v[192:195], v145 offset:54272
	ds_read_b128 v[196:199], v145 offset:55296
	ds_read_b128 v[200:203], v145 offset:56320
	global_load_lds_dwordx4 v[162:163], off
	v_lshl_add_u64 v[162:163], v[222:223], 0, s[66:67]
	s_mov_b32 m0, s91
	s_nop 0
	global_load_lds_dwordx4 v[162:163], off
	s_barrier
	s_waitcnt lgkmcnt(0)
	s_setprio 1
	s_waitcnt lgkmcnt(0)
	v_mfma_f32_16x16x32_bf16 v[60:63], v[138:141], v[158:161], v[60:63]
	v_mfma_f32_16x16x32_bf16 v[56:59], v[150:153], v[158:161], v[56:59]
	v_mfma_f32_16x16x32_bf16 v[44:47], v[138:141], v[174:177], v[44:47]
	v_mfma_f32_16x16x32_bf16 v[40:43], v[150:153], v[174:177], v[40:43]
	v_mfma_f32_16x16x32_bf16 v[28:31], v[138:141], v[188:191], v[28:31]
	v_mfma_f32_16x16x32_bf16 v[24:27], v[150:153], v[188:191], v[24:27]
	v_mfma_f32_16x16x32_bf16 v[12:15], v[138:141], v[196:199], v[12:15]
	v_mfma_f32_16x16x32_bf16 v[8:11], v[150:153], v[196:199], v[8:11]
	v_mfma_f32_16x16x32_bf16 v[60:63], v[146:149], v[170:173], v[60:63]
	v_mfma_f32_16x16x32_bf16 v[56:59], v[154:157], v[170:173], v[56:59]
	v_mfma_f32_16x16x32_bf16 v[44:47], v[146:149], v[178:181], v[44:47]
	v_mfma_f32_16x16x32_bf16 v[40:43], v[154:157], v[178:181], v[40:43]
	v_mfma_f32_16x16x32_bf16 v[28:31], v[146:149], v[192:195], v[28:31]
	v_mfma_f32_16x16x32_bf16 v[24:27], v[154:157], v[192:195], v[24:27]
	v_mfma_f32_16x16x32_bf16 v[12:15], v[146:149], v[200:203], v[12:15]
	v_mfma_f32_16x16x32_bf16 v[8:11], v[154:157], v[200:203], v[8:11]
	s_setprio 0
	s_barrier
	s_add_i32 s4, s40, s50
	v_lshl_add_u64 v[138:139], v[224:225], 0, s[66:67]
	s_mov_b32 m0, s4
	s_nop 0
	global_load_lds_dwordx4 v[138:139], off
	v_lshl_add_u64 v[138:139], v[226:227], 0, s[66:67]
	s_add_i32 m0, s4, 0x2000
	s_nop 0
	global_load_lds_dwordx4 v[138:139], off
	s_waitcnt vmcnt(6)
	s_barrier
	s_setprio 1
	v_mfma_f32_16x16x32_bf16 v[52:55], v[204:207], v[158:161], v[52:55]
	v_mfma_f32_16x16x32_bf16 v[48:51], v[212:215], v[158:161], v[48:51]
	v_mfma_f32_16x16x32_bf16 v[36:39], v[204:207], v[174:177], v[36:39]
	v_mfma_f32_16x16x32_bf16 v[32:35], v[212:215], v[174:177], v[32:35]
	v_mfma_f32_16x16x32_bf16 v[20:23], v[204:207], v[188:191], v[20:23]
	v_mfma_f32_16x16x32_bf16 v[16:19], v[212:215], v[188:191], v[16:19]
	v_mfma_f32_16x16x32_bf16 v[4:7], v[204:207], v[196:199], v[4:7]
	v_mfma_f32_16x16x32_bf16 v[0:3], v[212:215], v[196:199], v[0:3]
	v_mfma_f32_16x16x32_bf16 v[52:55], v[208:211], v[170:173], v[52:55]
	v_mfma_f32_16x16x32_bf16 v[48:51], v[216:219], v[170:173], v[48:51]
	v_mfma_f32_16x16x32_bf16 v[36:39], v[208:211], v[178:181], v[36:39]
	v_mfma_f32_16x16x32_bf16 v[32:35], v[216:219], v[178:181], v[32:35]
	v_mfma_f32_16x16x32_bf16 v[20:23], v[208:211], v[192:195], v[20:23]
	v_mfma_f32_16x16x32_bf16 v[16:19], v[216:219], v[192:195], v[16:19]
	v_mfma_f32_16x16x32_bf16 v[4:7], v[208:211], v[200:203], v[4:7]
	v_mfma_f32_16x16x32_bf16 v[0:3], v[216:219], v[200:203], v[0:3]
	s_setprio 0
	s_add_u32 s36, s36, 0x100
	s_addc_u32 s37, s37, 0
	s_add_u32 s0, s0, 0x100
	s_addc_u32 s44, s44, 0
	s_cmp_ge_i32 s5, s73
	s_mov_b32 s4, s5
	s_barrier
	s_cbranch_scc0 .LBB0_1231
	s_branch .Lpeel_exit_2

; DI float blo(unsigned w) { return __uint_as_float(w << 16); }
; DI float bhi(unsigned w) { return __uint_as_float(w & 0xffff0000u); }
; DI u32x4 pk8(f32x4 a, f32x4 b) { u32x4 r; r.x = pk2(a[0], a[1]); r.y = pk2(a[2], a[3]); r.z = pk2(b[0], b[1]); r.w = pk2(b[2], b[3]); return r; }
;     DI void operator()(const Acc& acc, const pg8::Unit& u, int wr, int wc, int fr, int fq) const {
;     ...
;             for (int m = 0; m < 4; ++m) { const int row = row0 + ai * 128 + m * 16; float ss = 0.f;
; #pragma unroll
;                 for (int bj = 0; bj < 2; ++bj) { f32x4 v0 = acc[ai][bj][m][0], v1 = acc[ai][bj][m][1]; const size_t off = (size_t)row * 1024 + c0 + bj * 128;
;                     if (gate) { const u32x4 gw = *(const u32x4*)(gate + off);
;                         v0[0] *= blo(gw.x); v0[1] *= bhi(gw.x); v0[2] *= blo(gw.y); v0[3] *= bhi(gw.y); v1[0] *= blo(gw.z); v1[1] *= bhi(gw.z); v1[2] *= blo(gw.w); v1[3] *= bhi(gw.w); }
;                     *(u32x4*)(t + off) = pk8(v0, v1);
;                     ss += v0[0] * v0[0] + v0[1] * v0[1] + v0[2] * v0[2] + v0[3] * v0[3] + v1[0] * v1[0] + v1[1] * v1[1] + v1[2] * v1[2] + v1[3] * v1[3]; }
;                 ss += __shfl_xor(ss, 16); ss += __shfl_xor(ss, 32);
;                 if (fq == 0) ssq[row * 16 + u.pn * 4 + wc] = ss;
.Lpeel_exit_2:
.LBB0_1232:
	v_and_b32_e32 v147, 64, v184
	v_xor_b32_e32 v146, 16, v184
	v_add_u32_e32 v148, 64, v147
	v_cmp_lt_i32_e32 vcc, v146, v148
	v_cvt_pk_bf16_f32 v150, v120, v121
	s_lshl_b32 s0, s78, 8
	v_cndmask_b32_e32 v146, v184, v146, vcc
	v_lshlrev_b32_e32 v147, 2, v146
	v_xor_b32_e32 v146, 32, v184
	v_cmp_lt_i32_e32 vcc, v146, v148
	v_cvt_pk_bf16_f32 v148, v124, v125
	v_mul_f32_e32 v125, v125, v125
	v_fmac_f32_e32 v125, v124, v124
	v_fmac_f32_e32 v125, v126, v126
	v_fmac_f32_e32 v125, v127, v127
	v_fmac_f32_e32 v125, v120, v120
	v_mul_f32_e32 v120, v117, v117
	v_fmac_f32_e32 v120, v116, v116
	v_fmac_f32_e32 v120, v118, v118
	v_fmac_f32_e32 v120, v119, v119
	v_fmac_f32_e32 v120, v112, v112
	v_fmac_f32_e32 v125, v121, v121
	v_fmac_f32_e32 v120, v113, v113
	v_fmac_f32_e32 v125, v122, v122
	v_fmac_f32_e32 v120, v114, v114
	v_fmac_f32_e32 v125, v123, v123
	v_fmac_f32_e32 v120, v115, v115
	v_mov_b32_e32 v138, v143
	v_mov_b32_e32 v141, v142
	s_add_i32 s0, s0, s74
	v_cvt_pk_bf16_f32 v151, v122, v123
	v_add_f32_e32 v122, v120, v125
	ds_bpermute_b32 v123, v147, v122
	v_add_u32_e32 v140, s0, v138
	s_lshl_b32 s0, s71, 8
	s_or_b32 s0, s0, s75
	v_lshl_add_u32 v138, v141, 3, s0
	v_cndmask_b32_e32 v146, v184, v146, vcc
	v_cmp_eq_u32_e32 vcc, 0, v141
	v_ashrrev_i32_e32 v141, 31, v140
	v_readlane_b32 s4, v237, 44
	v_lshlrev_b64 v[152:153], 11, v[140:141]
	v_readlane_b32 s5, v237, 45
	v_ashrrev_i32_e32 v139, 31, v138
	v_lshlrev_b32_e32 v146, 2, v146
	v_lshl_add_u64 v[120:121], s[4:5], 0, v[152:153]
	v_lshl_add_u64 v[124:125], v[138:139], 1, v[120:121]
	v_cvt_pk_bf16_f32 v120, v116, v117
	s_waitcnt lgkmcnt(0)
	v_add_f32_e32 v116, v122, v123
	ds_bpermute_b32 v117, v146, v116
	s_lshl_b32 s0, s71, 2
	s_or_b32 s0, s0, s72
	v_cvt_pk_bf16_f32 v149, v126, v127
	v_cvt_pk_bf16_f32 v121, v118, v119
	v_cvt_pk_bf16_f32 v122, v112, v113
	v_cvt_pk_bf16_f32 v123, v114, v115
	global_store_dwordx4 v[124:125], v[148:151], off
	global_store_dwordx4 v[124:125], v[120:123], off offset:256
	s_and_saveexec_b64 s[36:37], vcc
	s_cbranch_execz .LBB0_1234
	v_lshl_add_u32 v112, v140, 4, s0
	v_readlane_b32 s4, v238, 28
	v_ashrrev_i32_e32 v113, 31, v112
	v_readlane_b32 s5, v238, 29
	s_waitcnt lgkmcnt(0)
	v_add_f32_e32 v114, v116, v117
	v_lshl_add_u64 v[112:113], v[112:113], 2, s[4:5]
	global_store_dword v[112:113], v114, off

; #define PG8_STAGE(bufoff, gbase, voff) do { _Pragma("unroll") for (int _i = 0; _i < 2; ++_i) \
;         __builtin_amdgcn_global_load_lds((const unsigned*)((const char*)(gbase) + (voff)[_i]), (LAS unsigned*)(lds + (bufoff) + ldsw + _i * 8192), 16, 0, 0); } while (0)
; #define PG8_LDA(dst, b, h) do { _Pragma("unroll") for (int m = 0; m < 4; ++m) _Pragma("unroll") for (int k = 0; k < 2; ++k) dst[m][k] = *(const LAS bf16x8*)(lds + PG8_SA(b, h) + aoff + m * 2048 + k * 1024); } while (0)
; #define PG8_LDB(dst, b, h) do { _Pragma("unroll") for (int n = 0; n < 2; ++n) _Pragma("unroll") for (int k = 0; k < 2; ++k) dst[n][k] = *(const LAS bf16x8*)(lds + PG8_SB(b, h) + boff + n * 2048 + k * 1024); } while (0)
; #define PG8_MMA(ai, bj, At, Bt) do { __builtin_amdgcn_s_setprio(1); _Pragma("unroll") for (int m = 0; m < 4; ++m) _Pragma("unroll") for (int n = 0; n < 2; ++n) _Pragma("unroll") for (int k = 0; k < 2; ++k) \
;         acc[ai][bj][m][n] = __builtin_amdgcn_mfma_f32_16x16x32_bf16(Bt[n][k], At[m][k], acc[ai][bj][m][n], 0, 0, 0); __builtin_amdgcn_s_setprio(0); } while (0)
; #define PG8_WAIT_L(n) asm volatile("s_waitcnt lgkmcnt(" #n ")" ::: "memory")
; #define PG8_BAR __builtin_amdgcn_s_barrier()
; #define PG8_SCHED __builtin_amdgcn_sched_barrier(0)
; template <class Epi>
; DI void gemm_phase(LAS unsigned char* lds, const Gemm g, const StaticOrder& S, const Epi& E) {
;     ...
;             const bool last = (t == nt - 2);
;             const char* a1 = cA + (size_t)(t + 1) * kstep;
;             const char* a2 = last ? nA : cA + (size_t)(t + 2) * kstep; const char* b2 = last ? nB : cB + (size_t)(t + 2) * kstep;
;             const char* a3 = a2 + kstep; const char* b3 = b2 + kstep;
;             PG8_LDB(B0, 0, 0); PG8_SCHED; PG8_LDA(At, 0, 0); PG8_STAGE(PG8_SA(1, 1), a1 + hstep, voffA);
;             PG8_WAIT_L(8); PG8_BAR; PG8_WAIT_L(0); PG8_MMA(0, 0, At, B0); PG8_BAR; PG8_SCHED;
;             PG8_LDB(B1, 0, 1); PG8_STAGE(PG8_SB(0, 0), b2, voffB);
;             PG8_BAR; PG8_WAIT_L(0); PG8_MMA(0, 1, At, B1); PG8_BAR;
;             PG8_LDA(At, 0, 1); PG8_STAGE(PG8_SA(0, 0), a2, voffA);
;             PG8_BAR; PG8_WAIT_L(0); PG8_MMA(1, 0, At, B0); PG8_BAR; PG8_SCHED;
.LBB0_1377:
	s_andn2_b64 vcc, exec, s[14:15]
	s_cbranch_vccnz .LBB0_1370
	s_add_u32 s36, s36, 0x80
	s_addc_u32 s37, s37, 0
	s_add_u32 s44, s44, 0x100
	s_addc_u32 s45, s45, 0
	s_mov_b32 s4, 0
	s_add_i32 s5, s4, 2
	s_add_u32 s40, s36, 0x80
	s_addc_u32 s41, s37, 0
	s_add_i32 s79, s60, 0x100
	v_add_u32_e32 v149, s79, v140
	ds_read_b128 v[150:153], v149
	ds_read_b128 v[154:157], v149 offset:1024
	ds_read_b128 v[158:161], v149 offset:2048
	ds_read_b128 v[170:173], v149 offset:3072
	s_cmp_eq_u32 s87, s4
	s_cselect_b32 s41, s17, s41
	s_cselect_b32 s40, s16, s40
	s_cselect_b32 s43, s19, s45
	s_cselect_b32 s42, s18, s44
	v_lshl_add_u64 v[162:163], s[36:37], 0, v[134:135]
	s_add_i32 m0, s58, 0xc000
	ds_read_b128 v[174:177], v141
	ds_read_b128 v[178:181], v141 offset:1024
	ds_read_b128 v[188:191], v141 offset:2048
	ds_read_b128 v[192:195], v141 offset:3072
	ds_read_b128 v[196:199], v141 offset:4096
	ds_read_b128 v[200:203], v141 offset:5120
	ds_read_b128 v[204:207], v141 offset:6144
	ds_read_b128 v[208:211], v141 offset:7168
	global_load_lds_dwordx4 v[162:163], off
	v_lshl_add_u64 v[162:163], s[36:37], 0, v[136:137]
	s_add_i32 m0, s58, 0xe000
	s_nop 0
	global_load_lds_dwordx4 v[162:163], off
	s_waitcnt lgkmcnt(8)
	s_barrier
	s_waitcnt lgkmcnt(0)
	s_setprio 1
	s_waitcnt lgkmcnt(0)
	v_mfma_f32_16x16x32_bf16 v[120:123], v[150:153], v[174:177], 0
	v_mfma_f32_16x16x32_bf16 v[124:127], v[158:161], v[174:177], 0
	v_mfma_f32_16x16x32_bf16 v[108:111], v[150:153], v[188:191], 0
	v_mfma_f32_16x16x32_bf16 v[104:107], v[158:161], v[188:191], 0
	v_mfma_f32_16x16x32_bf16 v[92:95], v[150:153], v[196:199], 0
	v_mfma_f32_16x16x32_bf16 v[88:91], v[158:161], v[196:199], 0
	v_mfma_f32_16x16x32_bf16 v[76:79], v[150:153], v[204:207], 0
	v_mfma_f32_16x16x32_bf16 v[72:75], v[158:161], v[204:207], 0
	v_mfma_f32_16x16x32_bf16 v[120:123], v[154:157], v[178:181], v[120:123]
	v_mfma_f32_16x16x32_bf16 v[124:127], v[170:173], v[178:181], v[124:127]
	v_mfma_f32_16x16x32_bf16 v[108:111], v[154:157], v[192:195], v[108:111]
	v_mfma_f32_16x16x32_bf16 v[104:107], v[170:173], v[192:195], v[104:107]
	v_mfma_f32_16x16x32_bf16 v[92:95], v[154:157], v[200:203], v[92:95]
	v_mfma_f32_16x16x32_bf16 v[88:91], v[170:173], v[200:203], v[88:91]
	v_mfma_f32_16x16x32_bf16 v[76:79], v[154:157], v[208:211], v[76:79]
	v_mfma_f32_16x16x32_bf16 v[72:75], v[170:173], v[208:211], v[72:75]
	s_setprio 0
	s_barrier
	s_add_i32 s4, s61, 0x100
	s_add_i32 s79, s79, s50
	v_add_u32_e32 v149, s4, v140
	v_lshl_add_u64 v[162:163], s[42:43], 0, v[166:167]
	s_mov_b32 m0, s79
	ds_read_b128 v[212:215], v149
	ds_read_b128 v[216:219], v149 offset:1024
	ds_read_b128 v[220:223], v149 offset:2048
	ds_read_b128 v[224:227], v149 offset:3072
	global_load_lds_dwordx4 v[162:163], off
	v_lshl_add_u64 v[182:183], s[42:43], 0, v[128:129]
	s_add_i32 m0, s79, 0x2000
	s_nop 0
	global_load_lds_dwordx4 v[182:183], off
	s_barrier
	s_waitcnt lgkmcnt(0)
	s_setprio 1
	s_waitcnt lgkmcnt(0)
	v_mfma_f32_16x16x32_bf16 v[116:119], v[212:215], v[174:177], 0
	v_mfma_f32_16x16x32_bf16 v[112:115], v[220:223], v[174:177], 0
	v_mfma_f32_16x16x32_bf16 v[100:103], v[212:215], v[188:191], 0
	v_mfma_f32_16x16x32_bf16 v[96:99], v[220:223], v[188:191], 0
	v_mfma_f32_16x16x32_bf16 v[84:87], v[212:215], v[196:199], 0
	v_mfma_f32_16x16x32_bf16 v[80:83], v[220:223], v[196:199], 0
	v_mfma_f32_16x16x32_bf16 v[68:71], v[212:215], v[204:207], 0
	v_mfma_f32_16x16x32_bf16 v[64:67], v[220:223], v[204:207], 0
	v_mfma_f32_16x16x32_bf16 v[116:119], v[216:219], v[178:181], v[116:119]
	v_mfma_f32_16x16x32_bf16 v[112:115], v[224:227], v[178:181], v[112:115]
	v_mfma_f32_16x16x32_bf16 v[100:103], v[216:219], v[192:195], v[100:103]
	v_mfma_f32_16x16x32_bf16 v[96:99], v[224:227], v[192:195], v[96:99]
	v_mfma_f32_16x16x32_bf16 v[84:87], v[216:219], v[200:203], v[84:87]
	v_mfma_f32_16x16x32_bf16 v[80:83], v[224:227], v[200:203], v[80:83]
	v_mfma_f32_16x16x32_bf16 v[68:71], v[216:219], v[208:211], v[68:71]
	v_mfma_f32_16x16x32_bf16 v[64:67], v[224:227], v[208:211], v[64:67]
	s_setprio 0
	s_mov_b32 m0, s58
	v_lshl_add_u64 v[228:229], s[40:41], 0, v[132:133]
	s_barrier
	ds_read_b128 v[174:177], v141 offset:16384
	ds_read_b128 v[178:181], v141 offset:17408
	ds_read_b128 v[188:191], v141 offset:18432
	ds_read_b128 v[192:195], v141 offset:19456
	ds_read_b128 v[196:199], v141 offset:20480
	ds_read_b128 v[200:203], v141 offset:21504
	ds_read_b128 v[204:207], v141 offset:22528
	ds_read_b128 v[208:211], v141 offset:23552
	global_load_lds_dwordx4 v[228:229], off
	v_lshl_add_u64 v[230:231], s[40:41], 0, v[130:131]
	s_mov_b32 m0, s59
	s_nop 0
	global_load_lds_dwordx4 v[230:231], off
	s_barrier
	s_waitcnt lgkmcnt(0)
	s_setprio 1
	s_waitcnt lgkmcnt(0)
	v_mfma_f32_16x16x32_bf16 v[60:63], v[150:153], v[174:177], 0
	v_mfma_f32_16x16x32_bf16 v[56:59], v[158:161], v[174:177], 0
	v_mfma_f32_16x16x32_bf16 v[44:47], v[150:153], v[188:191], 0
	v_mfma_f32_16x16x32_bf16 v[40:43], v[158:161], v[188:191], 0
	v_mfma_f32_16x16x32_bf16 v[28:31], v[150:153], v[196:199], 0
	v_mfma_f32_16x16x32_bf16 v[24:27], v[158:161], v[196:199], 0
	v_mfma_f32_16x16x32_bf16 v[12:15], v[150:153], v[204:207], 0
	v_mfma_f32_16x16x32_bf16 v[8:11], v[158:161], v[204:207], 0
	v_mfma_f32_16x16x32_bf16 v[60:63], v[154:157], v[178:181], v[60:63]
	v_mfma_f32_16x16x32_bf16 v[56:59], v[170:173], v[178:181], v[56:59]
	v_mfma_f32_16x16x32_bf16 v[44:47], v[154:157], v[192:195], v[44:47]
	v_mfma_f32_16x16x32_bf16 v[40:43], v[170:173], v[192:195], v[40:43]
	v_mfma_f32_16x16x32_bf16 v[28:31], v[154:157], v[200:203], v[28:31]
	v_mfma_f32_16x16x32_bf16 v[24:27], v[170:173], v[200:203], v[24:27]
	v_mfma_f32_16x16x32_bf16 v[12:15], v[154:157], v[208:211], v[12:15]
	v_mfma_f32_16x16x32_bf16 v[8:11], v[170:173], v[208:211], v[8:11]
	s_setprio 0
	s_barrier
; #define PG8_STAGE(bufoff, gbase, voff) do { _Pragma("unroll") for (int _i = 0; _i < 2; ++_i) \
;         __builtin_amdgcn_global_load_lds((const unsigned*)((const char*)(gbase) + (voff)[_i]), (LAS unsigned*)(lds + (bufoff) + ldsw + _i * 8192), 16, 0, 0); } while (0)
; #define PG8_LDA(dst, b, h) do { _Pragma("unroll") for (int m = 0; m < 4; ++m) _Pragma("unroll") for (int k = 0; k < 2; ++k) dst[m][k] = *(const LAS bf16x8*)(lds + PG8_SA(b, h) + aoff + m * 2048 + k * 1024); } while (0)
; #define PG8_LDB(dst, b, h) do { _Pragma("unroll") for (int n = 0; n < 2; ++n) _Pragma("unroll") for (int k = 0; k < 2; ++k) dst[n][k] = *(const LAS bf16x8*)(lds + PG8_SB(b, h) + boff + n * 2048 + k * 1024); } while (0)
; #define PG8_MMA(ai, bj, At, Bt) do { __builtin_amdgcn_s_setprio(1); _Pragma("unroll") for (int m = 0; m < 4; ++m) _Pragma("unroll") for (int n = 0; n < 2; ++n) _Pragma("unroll") for (int k = 0; k < 2; ++k) \
;         acc[ai][bj][m][n] = __builtin_amdgcn_mfma_f32_16x16x32_bf16(Bt[n][k], At[m][k], acc[ai][bj][m][n], 0, 0, 0); __builtin_amdgcn_s_setprio(0); } while (0)
; #define PG8_WAIT_V(n) asm volatile("s_waitcnt vmcnt(" #n ")" ::: "memory")
; #define PG8_WAIT_L(n) asm volatile("s_waitcnt lgkmcnt(" #n ")" ::: "memory")
; #define PG8_BAR __builtin_amdgcn_s_barrier()
; #define PG8_SCHED __builtin_amdgcn_sched_barrier(0)
; template <class Epi>
; DI void gemm_phase(LAS unsigned char* lds, const Gemm g, const StaticOrder& S, const Epi& E) {
;     ...
;             PG8_STAGE(PG8_SB(0, 1), b2 + hstep, voffB);
;             PG8_WAIT_V(6); PG8_BAR; PG8_MMA(1, 1, At, B1); PG8_BAR;
;             PG8_LDB(B0, 1, 0); PG8_SCHED; PG8_LDA(At, 1, 0); PG8_STAGE(PG8_SA(0, 1), a2 + hstep, voffA);
;             PG8_WAIT_L(8); PG8_BAR; PG8_WAIT_L(0); PG8_MMA(0, 0, At, B0); PG8_BAR; PG8_SCHED;
;             PG8_LDB(B1, 1, 1); PG8_STAGE(PG8_SB(1, 0), b3, voffB);
;             PG8_BAR; PG8_WAIT_L(0); PG8_MMA(0, 1, At, B1); PG8_BAR;
;             PG8_LDA(At, 1, 1); PG8_STAGE(PG8_SA(1, 0), a3, voffA);
	s_add_u32 s42, s42, s10
	s_addc_u32 s43, s43, s11
	s_add_i32 s4, s4, s50
	v_lshl_add_u64 v[232:233], s[42:43], 0, v[166:167]
	s_mov_b32 m0, s4
	v_lshl_add_u64 v[234:235], s[42:43], 0, v[128:129]
	global_load_lds_dwordx4 v[232:233], off
	s_add_i32 m0, s4, 0x2000
	s_nop 0
	global_load_lds_dwordx4 v[234:235], off
	s_waitcnt vmcnt(6)
	s_barrier
	s_setprio 1
	v_mfma_f32_16x16x32_bf16 v[52:55], v[212:215], v[174:177], 0
	v_mfma_f32_16x16x32_bf16 v[48:51], v[220:223], v[174:177], 0
	v_mfma_f32_16x16x32_bf16 v[36:39], v[212:215], v[188:191], 0
	v_mfma_f32_16x16x32_bf16 v[32:35], v[220:223], v[188:191], 0
	v_mfma_f32_16x16x32_bf16 v[20:23], v[212:215], v[196:199], 0
	v_mfma_f32_16x16x32_bf16 v[16:19], v[220:223], v[196:199], 0
	v_mfma_f32_16x16x32_bf16 v[4:7], v[212:215], v[204:207], 0
	v_mfma_f32_16x16x32_bf16 v[0:3], v[220:223], v[204:207], 0
	v_mfma_f32_16x16x32_bf16 v[52:55], v[216:219], v[178:181], v[52:55]
	v_mfma_f32_16x16x32_bf16 v[48:51], v[224:227], v[178:181], v[48:51]
	v_mfma_f32_16x16x32_bf16 v[36:39], v[216:219], v[192:195], v[36:39]
	v_mfma_f32_16x16x32_bf16 v[32:35], v[224:227], v[192:195], v[32:35]
	v_mfma_f32_16x16x32_bf16 v[20:23], v[216:219], v[200:203], v[20:23]
	v_mfma_f32_16x16x32_bf16 v[16:19], v[224:227], v[200:203], v[16:19]
	v_mfma_f32_16x16x32_bf16 v[4:7], v[216:219], v[208:211], v[4:7]
	v_mfma_f32_16x16x32_bf16 v[0:3], v[224:227], v[208:211], v[0:3]
	s_setprio 0
	s_add_i32 s4, s62, 0x100
	v_add_u32_e32 v149, s4, v140
	s_barrier
	ds_read_b128 v[150:153], v149
	ds_read_b128 v[154:157], v149 offset:1024
	ds_read_b128 v[158:161], v149 offset:2048
	ds_read_b128 v[170:173], v149 offset:3072
	s_add_u32 s40, s40, s10
	s_addc_u32 s41, s41, s11
	s_mov_b32 m0, s76
	v_lshl_add_u64 v[212:213], s[40:41], 0, v[132:133]
	ds_read_b128 v[174:177], v141 offset:32768
	ds_read_b128 v[178:181], v141 offset:33792
	ds_read_b128 v[188:191], v141 offset:34816
	ds_read_b128 v[192:195], v141 offset:35840
	ds_read_b128 v[196:199], v141 offset:36864
	ds_read_b128 v[200:203], v141 offset:37888
	ds_read_b128 v[204:207], v141 offset:38912
	ds_read_b128 v[208:211], v141 offset:39936
	global_load_lds_dwordx4 v[212:213], off
	v_lshl_add_u64 v[212:213], s[40:41], 0, v[130:131]
	s_mov_b32 m0, s77
	s_nop 0
	global_load_lds_dwordx4 v[212:213], off
	s_waitcnt lgkmcnt(8)
	s_barrier
	s_waitcnt lgkmcnt(0)
	s_setprio 1
	s_waitcnt lgkmcnt(0)
	v_mfma_f32_16x16x32_bf16 v[120:123], v[150:153], v[174:177], v[120:123]
	v_mfma_f32_16x16x32_bf16 v[124:127], v[158:161], v[174:177], v[124:127]
	v_mfma_f32_16x16x32_bf16 v[108:111], v[150:153], v[188:191], v[108:111]
	v_mfma_f32_16x16x32_bf16 v[104:107], v[158:161], v[188:191], v[104:107]
	v_mfma_f32_16x16x32_bf16 v[92:95], v[150:153], v[196:199], v[92:95]
	v_mfma_f32_16x16x32_bf16 v[88:91], v[158:161], v[196:199], v[88:91]
	v_mfma_f32_16x16x32_bf16 v[76:79], v[150:153], v[204:207], v[76:79]
	v_mfma_f32_16x16x32_bf16 v[72:75], v[158:161], v[204:207], v[72:75]
	v_mfma_f32_16x16x32_bf16 v[120:123], v[154:157], v[178:181], v[120:123]
	v_mfma_f32_16x16x32_bf16 v[124:127], v[170:173], v[178:181], v[124:127]
	v_mfma_f32_16x16x32_bf16 v[108:111], v[154:157], v[192:195], v[108:111]
	v_mfma_f32_16x16x32_bf16 v[104:107], v[170:173], v[192:195], v[104:107]
	v_mfma_f32_16x16x32_bf16 v[92:95], v[154:157], v[200:203], v[92:95]
	v_mfma_f32_16x16x32_bf16 v[88:91], v[170:173], v[200:203], v[88:91]
	v_mfma_f32_16x16x32_bf16 v[76:79], v[154:157], v[208:211], v[76:79]
	v_mfma_f32_16x16x32_bf16 v[72:75], v[170:173], v[208:211], v[72:75]
	s_setprio 0
	s_barrier
	s_add_i32 s40, s63, 0x100
	s_add_i32 s4, s4, s50
	v_add_u32_e32 v149, s40, v140
	v_lshl_add_u64 v[162:163], v[162:163], 0, s[66:67]
	s_mov_b32 m0, s4
	ds_read_b128 v[212:215], v149
	ds_read_b128 v[216:219], v149 offset:1024
	ds_read_b128 v[220:223], v149 offset:2048
	ds_read_b128 v[224:227], v149 offset:3072
	global_load_lds_dwordx4 v[162:163], off
	v_lshl_add_u64 v[162:163], v[182:183], 0, s[66:67]
	s_add_i32 m0, s4, 0x2000
	s_nop 0
	global_load_lds_dwordx4 v[162:163], off
	s_barrier
	s_waitcnt lgkmcnt(0)
	s_setprio 1
	s_waitcnt lgkmcnt(0)
	v_mfma_f32_16x16x32_bf16 v[116:119], v[212:215], v[174:177], v[116:119]
	v_mfma_f32_16x16x32_bf16 v[112:115], v[220:223], v[174:177], v[112:115]
	v_mfma_f32_16x16x32_bf16 v[100:103], v[212:215], v[188:191], v[100:103]
	v_mfma_f32_16x16x32_bf16 v[96:99], v[220:223], v[188:191], v[96:99]
	v_mfma_f32_16x16x32_bf16 v[84:87], v[212:215], v[196:199], v[84:87]
	v_mfma_f32_16x16x32_bf16 v[80:83], v[220:223], v[196:199], v[80:83]
	v_mfma_f32_16x16x32_bf16 v[68:71], v[212:215], v[204:207], v[68:71]
	v_mfma_f32_16x16x32_bf16 v[64:67], v[220:223], v[204:207], v[64:67]
	v_mfma_f32_16x16x32_bf16 v[116:119], v[216:219], v[178:181], v[116:119]
	v_mfma_f32_16x16x32_bf16 v[112:115], v[224:227], v[178:181], v[112:115]
	v_mfma_f32_16x16x32_bf16 v[100:103], v[216:219], v[192:195], v[100:103]
	v_mfma_f32_16x16x32_bf16 v[96:99], v[224:227], v[192:195], v[96:99]
	v_mfma_f32_16x16x32_bf16 v[84:87], v[216:219], v[200:203], v[84:87]
	v_mfma_f32_16x16x32_bf16 v[80:83], v[224:227], v[200:203], v[80:83]
	v_mfma_f32_16x16x32_bf16 v[68:71], v[216:219], v[208:211], v[68:71]
	v_mfma_f32_16x16x32_bf16 v[64:67], v[224:227], v[208:211], v[64:67]
	s_setprio 0
	s_mov_b32 m0, s80
	v_lshl_add_u64 v[162:163], v[228:229], 0, s[66:67]
	s_barrier
	ds_read_b128 v[174:177], v141 offset:49152
	ds_read_b128 v[178:181], v141 offset:50176
	ds_read_b128 v[188:191], v141 offset:51200
	ds_read_b128 v[192:195], v141 offset:52224
	ds_read_b128 v[196:199], v141 offset:53248
	ds_read_b128 v[200:203], v141 offset:54272
	ds_read_b128 v[204:207], v141 offset:55296
	ds_read_b128 v[208:211], v141 offset:56320
	global_load_lds_dwordx4 v[162:163], off
	v_lshl_add_u64 v[162:163], v[230:231], 0, s[66:67]
	s_mov_b32 m0, s81
	s_nop 0
	global_load_lds_dwordx4 v[162:163], off
	s_barrier
; #define PG8_STAGE(bufoff, gbase, voff) do { _Pragma("unroll") for (int _i = 0; _i < 2; ++_i) \
;         __builtin_amdgcn_global_load_lds((const unsigned*)((const char*)(gbase) + (voff)[_i]), (LAS unsigned*)(lds + (bufoff) + ldsw + _i * 8192), 16, 0, 0); } while (0)
; #define PG8_LDA(dst, b, h) do { _Pragma("unroll") for (int m = 0; m < 4; ++m) _Pragma("unroll") for (int k = 0; k < 2; ++k) dst[m][k] = *(const LAS bf16x8*)(lds + PG8_SA(b, h) + aoff + m * 2048 + k * 1024); } while (0)
; #define PG8_LDB(dst, b, h) do { _Pragma("unroll") for (int n = 0; n < 2; ++n) _Pragma("unroll") for (int k = 0; k < 2; ++k) dst[n][k] = *(const LAS bf16x8*)(lds + PG8_SB(b, h) + boff + n * 2048 + k * 1024); } while (0)
; #define PG8_MMA(ai, bj, At, Bt) do { __builtin_amdgcn_s_setprio(1); _Pragma("unroll") for (int m = 0; m < 4; ++m) _Pragma("unroll") for (int n = 0; n < 2; ++n) _Pragma("unroll") for (int k = 0; k < 2; ++k) \
;         acc[ai][bj][m][n] = __builtin_amdgcn_mfma_f32_16x16x32_bf16(Bt[n][k], At[m][k], acc[ai][bj][m][n], 0, 0, 0); __builtin_amdgcn_s_setprio(0); } while (0)
; #define PG8_WAIT_V(n) asm volatile("s_waitcnt vmcnt(" #n ")" ::: "memory")
; #define PG8_WAIT_L(n) asm volatile("s_waitcnt lgkmcnt(" #n ")" ::: "memory")
; #define PG8_BAR __builtin_amdgcn_s_barrier()
; #define PG8_SCHED __builtin_amdgcn_sched_barrier(0)
; template <class Epi>
; DI void gemm_phase(LAS unsigned char* lds, const Gemm g, const StaticOrder& S, const Epi& E) {
;     ...
;             PG8_LDB(B0, 0, 0); PG8_SCHED; PG8_LDA(At, 0, 0); PG8_STAGE(PG8_SA(1, 1), a1 + hstep, voffA);
;             PG8_WAIT_L(8); PG8_BAR; PG8_WAIT_L(0); PG8_MMA(0, 0, At, B0); PG8_BAR; PG8_SCHED;
;             PG8_LDB(B1, 0, 1); PG8_STAGE(PG8_SB(0, 0), b2, voffB);
;     ...
;             PG8_BAR; PG8_WAIT_L(0); PG8_MMA(1, 0, At, B0); PG8_BAR; PG8_SCHED;
;             PG8_STAGE(PG8_SB(1, 1), b3 + hstep, voffB);
;             PG8_WAIT_V(6); PG8_BAR; PG8_MMA(1, 1, At, B1); PG8_BAR;
	s_waitcnt lgkmcnt(0)
	s_setprio 1
	s_waitcnt lgkmcnt(0)
	v_mfma_f32_16x16x32_bf16 v[60:63], v[150:153], v[174:177], v[60:63]
	v_mfma_f32_16x16x32_bf16 v[56:59], v[158:161], v[174:177], v[56:59]
	v_mfma_f32_16x16x32_bf16 v[44:47], v[150:153], v[188:191], v[44:47]
	v_mfma_f32_16x16x32_bf16 v[40:43], v[158:161], v[188:191], v[40:43]
	v_mfma_f32_16x16x32_bf16 v[28:31], v[150:153], v[196:199], v[28:31]
	v_mfma_f32_16x16x32_bf16 v[24:27], v[158:161], v[196:199], v[24:27]
	v_mfma_f32_16x16x32_bf16 v[12:15], v[150:153], v[204:207], v[12:15]
	v_mfma_f32_16x16x32_bf16 v[8:11], v[158:161], v[204:207], v[8:11]
	v_mfma_f32_16x16x32_bf16 v[60:63], v[154:157], v[178:181], v[60:63]
	v_mfma_f32_16x16x32_bf16 v[56:59], v[170:173], v[178:181], v[56:59]
	v_mfma_f32_16x16x32_bf16 v[44:47], v[154:157], v[192:195], v[44:47]
	v_mfma_f32_16x16x32_bf16 v[40:43], v[170:173], v[192:195], v[40:43]
	v_mfma_f32_16x16x32_bf16 v[28:31], v[154:157], v[200:203], v[28:31]
	v_mfma_f32_16x16x32_bf16 v[24:27], v[170:173], v[200:203], v[24:27]
	v_mfma_f32_16x16x32_bf16 v[12:15], v[154:157], v[208:211], v[12:15]
	v_mfma_f32_16x16x32_bf16 v[8:11], v[170:173], v[208:211], v[8:11]
	s_setprio 0
	s_barrier
	s_add_i32 s4, s40, s50
	v_lshl_add_u64 v[150:151], v[232:233], 0, s[66:67]
	s_mov_b32 m0, s4
	s_nop 0
	global_load_lds_dwordx4 v[150:151], off
	v_lshl_add_u64 v[150:151], v[234:235], 0, s[66:67]
	s_add_i32 m0, s4, 0x2000
	s_nop 0
	global_load_lds_dwordx4 v[150:151], off
	s_waitcnt vmcnt(6)
	s_barrier
	s_setprio 1
	v_mfma_f32_16x16x32_bf16 v[52:55], v[212:215], v[174:177], v[52:55]
	v_mfma_f32_16x16x32_bf16 v[48:51], v[220:223], v[174:177], v[48:51]
	v_mfma_f32_16x16x32_bf16 v[36:39], v[212:215], v[188:191], v[36:39]
	v_mfma_f32_16x16x32_bf16 v[32:35], v[220:223], v[188:191], v[32:35]
	v_mfma_f32_16x16x32_bf16 v[20:23], v[212:215], v[196:199], v[20:23]
	v_mfma_f32_16x16x32_bf16 v[16:19], v[220:223], v[196:199], v[16:19]
	v_mfma_f32_16x16x32_bf16 v[4:7], v[212:215], v[204:207], v[4:7]
	v_mfma_f32_16x16x32_bf16 v[0:3], v[220:223], v[204:207], v[0:3]
	v_mfma_f32_16x16x32_bf16 v[52:55], v[216:219], v[178:181], v[52:55]
	v_mfma_f32_16x16x32_bf16 v[48:51], v[224:227], v[178:181], v[48:51]
	v_mfma_f32_16x16x32_bf16 v[36:39], v[216:219], v[192:195], v[36:39]
	v_mfma_f32_16x16x32_bf16 v[32:35], v[224:227], v[192:195], v[32:35]
	v_mfma_f32_16x16x32_bf16 v[20:23], v[216:219], v[200:203], v[20:23]
	v_mfma_f32_16x16x32_bf16 v[16:19], v[224:227], v[200:203], v[16:19]
	v_mfma_f32_16x16x32_bf16 v[4:7], v[216:219], v[208:211], v[4:7]
	v_mfma_f32_16x16x32_bf16 v[0:3], v[224:227], v[208:211], v[0:3]
	s_setprio 0
	s_add_u32 s36, s36, 0x100
	s_addc_u32 s37, s37, 0
	s_add_u32 s44, s44, 0x100
	s_addc_u32 s45, s45, 0
	s_cmp_ge_i32 s5, s84
	s_mov_b32 s4, s5
	s_barrier
	s_cbranch_scc0 .LBB0_1379
	s_branch .Lpeel_exit_3
.LBB0_1379:
	s_add_i32 s5, s4, 2
	s_add_u32 s40, s36, 0x80
	s_addc_u32 s41, s37, 0
	s_add_i32 s79, s60, 0x100
	v_add_u32_e32 v149, s79, v140
	ds_read_b128 v[150:153], v149
	ds_read_b128 v[154:157], v149 offset:1024
	ds_read_b128 v[158:161], v149 offset:2048
	ds_read_b128 v[170:173], v149 offset:3072
	s_cmp_eq_u32 s87, s4
	s_cselect_b32 s41, s17, s41
	s_cselect_b32 s40, s16, s40
	s_cselect_b32 s43, s19, s45
	s_cselect_b32 s42, s18, s44
	v_lshl_add_u64 v[162:163], s[36:37], 0, v[134:135]
	s_add_i32 m0, s58, 0xc000
	ds_read_b128 v[174:177], v141
	ds_read_b128 v[178:181], v141 offset:1024
	ds_read_b128 v[188:191], v141 offset:2048
	ds_read_b128 v[192:195], v141 offset:3072
	ds_read_b128 v[196:199], v141 offset:4096
	ds_read_b128 v[200:203], v141 offset:5120
	ds_read_b128 v[204:207], v141 offset:6144
	ds_read_b128 v[208:211], v141 offset:7168
	global_load_lds_dwordx4 v[162:163], off
	v_lshl_add_u64 v[162:163], s[36:37], 0, v[136:137]
	s_add_i32 m0, s58, 0xe000
	s_nop 0
	global_load_lds_dwordx4 v[162:163], off
	s_waitcnt lgkmcnt(8)
	s_barrier
	s_waitcnt lgkmcnt(0)
	s_setprio 1
	s_waitcnt lgkmcnt(0)
	v_mfma_f32_16x16x32_bf16 v[120:123], v[150:153], v[174:177], v[120:123]
	v_mfma_f32_16x16x32_bf16 v[124:127], v[158:161], v[174:177], v[124:127]
	v_mfma_f32_16x16x32_bf16 v[108:111], v[150:153], v[188:191], v[108:111]
	v_mfma_f32_16x16x32_bf16 v[104:107], v[158:161], v[188:191], v[104:107]
	v_mfma_f32_16x16x32_bf16 v[92:95], v[150:153], v[196:199], v[92:95]
	v_mfma_f32_16x16x32_bf16 v[88:91], v[158:161], v[196:199], v[88:91]
	v_mfma_f32_16x16x32_bf16 v[76:79], v[150:153], v[204:207], v[76:79]
	v_mfma_f32_16x16x32_bf16 v[72:75], v[158:161], v[204:207], v[72:75]
	v_mfma_f32_16x16x32_bf16 v[120:123], v[154:157], v[178:181], v[120:123]
	v_mfma_f32_16x16x32_bf16 v[124:127], v[170:173], v[178:181], v[124:127]
	v_mfma_f32_16x16x32_bf16 v[108:111], v[154:157], v[192:195], v[108:111]
	v_mfma_f32_16x16x32_bf16 v[104:107], v[170:173], v[192:195], v[104:107]
	v_mfma_f32_16x16x32_bf16 v[92:95], v[154:157], v[200:203], v[92:95]
	v_mfma_f32_16x16x32_bf16 v[88:91], v[170:173], v[200:203], v[88:91]
	v_mfma_f32_16x16x32_bf16 v[76:79], v[154:157], v[208:211], v[76:79]
	v_mfma_f32_16x16x32_bf16 v[72:75], v[170:173], v[208:211], v[72:75]
	s_setprio 0
	s_barrier
	s_add_i32 s4, s61, 0x100
	s_add_i32 s79, s79, s50
	v_add_u32_e32 v149, s4, v140
	v_lshl_add_u64 v[162:163], s[42:43], 0, v[166:167]
	s_mov_b32 m0, s79
	ds_read_b128 v[212:215], v149
	ds_read_b128 v[216:219], v149 offset:1024
	ds_read_b128 v[220:223], v149 offset:2048
	ds_read_b128 v[224:227], v149 offset:3072
	global_load_lds_dwordx4 v[162:163], off
	v_lshl_add_u64 v[182:183], s[42:43], 0, v[128:129]
	s_add_i32 m0, s79, 0x2000
	s_nop 0
	global_load_lds_dwordx4 v[182:183], off
	s_barrier
; #define PG8_STAGE(bufoff, gbase, voff) do { _Pragma("unroll") for (int _i = 0; _i < 2; ++_i) \
;         __builtin_amdgcn_global_load_lds((const unsigned*)((const char*)(gbase) + (voff)[_i]), (LAS unsigned*)(lds + (bufoff) + ldsw + _i * 8192), 16, 0, 0); } while (0)
; #define PG8_LDA(dst, b, h) do { _Pragma("unroll") for (int m = 0; m < 4; ++m) _Pragma("unroll") for (int k = 0; k < 2; ++k) dst[m][k] = *(const LAS bf16x8*)(lds + PG8_SA(b, h) + aoff + m * 2048 + k * 1024); } while (0)
; #define PG8_LDB(dst, b, h) do { _Pragma("unroll") for (int n = 0; n < 2; ++n) _Pragma("unroll") for (int k = 0; k < 2; ++k) dst[n][k] = *(const LAS bf16x8*)(lds + PG8_SB(b, h) + boff + n * 2048 + k * 1024); } while (0)
; #define PG8_MMA(ai, bj, At, Bt) do { __builtin_amdgcn_s_setprio(1); _Pragma("unroll") for (int m = 0; m < 4; ++m) _Pragma("unroll") for (int n = 0; n < 2; ++n) _Pragma("unroll") for (int k = 0; k < 2; ++k) \
;         acc[ai][bj][m][n] = __builtin_amdgcn_mfma_f32_16x16x32_bf16(Bt[n][k], At[m][k], acc[ai][bj][m][n], 0, 0, 0); __builtin_amdgcn_s_setprio(0); } while (0)
; #define PG8_WAIT_V(n) asm volatile("s_waitcnt vmcnt(" #n ")" ::: "memory")
; #define PG8_WAIT_L(n) asm volatile("s_waitcnt lgkmcnt(" #n ")" ::: "memory")
; #define PG8_BAR __builtin_amdgcn_s_barrier()
; #define PG8_SCHED __builtin_amdgcn_sched_barrier(0)
; template <class Epi>
; DI void gemm_phase(LAS unsigned char* lds, const Gemm g, const StaticOrder& S, const Epi& E) {
;     ...
;             PG8_BAR; PG8_WAIT_L(0); PG8_MMA(0, 1, At, B1); PG8_BAR;
;             PG8_LDA(At, 0, 1); PG8_STAGE(PG8_SA(0, 0), a2, voffA);
;             PG8_BAR; PG8_WAIT_L(0); PG8_MMA(1, 0, At, B0); PG8_BAR; PG8_SCHED;
;             PG8_STAGE(PG8_SB(0, 1), b2 + hstep, voffB);
;             PG8_WAIT_V(6); PG8_BAR; PG8_MMA(1, 1, At, B1); PG8_BAR;
;             PG8_LDB(B0, 1, 0); PG8_SCHED; PG8_LDA(At, 1, 0); PG8_STAGE(PG8_SA(0, 1), a2 + hstep, voffA);
;             PG8_WAIT_L(8); PG8_BAR; PG8_WAIT_L(0); PG8_MMA(0, 0, At, B0); PG8_BAR; PG8_SCHED;
	s_waitcnt lgkmcnt(0)
	s_setprio 1
	s_waitcnt lgkmcnt(0)
	v_mfma_f32_16x16x32_bf16 v[116:119], v[212:215], v[174:177], v[116:119]
	v_mfma_f32_16x16x32_bf16 v[112:115], v[220:223], v[174:177], v[112:115]
	v_mfma_f32_16x16x32_bf16 v[100:103], v[212:215], v[188:191], v[100:103]
	v_mfma_f32_16x16x32_bf16 v[96:99], v[220:223], v[188:191], v[96:99]
	v_mfma_f32_16x16x32_bf16 v[84:87], v[212:215], v[196:199], v[84:87]
	v_mfma_f32_16x16x32_bf16 v[80:83], v[220:223], v[196:199], v[80:83]
	v_mfma_f32_16x16x32_bf16 v[68:71], v[212:215], v[204:207], v[68:71]
	v_mfma_f32_16x16x32_bf16 v[64:67], v[220:223], v[204:207], v[64:67]
	v_mfma_f32_16x16x32_bf16 v[116:119], v[216:219], v[178:181], v[116:119]
	v_mfma_f32_16x16x32_bf16 v[112:115], v[224:227], v[178:181], v[112:115]
	v_mfma_f32_16x16x32_bf16 v[100:103], v[216:219], v[192:195], v[100:103]
	v_mfma_f32_16x16x32_bf16 v[96:99], v[224:227], v[192:195], v[96:99]
	v_mfma_f32_16x16x32_bf16 v[84:87], v[216:219], v[200:203], v[84:87]
	v_mfma_f32_16x16x32_bf16 v[80:83], v[224:227], v[200:203], v[80:83]
	v_mfma_f32_16x16x32_bf16 v[68:71], v[216:219], v[208:211], v[68:71]
	v_mfma_f32_16x16x32_bf16 v[64:67], v[224:227], v[208:211], v[64:67]
	s_setprio 0
	s_mov_b32 m0, s58
	v_lshl_add_u64 v[228:229], s[40:41], 0, v[132:133]
	s_barrier
	ds_read_b128 v[174:177], v141 offset:16384
	ds_read_b128 v[178:181], v141 offset:17408
	ds_read_b128 v[188:191], v141 offset:18432
	ds_read_b128 v[192:195], v141 offset:19456
	ds_read_b128 v[196:199], v141 offset:20480
	ds_read_b128 v[200:203], v141 offset:21504
	ds_read_b128 v[204:207], v141 offset:22528
	ds_read_b128 v[208:211], v141 offset:23552
	global_load_lds_dwordx4 v[228:229], off
	v_lshl_add_u64 v[230:231], s[40:41], 0, v[130:131]
	s_mov_b32 m0, s59
	s_nop 0
	global_load_lds_dwordx4 v[230:231], off
	s_barrier
	s_waitcnt lgkmcnt(0)
	s_setprio 1
	s_waitcnt lgkmcnt(0)
	v_mfma_f32_16x16x32_bf16 v[60:63], v[150:153], v[174:177], v[60:63]
	v_mfma_f32_16x16x32_bf16 v[56:59], v[158:161], v[174:177], v[56:59]
	v_mfma_f32_16x16x32_bf16 v[44:47], v[150:153], v[188:191], v[44:47]
	v_mfma_f32_16x16x32_bf16 v[40:43], v[158:161], v[188:191], v[40:43]
	v_mfma_f32_16x16x32_bf16 v[28:31], v[150:153], v[196:199], v[28:31]
	v_mfma_f32_16x16x32_bf16 v[24:27], v[158:161], v[196:199], v[24:27]
	v_mfma_f32_16x16x32_bf16 v[12:15], v[150:153], v[204:207], v[12:15]
	v_mfma_f32_16x16x32_bf16 v[8:11], v[158:161], v[204:207], v[8:11]
	v_mfma_f32_16x16x32_bf16 v[60:63], v[154:157], v[178:181], v[60:63]
	v_mfma_f32_16x16x32_bf16 v[56:59], v[170:173], v[178:181], v[56:59]
	v_mfma_f32_16x16x32_bf16 v[44:47], v[154:157], v[192:195], v[44:47]
	v_mfma_f32_16x16x32_bf16 v[40:43], v[170:173], v[192:195], v[40:43]
	v_mfma_f32_16x16x32_bf16 v[28:31], v[154:157], v[200:203], v[28:31]
	v_mfma_f32_16x16x32_bf16 v[24:27], v[170:173], v[200:203], v[24:27]
	v_mfma_f32_16x16x32_bf16 v[12:15], v[154:157], v[208:211], v[12:15]
	v_mfma_f32_16x16x32_bf16 v[8:11], v[170:173], v[208:211], v[8:11]
	s_setprio 0
	s_barrier
	s_add_u32 s42, s42, s10
	s_addc_u32 s43, s43, s11
	s_add_i32 s4, s4, s50
	v_lshl_add_u64 v[232:233], s[42:43], 0, v[166:167]
	s_mov_b32 m0, s4
	v_lshl_add_u64 v[234:235], s[42:43], 0, v[128:129]
	global_load_lds_dwordx4 v[232:233], off
	s_add_i32 m0, s4, 0x2000
	s_nop 0
	global_load_lds_dwordx4 v[234:235], off
	s_waitcnt vmcnt(6)
	s_barrier
	s_setprio 1
	v_mfma_f32_16x16x32_bf16 v[52:55], v[212:215], v[174:177], v[52:55]
	v_mfma_f32_16x16x32_bf16 v[48:51], v[220:223], v[174:177], v[48:51]
	v_mfma_f32_16x16x32_bf16 v[36:39], v[212:215], v[188:191], v[36:39]
	v_mfma_f32_16x16x32_bf16 v[32:35], v[220:223], v[188:191], v[32:35]
	v_mfma_f32_16x16x32_bf16 v[20:23], v[212:215], v[196:199], v[20:23]
	v_mfma_f32_16x16x32_bf16 v[16:19], v[220:223], v[196:199], v[16:19]
	v_mfma_f32_16x16x32_bf16 v[4:7], v[212:215], v[204:207], v[4:7]
	v_mfma_f32_16x16x32_bf16 v[0:3], v[220:223], v[204:207], v[0:3]
	v_mfma_f32_16x16x32_bf16 v[52:55], v[216:219], v[178:181], v[52:55]
	v_mfma_f32_16x16x32_bf16 v[48:51], v[224:227], v[178:181], v[48:51]
	v_mfma_f32_16x16x32_bf16 v[36:39], v[216:219], v[192:195], v[36:39]
	v_mfma_f32_16x16x32_bf16 v[32:35], v[224:227], v[192:195], v[32:35]
	v_mfma_f32_16x16x32_bf16 v[20:23], v[216:219], v[200:203], v[20:23]
	v_mfma_f32_16x16x32_bf16 v[16:19], v[224:227], v[200:203], v[16:19]
	v_mfma_f32_16x16x32_bf16 v[4:7], v[216:219], v[208:211], v[4:7]
	v_mfma_f32_16x16x32_bf16 v[0:3], v[224:227], v[208:211], v[0:3]
	s_setprio 0
	s_add_i32 s4, s62, 0x100
	v_add_u32_e32 v149, s4, v140
	s_barrier
	ds_read_b128 v[150:153], v149
	ds_read_b128 v[154:157], v149 offset:1024
	ds_read_b128 v[158:161], v149 offset:2048
	ds_read_b128 v[170:173], v149 offset:3072
	s_add_u32 s40, s40, s10
	s_addc_u32 s41, s41, s11
	s_mov_b32 m0, s76
	v_lshl_add_u64 v[212:213], s[40:41], 0, v[132:133]
	ds_read_b128 v[174:177], v141 offset:32768
	ds_read_b128 v[178:181], v141 offset:33792
	ds_read_b128 v[188:191], v141 offset:34816
	ds_read_b128 v[192:195], v141 offset:35840
	ds_read_b128 v[196:199], v141 offset:36864
	ds_read_b128 v[200:203], v141 offset:37888
	ds_read_b128 v[204:207], v141 offset:38912
	ds_read_b128 v[208:211], v141 offset:39936
	global_load_lds_dwordx4 v[212:213], off
	v_lshl_add_u64 v[212:213], s[40:41], 0, v[130:131]
	s_mov_b32 m0, s77
	s_nop 0
	global_load_lds_dwordx4 v[212:213], off
	s_waitcnt lgkmcnt(8)
	s_barrier
; #define PG8_STAGE(bufoff, gbase, voff) do { _Pragma("unroll") for (int _i = 0; _i < 2; ++_i) \
;         __builtin_amdgcn_global_load_lds((const unsigned*)((const char*)(gbase) + (voff)[_i]), (LAS unsigned*)(lds + (bufoff) + ldsw + _i * 8192), 16, 0, 0); } while (0)
; #define PG8_LDA(dst, b, h) do { _Pragma("unroll") for (int m = 0; m < 4; ++m) _Pragma("unroll") for (int k = 0; k < 2; ++k) dst[m][k] = *(const LAS bf16x8*)(lds + PG8_SA(b, h) + aoff + m * 2048 + k * 1024); } while (0)
; #define PG8_LDB(dst, b, h) do { _Pragma("unroll") for (int n = 0; n < 2; ++n) _Pragma("unroll") for (int k = 0; k < 2; ++k) dst[n][k] = *(const LAS bf16x8*)(lds + PG8_SB(b, h) + boff + n * 2048 + k * 1024); } while (0)
; #define PG8_MMA(ai, bj, At, Bt) do { __builtin_amdgcn_s_setprio(1); _Pragma("unroll") for (int m = 0; m < 4; ++m) _Pragma("unroll") for (int n = 0; n < 2; ++n) _Pragma("unroll") for (int k = 0; k < 2; ++k) \
;         acc[ai][bj][m][n] = __builtin_amdgcn_mfma_f32_16x16x32_bf16(Bt[n][k], At[m][k], acc[ai][bj][m][n], 0, 0, 0); __builtin_amdgcn_s_setprio(0); } while (0)
; #define PG8_WAIT_V(n) asm volatile("s_waitcnt vmcnt(" #n ")" ::: "memory")
; #define PG8_WAIT_L(n) asm volatile("s_waitcnt lgkmcnt(" #n ")" ::: "memory")
; #define PG8_BAR __builtin_amdgcn_s_barrier()
; #define PG8_SCHED __builtin_amdgcn_sched_barrier(0)
; template <class Epi>
; DI void gemm_phase(LAS unsigned char* lds, const Gemm g, const StaticOrder& S, const Epi& E) {
;     ...
;             PG8_WAIT_L(8); PG8_BAR; PG8_WAIT_L(0); PG8_MMA(0, 0, At, B0); PG8_BAR; PG8_SCHED;
;             PG8_LDB(B1, 1, 1); PG8_STAGE(PG8_SB(1, 0), b3, voffB);
;             PG8_BAR; PG8_WAIT_L(0); PG8_MMA(0, 1, At, B1); PG8_BAR;
;             PG8_LDA(At, 1, 1); PG8_STAGE(PG8_SA(1, 0), a3, voffA);
;             PG8_BAR; PG8_WAIT_L(0); PG8_MMA(1, 0, At, B0); PG8_BAR; PG8_SCHED;
;             PG8_STAGE(PG8_SB(1, 1), b3 + hstep, voffB);
;             PG8_WAIT_V(6); PG8_BAR; PG8_MMA(1, 1, At, B1); PG8_BAR;
;     ...
;     PG8_WAIT_V(0);
;     if (wr == 0) PG8_BAR;
	s_waitcnt lgkmcnt(0)
	s_setprio 1
	s_waitcnt lgkmcnt(0)
	v_mfma_f32_16x16x32_bf16 v[120:123], v[150:153], v[174:177], v[120:123]
	v_mfma_f32_16x16x32_bf16 v[124:127], v[158:161], v[174:177], v[124:127]
	v_mfma_f32_16x16x32_bf16 v[108:111], v[150:153], v[188:191], v[108:111]
	v_mfma_f32_16x16x32_bf16 v[104:107], v[158:161], v[188:191], v[104:107]
	v_mfma_f32_16x16x32_bf16 v[92:95], v[150:153], v[196:199], v[92:95]
	v_mfma_f32_16x16x32_bf16 v[88:91], v[158:161], v[196:199], v[88:91]
	v_mfma_f32_16x16x32_bf16 v[76:79], v[150:153], v[204:207], v[76:79]
	v_mfma_f32_16x16x32_bf16 v[72:75], v[158:161], v[204:207], v[72:75]
	v_mfma_f32_16x16x32_bf16 v[120:123], v[154:157], v[178:181], v[120:123]
	v_mfma_f32_16x16x32_bf16 v[124:127], v[170:173], v[178:181], v[124:127]
	v_mfma_f32_16x16x32_bf16 v[108:111], v[154:157], v[192:195], v[108:111]
	v_mfma_f32_16x16x32_bf16 v[104:107], v[170:173], v[192:195], v[104:107]
	v_mfma_f32_16x16x32_bf16 v[92:95], v[154:157], v[200:203], v[92:95]
	v_mfma_f32_16x16x32_bf16 v[88:91], v[170:173], v[200:203], v[88:91]
	v_mfma_f32_16x16x32_bf16 v[76:79], v[154:157], v[208:211], v[76:79]
	v_mfma_f32_16x16x32_bf16 v[72:75], v[170:173], v[208:211], v[72:75]
	s_setprio 0
	s_barrier
	s_add_i32 s40, s63, 0x100
	s_add_i32 s4, s4, s50
	v_add_u32_e32 v149, s40, v140
	v_lshl_add_u64 v[162:163], v[162:163], 0, s[66:67]
	s_mov_b32 m0, s4
	ds_read_b128 v[212:215], v149
	ds_read_b128 v[216:219], v149 offset:1024
	ds_read_b128 v[220:223], v149 offset:2048
	ds_read_b128 v[224:227], v149 offset:3072
	global_load_lds_dwordx4 v[162:163], off
	v_lshl_add_u64 v[162:163], v[182:183], 0, s[66:67]
	s_add_i32 m0, s4, 0x2000
	s_nop 0
	global_load_lds_dwordx4 v[162:163], off
	s_barrier
	s_waitcnt lgkmcnt(0)
	s_setprio 1
	s_waitcnt lgkmcnt(0)
	v_mfma_f32_16x16x32_bf16 v[116:119], v[212:215], v[174:177], v[116:119]
	v_mfma_f32_16x16x32_bf16 v[112:115], v[220:223], v[174:177], v[112:115]
	v_mfma_f32_16x16x32_bf16 v[100:103], v[212:215], v[188:191], v[100:103]
	v_mfma_f32_16x16x32_bf16 v[96:99], v[220:223], v[188:191], v[96:99]
	v_mfma_f32_16x16x32_bf16 v[84:87], v[212:215], v[196:199], v[84:87]
	v_mfma_f32_16x16x32_bf16 v[80:83], v[220:223], v[196:199], v[80:83]
	v_mfma_f32_16x16x32_bf16 v[68:71], v[212:215], v[204:207], v[68:71]
	v_mfma_f32_16x16x32_bf16 v[64:67], v[220:223], v[204:207], v[64:67]
	v_mfma_f32_16x16x32_bf16 v[116:119], v[216:219], v[178:181], v[116:119]
	v_mfma_f32_16x16x32_bf16 v[112:115], v[224:227], v[178:181], v[112:115]
	v_mfma_f32_16x16x32_bf16 v[100:103], v[216:219], v[192:195], v[100:103]
	v_mfma_f32_16x16x32_bf16 v[96:99], v[224:227], v[192:195], v[96:99]
	v_mfma_f32_16x16x32_bf16 v[84:87], v[216:219], v[200:203], v[84:87]
	v_mfma_f32_16x16x32_bf16 v[80:83], v[224:227], v[200:203], v[80:83]
	v_mfma_f32_16x16x32_bf16 v[68:71], v[216:219], v[208:211], v[68:71]
	v_mfma_f32_16x16x32_bf16 v[64:67], v[224:227], v[208:211], v[64:67]
	s_setprio 0
	s_mov_b32 m0, s80
	v_lshl_add_u64 v[162:163], v[228:229], 0, s[66:67]
	s_barrier
	ds_read_b128 v[174:177], v141 offset:49152
	ds_read_b128 v[178:181], v141 offset:50176
	ds_read_b128 v[188:191], v141 offset:51200
	ds_read_b128 v[192:195], v141 offset:52224
	ds_read_b128 v[196:199], v141 offset:53248
	ds_read_b128 v[200:203], v141 offset:54272
	ds_read_b128 v[204:207], v141 offset:55296
	ds_read_b128 v[208:211], v141 offset:56320
	global_load_lds_dwordx4 v[162:163], off
	v_lshl_add_u64 v[162:163], v[230:231], 0, s[66:67]
	s_mov_b32 m0, s81
	s_nop 0
	global_load_lds_dwordx4 v[162:163], off
	s_barrier
	s_waitcnt lgkmcnt(0)
	s_setprio 1
	s_waitcnt lgkmcnt(0)
	v_mfma_f32_16x16x32_bf16 v[60:63], v[150:153], v[174:177], v[60:63]
	v_mfma_f32_16x16x32_bf16 v[56:59], v[158:161], v[174:177], v[56:59]
	v_mfma_f32_16x16x32_bf16 v[44:47], v[150:153], v[188:191], v[44:47]
	v_mfma_f32_16x16x32_bf16 v[40:43], v[158:161], v[188:191], v[40:43]
	v_mfma_f32_16x16x32_bf16 v[28:31], v[150:153], v[196:199], v[28:31]
	v_mfma_f32_16x16x32_bf16 v[24:27], v[158:161], v[196:199], v[24:27]
	v_mfma_f32_16x16x32_bf16 v[12:15], v[150:153], v[204:207], v[12:15]
	v_mfma_f32_16x16x32_bf16 v[8:11], v[158:161], v[204:207], v[8:11]
	v_mfma_f32_16x16x32_bf16 v[60:63], v[154:157], v[178:181], v[60:63]
	v_mfma_f32_16x16x32_bf16 v[56:59], v[170:173], v[178:181], v[56:59]
	v_mfma_f32_16x16x32_bf16 v[44:47], v[154:157], v[192:195], v[44:47]
	v_mfma_f32_16x16x32_bf16 v[40:43], v[170:173], v[192:195], v[40:43]
	v_mfma_f32_16x16x32_bf16 v[28:31], v[154:157], v[200:203], v[28:31]
	v_mfma_f32_16x16x32_bf16 v[24:27], v[170:173], v[200:203], v[24:27]
	v_mfma_f32_16x16x32_bf16 v[12:15], v[154:157], v[208:211], v[12:15]
	v_mfma_f32_16x16x32_bf16 v[8:11], v[170:173], v[208:211], v[8:11]
	s_setprio 0
	s_barrier
	s_add_i32 s4, s40, s50
	v_lshl_add_u64 v[150:151], v[232:233], 0, s[66:67]
	s_mov_b32 m0, s4
	s_nop 0
	global_load_lds_dwordx4 v[150:151], off
	v_lshl_add_u64 v[150:151], v[234:235], 0, s[66:67]
	s_add_i32 m0, s4, 0x2000
	s_nop 0
	global_load_lds_dwordx4 v[150:151], off
	s_waitcnt vmcnt(6)
	s_barrier
	s_setprio 1
	v_mfma_f32_16x16x32_bf16 v[52:55], v[212:215], v[174:177], v[52:55]
	v_mfma_f32_16x16x32_bf16 v[48:51], v[220:223], v[174:177], v[48:51]
	v_mfma_f32_16x16x32_bf16 v[36:39], v[212:215], v[188:191], v[36:39]
	v_mfma_f32_16x16x32_bf16 v[32:35], v[220:223], v[188:191], v[32:35]
	v_mfma_f32_16x16x32_bf16 v[20:23], v[212:215], v[196:199], v[20:23]
	v_mfma_f32_16x16x32_bf16 v[16:19], v[220:223], v[196:199], v[16:19]
	v_mfma_f32_16x16x32_bf16 v[4:7], v[212:215], v[204:207], v[4:7]
	v_mfma_f32_16x16x32_bf16 v[0:3], v[220:223], v[204:207], v[0:3]
	v_mfma_f32_16x16x32_bf16 v[52:55], v[216:219], v[178:181], v[52:55]
	v_mfma_f32_16x16x32_bf16 v[48:51], v[224:227], v[178:181], v[48:51]
	v_mfma_f32_16x16x32_bf16 v[36:39], v[216:219], v[192:195], v[36:39]
	v_mfma_f32_16x16x32_bf16 v[32:35], v[224:227], v[192:195], v[32:35]
	v_mfma_f32_16x16x32_bf16 v[20:23], v[216:219], v[200:203], v[20:23]
	v_mfma_f32_16x16x32_bf16 v[16:19], v[224:227], v[200:203], v[16:19]
	v_mfma_f32_16x16x32_bf16 v[4:7], v[216:219], v[208:211], v[4:7]
	v_mfma_f32_16x16x32_bf16 v[0:3], v[224:227], v[208:211], v[0:3]
	s_setprio 0
	s_add_u32 s36, s36, 0x100
	s_addc_u32 s37, s37, 0
	s_add_u32 s44, s44, 0x100
	s_addc_u32 s45, s45, 0
	s_cmp_ge_i32 s5, s84
	s_mov_b32 s4, s5
	s_barrier
	s_cbranch_scc0 .LBB0_1379
.Lpeel_exit_3:
	s_branch .LBB0_1370
.LBB0_1380:
	s_waitcnt vmcnt(0)
	s_cmpk_gt_u32 s47, 0xff
	s_cbranch_scc1 .LBB0_1382
	s_barrier

; #define PG8_STAGE(bufoff, gbase, voff) do { _Pragma("unroll") for (int _i = 0; _i < 2; ++_i) \
;         __builtin_amdgcn_global_load_lds((const unsigned*)((const char*)(gbase) + (voff)[_i]), (LAS unsigned*)(lds + (bufoff) + ldsw + _i * 8192), 16, 0, 0); } while (0)
; #define PG8_LDA(dst, b, h) do { _Pragma("unroll") for (int m = 0; m < 4; ++m) _Pragma("unroll") for (int k = 0; k < 2; ++k) dst[m][k] = *(const LAS bf16x8*)(lds + PG8_SA(b, h) + aoff + m * 2048 + k * 1024); } while (0)
; #define PG8_LDB(dst, b, h) do { _Pragma("unroll") for (int n = 0; n < 2; ++n) _Pragma("unroll") for (int k = 0; k < 2; ++k) dst[n][k] = *(const LAS bf16x8*)(lds + PG8_SB(b, h) + boff + n * 2048 + k * 1024); } while (0)
; #define PG8_MMA(ai, bj, At, Bt) do { __builtin_amdgcn_s_setprio(1); _Pragma("unroll") for (int m = 0; m < 4; ++m) _Pragma("unroll") for (int n = 0; n < 2; ++n) _Pragma("unroll") for (int k = 0; k < 2; ++k) \
;         acc[ai][bj][m][n] = __builtin_amdgcn_mfma_f32_16x16x32_bf16(Bt[n][k], At[m][k], acc[ai][bj][m][n], 0, 0, 0); __builtin_amdgcn_s_setprio(0); } while (0)
; #define PG8_WAIT_L(n) asm volatile("s_waitcnt lgkmcnt(" #n ")" ::: "memory")
; #define PG8_BAR __builtin_amdgcn_s_barrier()
; #define PG8_SCHED __builtin_amdgcn_sched_barrier(0)
; template <class Epi>
; DI void gemm_phase(LAS unsigned char* lds, const Gemm g, const StaticOrder& S, const Epi& E) {
;     ...
;             const bool last = (t == nt - 2);
;             const char* a1 = cA + (size_t)(t + 1) * kstep;
;             const char* a2 = last ? nA : cA + (size_t)(t + 2) * kstep; const char* b2 = last ? nB : cB + (size_t)(t + 2) * kstep;
;             const char* a3 = a2 + kstep; const char* b3 = b2 + kstep;
;             PG8_LDB(B0, 0, 0); PG8_SCHED; PG8_LDA(At, 0, 0); PG8_STAGE(PG8_SA(1, 1), a1 + hstep, voffA);
;             PG8_WAIT_L(8); PG8_BAR; PG8_WAIT_L(0); PG8_MMA(0, 0, At, B0); PG8_BAR; PG8_SCHED;
;             PG8_LDB(B1, 0, 1); PG8_STAGE(PG8_SB(0, 0), b2, voffB);
;             PG8_BAR; PG8_WAIT_L(0); PG8_MMA(0, 1, At, B1); PG8_BAR;
;             PG8_LDA(At, 0, 1); PG8_STAGE(PG8_SA(0, 0), a2, voffA);
;             PG8_BAR; PG8_WAIT_L(0); PG8_MMA(1, 0, At, B0); PG8_BAR; PG8_SCHED;
.LBB0_1448:
	s_andn2_b64 vcc, exec, s[14:15]
	s_waitcnt lgkmcnt(0)
	s_cbranch_vccnz .LBB0_1451
	s_add_u32 s36, s36, 0x80
	s_addc_u32 s37, s37, 0
	s_add_u32 s0, s44, 0x100
	s_addc_u32 s44, s45, 0
	s_mov_b32 s4, 0
	s_mov_b32 s72, 0x10000
	s_mov_b32 s73, 0x14000
	s_mov_b32 s74, 0x18000
	s_mov_b32 s75, 0x1c000
	s_mov_b64 s[76:77], 0x80
	s_add_i32 s5, s4, 2
	s_add_u32 s40, s36, 0x80
	s_addc_u32 s41, s37, 0
	s_add_i32 s45, s72, 0x100
	v_add_u32_e32 v153, s45, v151
	ds_read_b128 v[138:141], v153
	ds_read_b128 v[154:157], v153 offset:1024
	ds_read_b128 v[158:161], v153 offset:2048
	ds_read_b128 v[170:173], v153 offset:3072
	s_cmp_eq_u32 s62, s4
	s_cselect_b32 s41, s17, s41
	s_cselect_b32 s40, s16, s40
	s_cselect_b32 s43, s19, s44
	s_cselect_b32 s42, s18, s0
	v_lshl_add_u64 v[162:163], s[36:37], 0, v[134:135]
	s_add_i32 m0, s52, 0xc000
	ds_read_b128 v[174:177], v152
	ds_read_b128 v[178:181], v152 offset:1024
	ds_read_b128 v[188:191], v152 offset:2048
	ds_read_b128 v[192:195], v152 offset:3072
	ds_read_b128 v[196:199], v152 offset:4096
	ds_read_b128 v[200:203], v152 offset:5120
	ds_read_b128 v[204:207], v152 offset:6144
	ds_read_b128 v[208:211], v152 offset:7168
	global_load_lds_dwordx4 v[162:163], off
	v_lshl_add_u64 v[162:163], s[36:37], 0, v[136:137]
	s_add_i32 m0, s52, 0xe000
	s_nop 0
	global_load_lds_dwordx4 v[162:163], off
	s_waitcnt lgkmcnt(8)
	s_barrier
	s_waitcnt lgkmcnt(0)
	s_setprio 1
	s_waitcnt lgkmcnt(0)
	v_mfma_f32_16x16x32_bf16 v[124:127], v[138:141], v[174:177], 0
	v_mfma_f32_16x16x32_bf16 v[120:123], v[158:161], v[174:177], 0
	v_mfma_f32_16x16x32_bf16 v[108:111], v[138:141], v[188:191], 0
	v_mfma_f32_16x16x32_bf16 v[104:107], v[158:161], v[188:191], 0
	v_mfma_f32_16x16x32_bf16 v[92:95], v[138:141], v[196:199], 0
	v_mfma_f32_16x16x32_bf16 v[88:91], v[158:161], v[196:199], 0
	v_mfma_f32_16x16x32_bf16 v[76:79], v[138:141], v[204:207], 0
	v_mfma_f32_16x16x32_bf16 v[72:75], v[158:161], v[204:207], 0
	v_mfma_f32_16x16x32_bf16 v[124:127], v[154:157], v[178:181], v[124:127]
	v_mfma_f32_16x16x32_bf16 v[120:123], v[170:173], v[178:181], v[120:123]
	v_mfma_f32_16x16x32_bf16 v[108:111], v[154:157], v[192:195], v[108:111]
	v_mfma_f32_16x16x32_bf16 v[104:107], v[170:173], v[192:195], v[104:107]
	v_mfma_f32_16x16x32_bf16 v[92:95], v[154:157], v[200:203], v[92:95]
	v_mfma_f32_16x16x32_bf16 v[88:91], v[170:173], v[200:203], v[88:91]
	v_mfma_f32_16x16x32_bf16 v[76:79], v[154:157], v[208:211], v[76:79]
	v_mfma_f32_16x16x32_bf16 v[72:75], v[170:173], v[208:211], v[72:75]
	s_setprio 0
	s_barrier
	s_add_i32 s4, s73, 0x100
	s_add_i32 s45, s45, s51
	v_add_u32_e32 v153, s4, v151
	v_lshl_add_u64 v[162:163], s[42:43], 0, v[166:167]
	s_mov_b32 m0, s45
	ds_read_b128 v[212:215], v153
	ds_read_b128 v[216:219], v153 offset:1024
	ds_read_b128 v[220:223], v153 offset:2048
	ds_read_b128 v[224:227], v153 offset:3072
	global_load_lds_dwordx4 v[162:163], off
	v_lshl_add_u64 v[182:183], s[42:43], 0, v[132:133]
	s_add_i32 m0, s45, 0x2000
	s_nop 0
	global_load_lds_dwordx4 v[182:183], off
	s_barrier
	s_waitcnt lgkmcnt(0)
	s_setprio 1
	s_waitcnt lgkmcnt(0)
	v_mfma_f32_16x16x32_bf16 v[116:119], v[212:215], v[174:177], 0
	v_mfma_f32_16x16x32_bf16 v[112:115], v[220:223], v[174:177], 0
	v_mfma_f32_16x16x32_bf16 v[100:103], v[212:215], v[188:191], 0
	v_mfma_f32_16x16x32_bf16 v[96:99], v[220:223], v[188:191], 0
	v_mfma_f32_16x16x32_bf16 v[84:87], v[212:215], v[196:199], 0
	v_mfma_f32_16x16x32_bf16 v[80:83], v[220:223], v[196:199], 0
	v_mfma_f32_16x16x32_bf16 v[68:71], v[212:215], v[204:207], 0
	v_mfma_f32_16x16x32_bf16 v[64:67], v[220:223], v[204:207], 0
	v_mfma_f32_16x16x32_bf16 v[116:119], v[216:219], v[178:181], v[116:119]
	v_mfma_f32_16x16x32_bf16 v[112:115], v[224:227], v[178:181], v[112:115]
	v_mfma_f32_16x16x32_bf16 v[100:103], v[216:219], v[192:195], v[100:103]
	v_mfma_f32_16x16x32_bf16 v[96:99], v[224:227], v[192:195], v[96:99]
	v_mfma_f32_16x16x32_bf16 v[84:87], v[216:219], v[200:203], v[84:87]
	v_mfma_f32_16x16x32_bf16 v[80:83], v[224:227], v[200:203], v[80:83]
	v_mfma_f32_16x16x32_bf16 v[68:71], v[216:219], v[208:211], v[68:71]
	v_mfma_f32_16x16x32_bf16 v[64:67], v[224:227], v[208:211], v[64:67]
	s_setprio 0
	s_mov_b32 m0, s52
	v_lshl_add_u64 v[228:229], s[40:41], 0, v[128:129]
	s_barrier
	ds_read_b128 v[174:177], v152 offset:16384
	ds_read_b128 v[178:181], v152 offset:17408
	ds_read_b128 v[188:191], v152 offset:18432
	ds_read_b128 v[192:195], v152 offset:19456
	ds_read_b128 v[196:199], v152 offset:20480
	ds_read_b128 v[200:203], v152 offset:21504
	ds_read_b128 v[204:207], v152 offset:22528
	ds_read_b128 v[208:211], v152 offset:23552
	global_load_lds_dwordx4 v[228:229], off
	v_lshl_add_u64 v[230:231], s[40:41], 0, v[130:131]
	s_mov_b32 m0, s53
	s_nop 0
	global_load_lds_dwordx4 v[230:231], off
	s_barrier
	s_waitcnt lgkmcnt(0)
	s_setprio 1
	s_waitcnt lgkmcnt(0)
	v_mfma_f32_16x16x32_bf16 v[60:63], v[138:141], v[174:177], 0
	v_mfma_f32_16x16x32_bf16 v[56:59], v[158:161], v[174:177], 0
	v_mfma_f32_16x16x32_bf16 v[44:47], v[138:141], v[188:191], 0
	v_mfma_f32_16x16x32_bf16 v[40:43], v[158:161], v[188:191], 0
	v_mfma_f32_16x16x32_bf16 v[28:31], v[138:141], v[196:199], 0
	v_mfma_f32_16x16x32_bf16 v[24:27], v[158:161], v[196:199], 0
	v_mfma_f32_16x16x32_bf16 v[12:15], v[138:141], v[204:207], 0
	v_mfma_f32_16x16x32_bf16 v[8:11], v[158:161], v[204:207], 0
	v_mfma_f32_16x16x32_bf16 v[60:63], v[154:157], v[178:181], v[60:63]
	v_mfma_f32_16x16x32_bf16 v[56:59], v[170:173], v[178:181], v[56:59]
	v_mfma_f32_16x16x32_bf16 v[44:47], v[154:157], v[192:195], v[44:47]
	v_mfma_f32_16x16x32_bf16 v[40:43], v[170:173], v[192:195], v[40:43]
	v_mfma_f32_16x16x32_bf16 v[28:31], v[154:157], v[200:203], v[28:31]
	v_mfma_f32_16x16x32_bf16 v[24:27], v[170:173], v[200:203], v[24:27]
	v_mfma_f32_16x16x32_bf16 v[12:15], v[154:157], v[208:211], v[12:15]
	v_mfma_f32_16x16x32_bf16 v[8:11], v[170:173], v[208:211], v[8:11]
	s_setprio 0
	s_barrier
; #define PG8_STAGE(bufoff, gbase, voff) do { _Pragma("unroll") for (int _i = 0; _i < 2; ++_i) \
;         __builtin_amdgcn_global_load_lds((const unsigned*)((const char*)(gbase) + (voff)[_i]), (LAS unsigned*)(lds + (bufoff) + ldsw + _i * 8192), 16, 0, 0); } while (0)
; #define PG8_LDA(dst, b, h) do { _Pragma("unroll") for (int m = 0; m < 4; ++m) _Pragma("unroll") for (int k = 0; k < 2; ++k) dst[m][k] = *(const LAS bf16x8*)(lds + PG8_SA(b, h) + aoff + m * 2048 + k * 1024); } while (0)
; #define PG8_LDB(dst, b, h) do { _Pragma("unroll") for (int n = 0; n < 2; ++n) _Pragma("unroll") for (int k = 0; k < 2; ++k) dst[n][k] = *(const LAS bf16x8*)(lds + PG8_SB(b, h) + boff + n * 2048 + k * 1024); } while (0)
; #define PG8_MMA(ai, bj, At, Bt) do { __builtin_amdgcn_s_setprio(1); _Pragma("unroll") for (int m = 0; m < 4; ++m) _Pragma("unroll") for (int n = 0; n < 2; ++n) _Pragma("unroll") for (int k = 0; k < 2; ++k) \
;         acc[ai][bj][m][n] = __builtin_amdgcn_mfma_f32_16x16x32_bf16(Bt[n][k], At[m][k], acc[ai][bj][m][n], 0, 0, 0); __builtin_amdgcn_s_setprio(0); } while (0)
; #define PG8_WAIT_V(n) asm volatile("s_waitcnt vmcnt(" #n ")" ::: "memory")
; #define PG8_WAIT_L(n) asm volatile("s_waitcnt lgkmcnt(" #n ")" ::: "memory")
; #define PG8_BAR __builtin_amdgcn_s_barrier()
; #define PG8_SCHED __builtin_amdgcn_sched_barrier(0)
; template <class Epi>
; DI void gemm_phase(LAS unsigned char* lds, const Gemm g, const StaticOrder& S, const Epi& E) {
;     ...
;             PG8_STAGE(PG8_SB(0, 1), b2 + hstep, voffB);
;             PG8_WAIT_V(6); PG8_BAR; PG8_MMA(1, 1, At, B1); PG8_BAR;
;             PG8_LDB(B0, 1, 0); PG8_SCHED; PG8_LDA(At, 1, 0); PG8_STAGE(PG8_SA(0, 1), a2 + hstep, voffA);
;             PG8_WAIT_L(8); PG8_BAR; PG8_WAIT_L(0); PG8_MMA(0, 0, At, B0); PG8_BAR; PG8_SCHED;
;             PG8_LDB(B1, 1, 1); PG8_STAGE(PG8_SB(1, 0), b3, voffB);
	s_add_u32 s42, s42, s10
	s_addc_u32 s43, s43, s11
	s_add_i32 s4, s4, s51
	v_lshl_add_u64 v[232:233], s[42:43], 0, v[166:167]
	s_mov_b32 m0, s4
	v_lshl_add_u64 v[234:235], s[42:43], 0, v[132:133]
	global_load_lds_dwordx4 v[232:233], off
	s_add_i32 m0, s4, 0x2000
	s_nop 0
	global_load_lds_dwordx4 v[234:235], off
	s_waitcnt vmcnt(6)
	s_barrier
	s_setprio 1
	v_mfma_f32_16x16x32_bf16 v[52:55], v[212:215], v[174:177], 0
	v_mfma_f32_16x16x32_bf16 v[48:51], v[220:223], v[174:177], 0
	v_mfma_f32_16x16x32_bf16 v[36:39], v[212:215], v[188:191], 0
	v_mfma_f32_16x16x32_bf16 v[32:35], v[220:223], v[188:191], 0
	v_mfma_f32_16x16x32_bf16 v[20:23], v[212:215], v[196:199], 0
	v_mfma_f32_16x16x32_bf16 v[16:19], v[220:223], v[196:199], 0
	v_mfma_f32_16x16x32_bf16 v[4:7], v[212:215], v[204:207], 0
	v_mfma_f32_16x16x32_bf16 v[0:3], v[220:223], v[204:207], 0
	v_mfma_f32_16x16x32_bf16 v[52:55], v[216:219], v[178:181], v[52:55]
	v_mfma_f32_16x16x32_bf16 v[48:51], v[224:227], v[178:181], v[48:51]
	v_mfma_f32_16x16x32_bf16 v[36:39], v[216:219], v[192:195], v[36:39]
	v_mfma_f32_16x16x32_bf16 v[32:35], v[224:227], v[192:195], v[32:35]
	v_mfma_f32_16x16x32_bf16 v[20:23], v[216:219], v[200:203], v[20:23]
	v_mfma_f32_16x16x32_bf16 v[16:19], v[224:227], v[200:203], v[16:19]
	v_mfma_f32_16x16x32_bf16 v[4:7], v[216:219], v[208:211], v[4:7]
	v_mfma_f32_16x16x32_bf16 v[0:3], v[224:227], v[208:211], v[0:3]
	s_setprio 0
	s_add_i32 s4, s74, 0x100
	v_add_u32_e32 v153, s4, v151
	s_barrier
	ds_read_b128 v[138:141], v153
	ds_read_b128 v[154:157], v153 offset:1024
	ds_read_b128 v[158:161], v153 offset:2048
	ds_read_b128 v[170:173], v153 offset:3072
	s_add_u32 s40, s40, s10
	s_addc_u32 s41, s41, s11
	s_mov_b32 m0, s54
	v_lshl_add_u64 v[212:213], s[40:41], 0, v[128:129]
	ds_read_b128 v[174:177], v152 offset:32768
	ds_read_b128 v[178:181], v152 offset:33792
	ds_read_b128 v[188:191], v152 offset:34816
	ds_read_b128 v[192:195], v152 offset:35840
	ds_read_b128 v[196:199], v152 offset:36864
	ds_read_b128 v[200:203], v152 offset:37888
	ds_read_b128 v[204:207], v152 offset:38912
	ds_read_b128 v[208:211], v152 offset:39936
	global_load_lds_dwordx4 v[212:213], off
	v_lshl_add_u64 v[212:213], s[40:41], 0, v[130:131]
	s_mov_b32 m0, s55
	s_nop 0
	global_load_lds_dwordx4 v[212:213], off
	s_waitcnt lgkmcnt(8)
	s_barrier
	s_waitcnt lgkmcnt(0)
	s_setprio 1
	s_waitcnt lgkmcnt(0)
	v_mfma_f32_16x16x32_bf16 v[124:127], v[138:141], v[174:177], v[124:127]
	v_mfma_f32_16x16x32_bf16 v[120:123], v[158:161], v[174:177], v[120:123]
	v_mfma_f32_16x16x32_bf16 v[108:111], v[138:141], v[188:191], v[108:111]
	v_mfma_f32_16x16x32_bf16 v[104:107], v[158:161], v[188:191], v[104:107]
	v_mfma_f32_16x16x32_bf16 v[92:95], v[138:141], v[196:199], v[92:95]
	v_mfma_f32_16x16x32_bf16 v[88:91], v[158:161], v[196:199], v[88:91]
	v_mfma_f32_16x16x32_bf16 v[76:79], v[138:141], v[204:207], v[76:79]
	v_mfma_f32_16x16x32_bf16 v[72:75], v[158:161], v[204:207], v[72:75]
	v_mfma_f32_16x16x32_bf16 v[124:127], v[154:157], v[178:181], v[124:127]
	v_mfma_f32_16x16x32_bf16 v[120:123], v[170:173], v[178:181], v[120:123]
	v_mfma_f32_16x16x32_bf16 v[108:111], v[154:157], v[192:195], v[108:111]
	v_mfma_f32_16x16x32_bf16 v[104:107], v[170:173], v[192:195], v[104:107]
	v_mfma_f32_16x16x32_bf16 v[92:95], v[154:157], v[200:203], v[92:95]
	v_mfma_f32_16x16x32_bf16 v[88:91], v[170:173], v[200:203], v[88:91]
	v_mfma_f32_16x16x32_bf16 v[76:79], v[154:157], v[208:211], v[76:79]
	v_mfma_f32_16x16x32_bf16 v[72:75], v[170:173], v[208:211], v[72:75]
	s_setprio 0
	s_barrier
	s_add_i32 s40, s75, 0x100
	s_add_i32 s4, s4, s51
	v_add_u32_e32 v153, s40, v151
	v_lshl_add_u64 v[162:163], v[162:163], 0, s[76:77]
	s_mov_b32 m0, s4
	ds_read_b128 v[212:215], v153
	ds_read_b128 v[216:219], v153 offset:1024
	ds_read_b128 v[220:223], v153 offset:2048
	ds_read_b128 v[224:227], v153 offset:3072
	global_load_lds_dwordx4 v[162:163], off
	v_lshl_add_u64 v[162:163], v[182:183], 0, s[76:77]
	s_add_i32 m0, s4, 0x2000
	s_nop 0
	global_load_lds_dwordx4 v[162:163], off
	s_barrier
; #define PG8_STAGE(bufoff, gbase, voff) do { _Pragma("unroll") for (int _i = 0; _i < 2; ++_i) \
;         __builtin_amdgcn_global_load_lds((const unsigned*)((const char*)(gbase) + (voff)[_i]), (LAS unsigned*)(lds + (bufoff) + ldsw + _i * 8192), 16, 0, 0); } while (0)
; #define PG8_LDA(dst, b, h) do { _Pragma("unroll") for (int m = 0; m < 4; ++m) _Pragma("unroll") for (int k = 0; k < 2; ++k) dst[m][k] = *(const LAS bf16x8*)(lds + PG8_SA(b, h) + aoff + m * 2048 + k * 1024); } while (0)
; #define PG8_MMA(ai, bj, At, Bt) do { __builtin_amdgcn_s_setprio(1); _Pragma("unroll") for (int m = 0; m < 4; ++m) _Pragma("unroll") for (int n = 0; n < 2; ++n) _Pragma("unroll") for (int k = 0; k < 2; ++k) \
;         acc[ai][bj][m][n] = __builtin_amdgcn_mfma_f32_16x16x32_bf16(Bt[n][k], At[m][k], acc[ai][bj][m][n], 0, 0, 0); __builtin_amdgcn_s_setprio(0); } while (0)
; #define PG8_WAIT_V(n) asm volatile("s_waitcnt vmcnt(" #n ")" ::: "memory")
; #define PG8_WAIT_L(n) asm volatile("s_waitcnt lgkmcnt(" #n ")" ::: "memory")
; #define PG8_BAR __builtin_amdgcn_s_barrier()
; #define PG8_SCHED __builtin_amdgcn_sched_barrier(0)
; template <class Epi>
; DI void gemm_phase(LAS unsigned char* lds, const Gemm g, const StaticOrder& S, const Epi& E) {
;     ...
;             PG8_BAR; PG8_WAIT_L(0); PG8_MMA(0, 1, At, B1); PG8_BAR;
;             PG8_LDA(At, 1, 1); PG8_STAGE(PG8_SA(1, 0), a3, voffA);
;             PG8_BAR; PG8_WAIT_L(0); PG8_MMA(1, 0, At, B0); PG8_BAR; PG8_SCHED;
;             PG8_STAGE(PG8_SB(1, 1), b3 + hstep, voffB);
;             PG8_WAIT_V(6); PG8_BAR; PG8_MMA(1, 1, At, B1); PG8_BAR;
	s_waitcnt lgkmcnt(0)
	s_setprio 1
	s_waitcnt lgkmcnt(0)
	v_mfma_f32_16x16x32_bf16 v[116:119], v[212:215], v[174:177], v[116:119]
	v_mfma_f32_16x16x32_bf16 v[112:115], v[220:223], v[174:177], v[112:115]
	v_mfma_f32_16x16x32_bf16 v[100:103], v[212:215], v[188:191], v[100:103]
	v_mfma_f32_16x16x32_bf16 v[96:99], v[220:223], v[188:191], v[96:99]
	v_mfma_f32_16x16x32_bf16 v[84:87], v[212:215], v[196:199], v[84:87]
	v_mfma_f32_16x16x32_bf16 v[80:83], v[220:223], v[196:199], v[80:83]
	v_mfma_f32_16x16x32_bf16 v[68:71], v[212:215], v[204:207], v[68:71]
	v_mfma_f32_16x16x32_bf16 v[64:67], v[220:223], v[204:207], v[64:67]
	v_mfma_f32_16x16x32_bf16 v[116:119], v[216:219], v[178:181], v[116:119]
	v_mfma_f32_16x16x32_bf16 v[112:115], v[224:227], v[178:181], v[112:115]
	v_mfma_f32_16x16x32_bf16 v[100:103], v[216:219], v[192:195], v[100:103]
	v_mfma_f32_16x16x32_bf16 v[96:99], v[224:227], v[192:195], v[96:99]
	v_mfma_f32_16x16x32_bf16 v[84:87], v[216:219], v[200:203], v[84:87]
	v_mfma_f32_16x16x32_bf16 v[80:83], v[224:227], v[200:203], v[80:83]
	v_mfma_f32_16x16x32_bf16 v[68:71], v[216:219], v[208:211], v[68:71]
	v_mfma_f32_16x16x32_bf16 v[64:67], v[224:227], v[208:211], v[64:67]
	s_setprio 0
	s_mov_b32 m0, s60
	v_lshl_add_u64 v[162:163], v[228:229], 0, s[76:77]
	s_barrier
	ds_read_b128 v[174:177], v152 offset:49152
	ds_read_b128 v[178:181], v152 offset:50176
	ds_read_b128 v[188:191], v152 offset:51200
	ds_read_b128 v[192:195], v152 offset:52224
	ds_read_b128 v[196:199], v152 offset:53248
	ds_read_b128 v[200:203], v152 offset:54272
	ds_read_b128 v[204:207], v152 offset:55296
	ds_read_b128 v[208:211], v152 offset:56320
	global_load_lds_dwordx4 v[162:163], off
	v_lshl_add_u64 v[162:163], v[230:231], 0, s[76:77]
	s_mov_b32 m0, s61
	s_nop 0
	global_load_lds_dwordx4 v[162:163], off
	s_barrier
	s_waitcnt lgkmcnt(0)
	s_setprio 1
	s_waitcnt lgkmcnt(0)
	v_mfma_f32_16x16x32_bf16 v[60:63], v[138:141], v[174:177], v[60:63]
	v_mfma_f32_16x16x32_bf16 v[56:59], v[158:161], v[174:177], v[56:59]
	v_mfma_f32_16x16x32_bf16 v[44:47], v[138:141], v[188:191], v[44:47]
	v_mfma_f32_16x16x32_bf16 v[40:43], v[158:161], v[188:191], v[40:43]
	v_mfma_f32_16x16x32_bf16 v[28:31], v[138:141], v[196:199], v[28:31]
	v_mfma_f32_16x16x32_bf16 v[24:27], v[158:161], v[196:199], v[24:27]
	v_mfma_f32_16x16x32_bf16 v[12:15], v[138:141], v[204:207], v[12:15]
	v_mfma_f32_16x16x32_bf16 v[8:11], v[158:161], v[204:207], v[8:11]
	v_mfma_f32_16x16x32_bf16 v[60:63], v[154:157], v[178:181], v[60:63]
	v_mfma_f32_16x16x32_bf16 v[56:59], v[170:173], v[178:181], v[56:59]
	v_mfma_f32_16x16x32_bf16 v[44:47], v[154:157], v[192:195], v[44:47]
	v_mfma_f32_16x16x32_bf16 v[40:43], v[170:173], v[192:195], v[40:43]
	v_mfma_f32_16x16x32_bf16 v[28:31], v[154:157], v[200:203], v[28:31]
	v_mfma_f32_16x16x32_bf16 v[24:27], v[170:173], v[200:203], v[24:27]
	v_mfma_f32_16x16x32_bf16 v[12:15], v[154:157], v[208:211], v[12:15]
	v_mfma_f32_16x16x32_bf16 v[8:11], v[170:173], v[208:211], v[8:11]
	s_setprio 0
	s_barrier
	s_add_i32 s4, s40, s51
	v_lshl_add_u64 v[138:139], v[232:233], 0, s[76:77]
	s_mov_b32 m0, s4
	s_nop 0
	global_load_lds_dwordx4 v[138:139], off
	v_lshl_add_u64 v[138:139], v[234:235], 0, s[76:77]
	s_add_i32 m0, s4, 0x2000
	s_nop 0
	global_load_lds_dwordx4 v[138:139], off
	s_waitcnt vmcnt(6)
	s_barrier
	s_setprio 1
	v_mfma_f32_16x16x32_bf16 v[52:55], v[212:215], v[174:177], v[52:55]
	v_mfma_f32_16x16x32_bf16 v[48:51], v[220:223], v[174:177], v[48:51]
	v_mfma_f32_16x16x32_bf16 v[36:39], v[212:215], v[188:191], v[36:39]
	v_mfma_f32_16x16x32_bf16 v[32:35], v[220:223], v[188:191], v[32:35]
	v_mfma_f32_16x16x32_bf16 v[20:23], v[212:215], v[196:199], v[20:23]
	v_mfma_f32_16x16x32_bf16 v[16:19], v[220:223], v[196:199], v[16:19]
	v_mfma_f32_16x16x32_bf16 v[4:7], v[212:215], v[204:207], v[4:7]
	v_mfma_f32_16x16x32_bf16 v[0:3], v[220:223], v[204:207], v[0:3]
	v_mfma_f32_16x16x32_bf16 v[52:55], v[216:219], v[178:181], v[52:55]
	v_mfma_f32_16x16x32_bf16 v[48:51], v[224:227], v[178:181], v[48:51]
	v_mfma_f32_16x16x32_bf16 v[36:39], v[216:219], v[192:195], v[36:39]
	v_mfma_f32_16x16x32_bf16 v[32:35], v[224:227], v[192:195], v[32:35]
	v_mfma_f32_16x16x32_bf16 v[20:23], v[216:219], v[200:203], v[20:23]
	v_mfma_f32_16x16x32_bf16 v[16:19], v[224:227], v[200:203], v[16:19]
	v_mfma_f32_16x16x32_bf16 v[4:7], v[216:219], v[208:211], v[4:7]
	v_mfma_f32_16x16x32_bf16 v[0:3], v[224:227], v[208:211], v[0:3]
	s_setprio 0
	s_add_u32 s36, s36, 0x100
	s_addc_u32 s37, s37, 0
	s_add_u32 s0, s0, 0x100
	s_addc_u32 s44, s44, 0
	s_cmp_ge_i32 s5, s57
	s_mov_b32 s4, s5
	s_barrier
	s_cbranch_scc0 .LBB0_1450
	s_branch .Lpeel_exit_4

; DI float blo(unsigned w) { return __uint_as_float(w << 16); }
; DI float bhi(unsigned w) { return __uint_as_float(w & 0xffff0000u); }
; DI u32x4 pk8(f32x4 a, f32x4 b) { u32x4 r; r.x = pk2(a[0], a[1]); r.y = pk2(a[2], a[3]); r.z = pk2(b[0], b[1]); r.w = pk2(b[2], b[3]); return r; }
;     DI void operator()(const Acc& acc, const pg8::Unit& u, int wr, int wc, int fr, int fq) const {
;     ...
;             for (int m = 0; m < 4; ++m) { const int row = row0 + ai * 128 + m * 16; float ss = 0.f;
; #pragma unroll
;                 for (int bj = 0; bj < 2; ++bj) { f32x4 v0 = acc[ai][bj][m][0], v1 = acc[ai][bj][m][1]; const size_t off = (size_t)row * 1024 + c0 + bj * 128;
;                     if (gate) { const u32x4 gw = *(const u32x4*)(gate + off);
;                         v0[0] *= blo(gw.x); v0[1] *= bhi(gw.x); v0[2] *= blo(gw.y); v0[3] *= bhi(gw.y); v1[0] *= blo(gw.z); v1[1] *= bhi(gw.z); v1[2] *= blo(gw.w); v1[3] *= bhi(gw.w); }
;                     *(u32x4*)(t + off) = pk8(v0, v1);
;                     ss += v0[0] * v0[0] + v0[1] * v0[1] + v0[2] * v0[2] + v0[3] * v0[3] + v1[0] * v1[0] + v1[1] * v1[1] + v1[2] * v1[2] + v1[3] * v1[3]; }
;                 ss += __shfl_xor(ss, 16); ss += __shfl_xor(ss, 32);
;                 if (fq == 0) ssq[row * 16 + u.pn * 4 + wc] = ss;
.Lpeel_exit_4:
.LBB0_1451:
	v_cvt_pk_bf16_f32 v156, v124, v125
	v_mul_f32_e32 v125, v125, v125
	v_fmac_f32_e32 v125, v124, v124
	v_fmac_f32_e32 v125, v126, v126
	v_fmac_f32_e32 v125, v127, v127
	v_cvt_pk_bf16_f32 v158, v120, v121
	v_fmac_f32_e32 v125, v120, v120
	v_mul_f32_e32 v120, v117, v117
	v_fmac_f32_e32 v120, v116, v116
	v_fmac_f32_e32 v120, v118, v118
	v_fmac_f32_e32 v120, v119, v119
	v_fmac_f32_e32 v120, v112, v112
	v_add_u32_e32 v153, 64, v148
	v_fmac_f32_e32 v125, v121, v121
	v_fmac_f32_e32 v120, v113, v113
	v_cmp_lt_i32_e32 vcc, v146, v153
	v_fmac_f32_e32 v125, v122, v122
	v_fmac_f32_e32 v120, v114, v114
	s_lshl_b32 s0, s79, 8
	v_cndmask_b32_e32 v154, v184, v146, vcc
	v_fmac_f32_e32 v125, v123, v123
	v_fmac_f32_e32 v120, v115, v115
	v_mov_b32_e32 v138, v150
	v_mov_b32_e32 v141, v149
	s_add_i32 s0, s0, s58
	v_lshlrev_b32_e32 v154, 2, v154
	v_cvt_pk_bf16_f32 v159, v122, v123
	v_add_f32_e32 v122, v120, v125
	ds_bpermute_b32 v123, v154, v122
	v_add_u32_e32 v140, s0, v138
	s_lshl_b32 s0, s78, 8
	s_or_b32 s0, s0, s59
	v_cmp_lt_i32_e32 vcc, v147, v153
	v_lshl_add_u32 v138, v141, 3, s0
	s_lshl_b32 s0, s78, 2
	v_cndmask_b32_e32 v153, v184, v147, vcc
	v_cmp_eq_u32_e32 vcc, 0, v141
	v_ashrrev_i32_e32 v141, 31, v140
	v_readlane_b32 s72, v238, 1
	v_lshlrev_b64 v[160:161], 11, v[140:141]
	v_readlane_b32 s84, v238, 13
	v_readlane_b32 s85, v238, 14
	v_ashrrev_i32_e32 v139, 31, v138
	v_lshlrev_b32_e32 v153, 2, v153
	v_lshl_add_u64 v[120:121], s[84:85], 0, v[160:161]
	v_lshl_add_u64 v[124:125], v[138:139], 1, v[120:121]
	v_cvt_pk_bf16_f32 v120, v116, v117
	s_waitcnt lgkmcnt(0)
	v_add_f32_e32 v116, v122, v123
	ds_bpermute_b32 v117, v153, v116
	s_or_b32 s0, s0, s56
	v_cvt_pk_bf16_f32 v157, v126, v127
	v_cvt_pk_bf16_f32 v121, v118, v119
	v_cvt_pk_bf16_f32 v122, v112, v113
	v_cvt_pk_bf16_f32 v123, v114, v115
	v_readlane_b32 s73, v238, 2
	v_readlane_b32 s74, v238, 3
	v_readlane_b32 s75, v238, 4
	v_readlane_b32 s76, v238, 5
	v_readlane_b32 s77, v238, 6
	v_readlane_b32 s78, v238, 7
	v_readlane_b32 s79, v238, 8
	v_readlane_b32 s80, v238, 9
	v_readlane_b32 s81, v238, 10
	v_readlane_b32 s82, v238, 11
	v_readlane_b32 s83, v238, 12
	v_readlane_b32 s86, v238, 15
	v_readlane_b32 s87, v238, 16
	global_store_dwordx4 v[124:125], v[156:159], off
	global_store_dwordx4 v[124:125], v[120:123], off offset:256
	s_and_saveexec_b64 s[36:37], vcc
	s_cbranch_execz .LBB0_1453
	v_lshl_add_u32 v112, v140, 4, s0
	v_readlane_b32 s4, v238, 28
	v_ashrrev_i32_e32 v113, 31, v112
	v_readlane_b32 s5, v238, 29
	s_waitcnt lgkmcnt(0)
	v_add_f32_e32 v114, v116, v117
	v_lshl_add_u64 v[112:113], v[112:113], 2, s[4:5]
	global_store_dword v[112:113], v114, off

; #define PG8_STAGE(bufoff, gbase, voff) do { _Pragma("unroll") for (int _i = 0; _i < 2; ++_i) \
;         __builtin_amdgcn_global_load_lds((const unsigned*)((const char*)(gbase) + (voff)[_i]), (LAS unsigned*)(lds + (bufoff) + ldsw + _i * 8192), 16, 0, 0); } while (0)
; #define PG8_LDA(dst, b, h) do { _Pragma("unroll") for (int m = 0; m < 4; ++m) _Pragma("unroll") for (int k = 0; k < 2; ++k) dst[m][k] = *(const LAS bf16x8*)(lds + PG8_SA(b, h) + aoff + m * 2048 + k * 1024); } while (0)
; #define PG8_LDB(dst, b, h) do { _Pragma("unroll") for (int n = 0; n < 2; ++n) _Pragma("unroll") for (int k = 0; k < 2; ++k) dst[n][k] = *(const LAS bf16x8*)(lds + PG8_SB(b, h) + boff + n * 2048 + k * 1024); } while (0)
; #define PG8_MMA(ai, bj, At, Bt) do { __builtin_amdgcn_s_setprio(1); _Pragma("unroll") for (int m = 0; m < 4; ++m) _Pragma("unroll") for (int n = 0; n < 2; ++n) _Pragma("unroll") for (int k = 0; k < 2; ++k) \
;         acc[ai][bj][m][n] = __builtin_amdgcn_mfma_f32_16x16x32_bf16(Bt[n][k], At[m][k], acc[ai][bj][m][n], 0, 0, 0); __builtin_amdgcn_s_setprio(0); } while (0)
; #define PG8_WAIT_L(n) asm volatile("s_waitcnt lgkmcnt(" #n ")" ::: "memory")
; #define PG8_BAR __builtin_amdgcn_s_barrier()
; #define PG8_SCHED __builtin_amdgcn_sched_barrier(0)
; template <class Epi>
; DI void gemm_phase(LAS unsigned char* lds, const Gemm g, const StaticOrder& S, const Epi& E) {
;     ...
;             const bool last = (t == nt - 2);
;             const char* a1 = cA + (size_t)(t + 1) * kstep;
;             const char* a2 = last ? nA : cA + (size_t)(t + 2) * kstep; const char* b2 = last ? nB : cB + (size_t)(t + 2) * kstep;
;             const char* a3 = a2 + kstep; const char* b3 = b2 + kstep;
;             PG8_LDB(B0, 0, 0); PG8_SCHED; PG8_LDA(At, 0, 0); PG8_STAGE(PG8_SA(1, 1), a1 + hstep, voffA);
;             PG8_WAIT_L(8); PG8_BAR; PG8_WAIT_L(0); PG8_MMA(0, 0, At, B0); PG8_BAR; PG8_SCHED;
;             PG8_LDB(B1, 0, 1); PG8_STAGE(PG8_SB(0, 0), b2, voffB);
;             PG8_BAR; PG8_WAIT_L(0); PG8_MMA(0, 1, At, B1); PG8_BAR;
;             PG8_LDA(At, 0, 1); PG8_STAGE(PG8_SA(0, 0), a2, voffA);
;             PG8_BAR; PG8_WAIT_L(0); PG8_MMA(1, 0, At, B0); PG8_BAR; PG8_SCHED;
.LBB0_1596:
	s_andn2_b64 vcc, exec, s[14:15]
	s_cbranch_vccnz .LBB0_1589
	s_add_u32 s36, s36, 0x80
	s_addc_u32 s37, s37, 0
	s_add_u32 s44, s44, 0x100
	s_addc_u32 s45, s45, 0
	s_mov_b32 s4, 0
	s_mov_b32 s72, 0x10000
	s_mov_b32 s73, 0x14000
	s_mov_b32 s74, 0x18000
	s_mov_b32 s75, 0x1c000
	s_mov_b64 s[76:77], 0x80
	s_add_i32 s5, s4, 2
	s_add_u32 s40, s36, 0x80
	s_addc_u32 s41, s37, 0
	s_add_i32 s79, s72, 0x100
	v_add_u32_e32 v149, s79, v140
	ds_read_b128 v[150:153], v149
	ds_read_b128 v[154:157], v149 offset:1024
	ds_read_b128 v[158:161], v149 offset:2048
	ds_read_b128 v[170:173], v149 offset:3072
	s_cmp_eq_u32 s67, s4
	s_cselect_b32 s41, s17, s41
	s_cselect_b32 s40, s16, s40
	s_cselect_b32 s43, s19, s45
	s_cselect_b32 s42, s18, s44
	v_lshl_add_u64 v[162:163], s[36:37], 0, v[134:135]
	s_add_i32 m0, s58, 0xc000
	ds_read_b128 v[174:177], v141
	ds_read_b128 v[178:181], v141 offset:1024
	ds_read_b128 v[188:191], v141 offset:2048
	ds_read_b128 v[192:195], v141 offset:3072
	ds_read_b128 v[196:199], v141 offset:4096
	ds_read_b128 v[200:203], v141 offset:5120
	ds_read_b128 v[204:207], v141 offset:6144
	ds_read_b128 v[208:211], v141 offset:7168
	global_load_lds_dwordx4 v[162:163], off
	v_lshl_add_u64 v[162:163], s[36:37], 0, v[136:137]
	s_add_i32 m0, s58, 0xe000
	s_nop 0
	global_load_lds_dwordx4 v[162:163], off
	s_waitcnt lgkmcnt(8)
	s_barrier
	s_waitcnt lgkmcnt(0)
	s_setprio 1
	s_waitcnt lgkmcnt(0)
	v_mfma_f32_16x16x32_bf16 v[124:127], v[150:153], v[174:177], 0
	v_mfma_f32_16x16x32_bf16 v[120:123], v[158:161], v[174:177], 0
	v_mfma_f32_16x16x32_bf16 v[108:111], v[150:153], v[188:191], 0
	v_mfma_f32_16x16x32_bf16 v[104:107], v[158:161], v[188:191], 0
	v_mfma_f32_16x16x32_bf16 v[92:95], v[150:153], v[196:199], 0
	v_mfma_f32_16x16x32_bf16 v[88:91], v[158:161], v[196:199], 0
	v_mfma_f32_16x16x32_bf16 v[76:79], v[150:153], v[204:207], 0
	v_mfma_f32_16x16x32_bf16 v[72:75], v[158:161], v[204:207], 0
	v_mfma_f32_16x16x32_bf16 v[124:127], v[154:157], v[178:181], v[124:127]
	v_mfma_f32_16x16x32_bf16 v[120:123], v[170:173], v[178:181], v[120:123]
	v_mfma_f32_16x16x32_bf16 v[108:111], v[154:157], v[192:195], v[108:111]
	v_mfma_f32_16x16x32_bf16 v[104:107], v[170:173], v[192:195], v[104:107]
	v_mfma_f32_16x16x32_bf16 v[92:95], v[154:157], v[200:203], v[92:95]
	v_mfma_f32_16x16x32_bf16 v[88:91], v[170:173], v[200:203], v[88:91]
	v_mfma_f32_16x16x32_bf16 v[76:79], v[154:157], v[208:211], v[76:79]
	v_mfma_f32_16x16x32_bf16 v[72:75], v[170:173], v[208:211], v[72:75]
	s_setprio 0
	s_barrier
	s_add_i32 s4, s73, 0x100
	s_add_i32 s79, s79, s50
	v_add_u32_e32 v149, s4, v140
	v_lshl_add_u64 v[162:163], s[42:43], 0, v[166:167]
	s_mov_b32 m0, s79
	ds_read_b128 v[212:215], v149
	ds_read_b128 v[216:219], v149 offset:1024
	ds_read_b128 v[220:223], v149 offset:2048
	ds_read_b128 v[224:227], v149 offset:3072
	global_load_lds_dwordx4 v[162:163], off
	v_lshl_add_u64 v[182:183], s[42:43], 0, v[128:129]
	s_add_i32 m0, s79, 0x2000
	s_nop 0
	global_load_lds_dwordx4 v[182:183], off
	s_barrier
	s_waitcnt lgkmcnt(0)
	s_setprio 1
	s_waitcnt lgkmcnt(0)
	v_mfma_f32_16x16x32_bf16 v[116:119], v[212:215], v[174:177], 0
	v_mfma_f32_16x16x32_bf16 v[112:115], v[220:223], v[174:177], 0
	v_mfma_f32_16x16x32_bf16 v[100:103], v[212:215], v[188:191], 0
	v_mfma_f32_16x16x32_bf16 v[96:99], v[220:223], v[188:191], 0
	v_mfma_f32_16x16x32_bf16 v[84:87], v[212:215], v[196:199], 0
	v_mfma_f32_16x16x32_bf16 v[80:83], v[220:223], v[196:199], 0
	v_mfma_f32_16x16x32_bf16 v[68:71], v[212:215], v[204:207], 0
	v_mfma_f32_16x16x32_bf16 v[64:67], v[220:223], v[204:207], 0
	v_mfma_f32_16x16x32_bf16 v[116:119], v[216:219], v[178:181], v[116:119]
	v_mfma_f32_16x16x32_bf16 v[112:115], v[224:227], v[178:181], v[112:115]
	v_mfma_f32_16x16x32_bf16 v[100:103], v[216:219], v[192:195], v[100:103]
	v_mfma_f32_16x16x32_bf16 v[96:99], v[224:227], v[192:195], v[96:99]
	v_mfma_f32_16x16x32_bf16 v[84:87], v[216:219], v[200:203], v[84:87]
	v_mfma_f32_16x16x32_bf16 v[80:83], v[224:227], v[200:203], v[80:83]
	v_mfma_f32_16x16x32_bf16 v[68:71], v[216:219], v[208:211], v[68:71]
	v_mfma_f32_16x16x32_bf16 v[64:67], v[224:227], v[208:211], v[64:67]
	s_setprio 0
	s_mov_b32 m0, s58
	v_lshl_add_u64 v[228:229], s[40:41], 0, v[132:133]
	s_barrier
	ds_read_b128 v[174:177], v141 offset:16384
	ds_read_b128 v[178:181], v141 offset:17408
	ds_read_b128 v[188:191], v141 offset:18432
	ds_read_b128 v[192:195], v141 offset:19456
	ds_read_b128 v[196:199], v141 offset:20480
	ds_read_b128 v[200:203], v141 offset:21504
	ds_read_b128 v[204:207], v141 offset:22528
	ds_read_b128 v[208:211], v141 offset:23552
	global_load_lds_dwordx4 v[228:229], off
	v_lshl_add_u64 v[230:231], s[40:41], 0, v[130:131]
	s_mov_b32 m0, s59
	s_nop 0
	global_load_lds_dwordx4 v[230:231], off
	s_barrier
	s_waitcnt lgkmcnt(0)
	s_setprio 1
	s_waitcnt lgkmcnt(0)
	v_mfma_f32_16x16x32_bf16 v[60:63], v[150:153], v[174:177], 0
	v_mfma_f32_16x16x32_bf16 v[56:59], v[158:161], v[174:177], 0
	v_mfma_f32_16x16x32_bf16 v[44:47], v[150:153], v[188:191], 0
	v_mfma_f32_16x16x32_bf16 v[40:43], v[158:161], v[188:191], 0
	v_mfma_f32_16x16x32_bf16 v[28:31], v[150:153], v[196:199], 0
	v_mfma_f32_16x16x32_bf16 v[24:27], v[158:161], v[196:199], 0
	v_mfma_f32_16x16x32_bf16 v[12:15], v[150:153], v[204:207], 0
	v_mfma_f32_16x16x32_bf16 v[8:11], v[158:161], v[204:207], 0
	v_mfma_f32_16x16x32_bf16 v[60:63], v[154:157], v[178:181], v[60:63]
	v_mfma_f32_16x16x32_bf16 v[56:59], v[170:173], v[178:181], v[56:59]
	v_mfma_f32_16x16x32_bf16 v[44:47], v[154:157], v[192:195], v[44:47]
	v_mfma_f32_16x16x32_bf16 v[40:43], v[170:173], v[192:195], v[40:43]
	v_mfma_f32_16x16x32_bf16 v[28:31], v[154:157], v[200:203], v[28:31]
	v_mfma_f32_16x16x32_bf16 v[24:27], v[170:173], v[200:203], v[24:27]
	v_mfma_f32_16x16x32_bf16 v[12:15], v[154:157], v[208:211], v[12:15]
	v_mfma_f32_16x16x32_bf16 v[8:11], v[170:173], v[208:211], v[8:11]
	s_setprio 0
	s_barrier
; #define PG8_STAGE(bufoff, gbase, voff) do { _Pragma("unroll") for (int _i = 0; _i < 2; ++_i) \
;         __builtin_amdgcn_global_load_lds((const unsigned*)((const char*)(gbase) + (voff)[_i]), (LAS unsigned*)(lds + (bufoff) + ldsw + _i * 8192), 16, 0, 0); } while (0)
; #define PG8_LDA(dst, b, h) do { _Pragma("unroll") for (int m = 0; m < 4; ++m) _Pragma("unroll") for (int k = 0; k < 2; ++k) dst[m][k] = *(const LAS bf16x8*)(lds + PG8_SA(b, h) + aoff + m * 2048 + k * 1024); } while (0)
; #define PG8_LDB(dst, b, h) do { _Pragma("unroll") for (int n = 0; n < 2; ++n) _Pragma("unroll") for (int k = 0; k < 2; ++k) dst[n][k] = *(const LAS bf16x8*)(lds + PG8_SB(b, h) + boff + n * 2048 + k * 1024); } while (0)
; #define PG8_MMA(ai, bj, At, Bt) do { __builtin_amdgcn_s_setprio(1); _Pragma("unroll") for (int m = 0; m < 4; ++m) _Pragma("unroll") for (int n = 0; n < 2; ++n) _Pragma("unroll") for (int k = 0; k < 2; ++k) \
;         acc[ai][bj][m][n] = __builtin_amdgcn_mfma_f32_16x16x32_bf16(Bt[n][k], At[m][k], acc[ai][bj][m][n], 0, 0, 0); __builtin_amdgcn_s_setprio(0); } while (0)
; #define PG8_WAIT_V(n) asm volatile("s_waitcnt vmcnt(" #n ")" ::: "memory")
; #define PG8_WAIT_L(n) asm volatile("s_waitcnt lgkmcnt(" #n ")" ::: "memory")
; #define PG8_BAR __builtin_amdgcn_s_barrier()
; #define PG8_SCHED __builtin_amdgcn_sched_barrier(0)
; template <class Epi>
; DI void gemm_phase(LAS unsigned char* lds, const Gemm g, const StaticOrder& S, const Epi& E) {
;     ...
;             PG8_STAGE(PG8_SB(0, 1), b2 + hstep, voffB);
;             PG8_WAIT_V(6); PG8_BAR; PG8_MMA(1, 1, At, B1); PG8_BAR;
;             PG8_LDB(B0, 1, 0); PG8_SCHED; PG8_LDA(At, 1, 0); PG8_STAGE(PG8_SA(0, 1), a2 + hstep, voffA);
;             PG8_WAIT_L(8); PG8_BAR; PG8_WAIT_L(0); PG8_MMA(0, 0, At, B0); PG8_BAR; PG8_SCHED;
;             PG8_LDB(B1, 1, 1); PG8_STAGE(PG8_SB(1, 0), b3, voffB);
	s_add_u32 s42, s42, s10
	s_addc_u32 s43, s43, s11
	s_add_i32 s4, s4, s50
	v_lshl_add_u64 v[232:233], s[42:43], 0, v[166:167]
	s_mov_b32 m0, s4
	v_lshl_add_u64 v[234:235], s[42:43], 0, v[128:129]
	global_load_lds_dwordx4 v[232:233], off
	s_add_i32 m0, s4, 0x2000
	s_nop 0
	global_load_lds_dwordx4 v[234:235], off
	s_waitcnt vmcnt(6)
	s_barrier
	s_setprio 1
	v_mfma_f32_16x16x32_bf16 v[52:55], v[212:215], v[174:177], 0
	v_mfma_f32_16x16x32_bf16 v[48:51], v[220:223], v[174:177], 0
	v_mfma_f32_16x16x32_bf16 v[36:39], v[212:215], v[188:191], 0
	v_mfma_f32_16x16x32_bf16 v[32:35], v[220:223], v[188:191], 0
	v_mfma_f32_16x16x32_bf16 v[20:23], v[212:215], v[196:199], 0
	v_mfma_f32_16x16x32_bf16 v[16:19], v[220:223], v[196:199], 0
	v_mfma_f32_16x16x32_bf16 v[4:7], v[212:215], v[204:207], 0
	v_mfma_f32_16x16x32_bf16 v[0:3], v[220:223], v[204:207], 0
	v_mfma_f32_16x16x32_bf16 v[52:55], v[216:219], v[178:181], v[52:55]
	v_mfma_f32_16x16x32_bf16 v[48:51], v[224:227], v[178:181], v[48:51]
	v_mfma_f32_16x16x32_bf16 v[36:39], v[216:219], v[192:195], v[36:39]
	v_mfma_f32_16x16x32_bf16 v[32:35], v[224:227], v[192:195], v[32:35]
	v_mfma_f32_16x16x32_bf16 v[20:23], v[216:219], v[200:203], v[20:23]
	v_mfma_f32_16x16x32_bf16 v[16:19], v[224:227], v[200:203], v[16:19]
	v_mfma_f32_16x16x32_bf16 v[4:7], v[216:219], v[208:211], v[4:7]
	v_mfma_f32_16x16x32_bf16 v[0:3], v[224:227], v[208:211], v[0:3]
	s_setprio 0
	s_add_i32 s4, s74, 0x100
	v_add_u32_e32 v149, s4, v140
	s_barrier
	ds_read_b128 v[150:153], v149
	ds_read_b128 v[154:157], v149 offset:1024
	ds_read_b128 v[158:161], v149 offset:2048
	ds_read_b128 v[170:173], v149 offset:3072
	s_add_u32 s40, s40, s10
	s_addc_u32 s41, s41, s11
	s_mov_b32 m0, s60
	v_lshl_add_u64 v[212:213], s[40:41], 0, v[132:133]
	ds_read_b128 v[174:177], v141 offset:32768
	ds_read_b128 v[178:181], v141 offset:33792
	ds_read_b128 v[188:191], v141 offset:34816
	ds_read_b128 v[192:195], v141 offset:35840
	ds_read_b128 v[196:199], v141 offset:36864
	ds_read_b128 v[200:203], v141 offset:37888
	ds_read_b128 v[204:207], v141 offset:38912
	ds_read_b128 v[208:211], v141 offset:39936
	global_load_lds_dwordx4 v[212:213], off
	v_lshl_add_u64 v[212:213], s[40:41], 0, v[130:131]
	s_mov_b32 m0, s61
	s_nop 0
	global_load_lds_dwordx4 v[212:213], off
	s_waitcnt lgkmcnt(8)
	s_barrier
	s_waitcnt lgkmcnt(0)
	s_setprio 1
	s_waitcnt lgkmcnt(0)
	v_mfma_f32_16x16x32_bf16 v[124:127], v[150:153], v[174:177], v[124:127]
	v_mfma_f32_16x16x32_bf16 v[120:123], v[158:161], v[174:177], v[120:123]
	v_mfma_f32_16x16x32_bf16 v[108:111], v[150:153], v[188:191], v[108:111]
	v_mfma_f32_16x16x32_bf16 v[104:107], v[158:161], v[188:191], v[104:107]
	v_mfma_f32_16x16x32_bf16 v[92:95], v[150:153], v[196:199], v[92:95]
	v_mfma_f32_16x16x32_bf16 v[88:91], v[158:161], v[196:199], v[88:91]
	v_mfma_f32_16x16x32_bf16 v[76:79], v[150:153], v[204:207], v[76:79]
	v_mfma_f32_16x16x32_bf16 v[72:75], v[158:161], v[204:207], v[72:75]
	v_mfma_f32_16x16x32_bf16 v[124:127], v[154:157], v[178:181], v[124:127]
	v_mfma_f32_16x16x32_bf16 v[120:123], v[170:173], v[178:181], v[120:123]
	v_mfma_f32_16x16x32_bf16 v[108:111], v[154:157], v[192:195], v[108:111]
	v_mfma_f32_16x16x32_bf16 v[104:107], v[170:173], v[192:195], v[104:107]
	v_mfma_f32_16x16x32_bf16 v[92:95], v[154:157], v[200:203], v[92:95]
	v_mfma_f32_16x16x32_bf16 v[88:91], v[170:173], v[200:203], v[88:91]
	v_mfma_f32_16x16x32_bf16 v[76:79], v[154:157], v[208:211], v[76:79]
	v_mfma_f32_16x16x32_bf16 v[72:75], v[170:173], v[208:211], v[72:75]
	s_setprio 0
	s_barrier
	s_add_i32 s40, s75, 0x100
	s_add_i32 s4, s4, s50
	v_add_u32_e32 v149, s40, v140
	v_lshl_add_u64 v[162:163], v[162:163], 0, s[76:77]
	s_mov_b32 m0, s4
	ds_read_b128 v[212:215], v149
	ds_read_b128 v[216:219], v149 offset:1024
	ds_read_b128 v[220:223], v149 offset:2048
	ds_read_b128 v[224:227], v149 offset:3072
	global_load_lds_dwordx4 v[162:163], off
	v_lshl_add_u64 v[162:163], v[182:183], 0, s[76:77]
	s_add_i32 m0, s4, 0x2000
	s_nop 0
	global_load_lds_dwordx4 v[162:163], off
	s_barrier
; #define PG8_STAGE(bufoff, gbase, voff) do { _Pragma("unroll") for (int _i = 0; _i < 2; ++_i) \
;         __builtin_amdgcn_global_load_lds((const unsigned*)((const char*)(gbase) + (voff)[_i]), (LAS unsigned*)(lds + (bufoff) + ldsw + _i * 8192), 16, 0, 0); } while (0)
; #define PG8_LDA(dst, b, h) do { _Pragma("unroll") for (int m = 0; m < 4; ++m) _Pragma("unroll") for (int k = 0; k < 2; ++k) dst[m][k] = *(const LAS bf16x8*)(lds + PG8_SA(b, h) + aoff + m * 2048 + k * 1024); } while (0)
; #define PG8_MMA(ai, bj, At, Bt) do { __builtin_amdgcn_s_setprio(1); _Pragma("unroll") for (int m = 0; m < 4; ++m) _Pragma("unroll") for (int n = 0; n < 2; ++n) _Pragma("unroll") for (int k = 0; k < 2; ++k) \
;         acc[ai][bj][m][n] = __builtin_amdgcn_mfma_f32_16x16x32_bf16(Bt[n][k], At[m][k], acc[ai][bj][m][n], 0, 0, 0); __builtin_amdgcn_s_setprio(0); } while (0)
; #define PG8_WAIT_V(n) asm volatile("s_waitcnt vmcnt(" #n ")" ::: "memory")
; #define PG8_WAIT_L(n) asm volatile("s_waitcnt lgkmcnt(" #n ")" ::: "memory")
; #define PG8_BAR __builtin_amdgcn_s_barrier()
; #define PG8_SCHED __builtin_amdgcn_sched_barrier(0)
; template <class Epi>
; DI void gemm_phase(LAS unsigned char* lds, const Gemm g, const StaticOrder& S, const Epi& E) {
;     ...
;             PG8_BAR; PG8_WAIT_L(0); PG8_MMA(0, 1, At, B1); PG8_BAR;
;             PG8_LDA(At, 1, 1); PG8_STAGE(PG8_SA(1, 0), a3, voffA);
;             PG8_BAR; PG8_WAIT_L(0); PG8_MMA(1, 0, At, B0); PG8_BAR; PG8_SCHED;
;             PG8_STAGE(PG8_SB(1, 1), b3 + hstep, voffB);
;             PG8_WAIT_V(6); PG8_BAR; PG8_MMA(1, 1, At, B1); PG8_BAR;
	s_waitcnt lgkmcnt(0)
	s_setprio 1
	s_waitcnt lgkmcnt(0)
	v_mfma_f32_16x16x32_bf16 v[116:119], v[212:215], v[174:177], v[116:119]
	v_mfma_f32_16x16x32_bf16 v[112:115], v[220:223], v[174:177], v[112:115]
	v_mfma_f32_16x16x32_bf16 v[100:103], v[212:215], v[188:191], v[100:103]
	v_mfma_f32_16x16x32_bf16 v[96:99], v[220:223], v[188:191], v[96:99]
	v_mfma_f32_16x16x32_bf16 v[84:87], v[212:215], v[196:199], v[84:87]
	v_mfma_f32_16x16x32_bf16 v[80:83], v[220:223], v[196:199], v[80:83]
	v_mfma_f32_16x16x32_bf16 v[68:71], v[212:215], v[204:207], v[68:71]
	v_mfma_f32_16x16x32_bf16 v[64:67], v[220:223], v[204:207], v[64:67]
	v_mfma_f32_16x16x32_bf16 v[116:119], v[216:219], v[178:181], v[116:119]
	v_mfma_f32_16x16x32_bf16 v[112:115], v[224:227], v[178:181], v[112:115]
	v_mfma_f32_16x16x32_bf16 v[100:103], v[216:219], v[192:195], v[100:103]
	v_mfma_f32_16x16x32_bf16 v[96:99], v[224:227], v[192:195], v[96:99]
	v_mfma_f32_16x16x32_bf16 v[84:87], v[216:219], v[200:203], v[84:87]
	v_mfma_f32_16x16x32_bf16 v[80:83], v[224:227], v[200:203], v[80:83]
	v_mfma_f32_16x16x32_bf16 v[68:71], v[216:219], v[208:211], v[68:71]
	v_mfma_f32_16x16x32_bf16 v[64:67], v[224:227], v[208:211], v[64:67]
	s_setprio 0
	s_mov_b32 m0, s65
	v_lshl_add_u64 v[162:163], v[228:229], 0, s[76:77]
	s_barrier
	ds_read_b128 v[174:177], v141 offset:49152
	ds_read_b128 v[178:181], v141 offset:50176
	ds_read_b128 v[188:191], v141 offset:51200
	ds_read_b128 v[192:195], v141 offset:52224
	ds_read_b128 v[196:199], v141 offset:53248
	ds_read_b128 v[200:203], v141 offset:54272
	ds_read_b128 v[204:207], v141 offset:55296
	ds_read_b128 v[208:211], v141 offset:56320
	global_load_lds_dwordx4 v[162:163], off
	v_lshl_add_u64 v[162:163], v[230:231], 0, s[76:77]
	s_mov_b32 m0, s66
	s_nop 0
	global_load_lds_dwordx4 v[162:163], off
	s_barrier
	s_waitcnt lgkmcnt(0)
	s_setprio 1
	s_waitcnt lgkmcnt(0)
	v_mfma_f32_16x16x32_bf16 v[60:63], v[150:153], v[174:177], v[60:63]
	v_mfma_f32_16x16x32_bf16 v[56:59], v[158:161], v[174:177], v[56:59]
	v_mfma_f32_16x16x32_bf16 v[44:47], v[150:153], v[188:191], v[44:47]
	v_mfma_f32_16x16x32_bf16 v[40:43], v[158:161], v[188:191], v[40:43]
	v_mfma_f32_16x16x32_bf16 v[28:31], v[150:153], v[196:199], v[28:31]
	v_mfma_f32_16x16x32_bf16 v[24:27], v[158:161], v[196:199], v[24:27]
	v_mfma_f32_16x16x32_bf16 v[12:15], v[150:153], v[204:207], v[12:15]
	v_mfma_f32_16x16x32_bf16 v[8:11], v[158:161], v[204:207], v[8:11]
	v_mfma_f32_16x16x32_bf16 v[60:63], v[154:157], v[178:181], v[60:63]
	v_mfma_f32_16x16x32_bf16 v[56:59], v[170:173], v[178:181], v[56:59]
	v_mfma_f32_16x16x32_bf16 v[44:47], v[154:157], v[192:195], v[44:47]
	v_mfma_f32_16x16x32_bf16 v[40:43], v[170:173], v[192:195], v[40:43]
	v_mfma_f32_16x16x32_bf16 v[28:31], v[154:157], v[200:203], v[28:31]
	v_mfma_f32_16x16x32_bf16 v[24:27], v[170:173], v[200:203], v[24:27]
	v_mfma_f32_16x16x32_bf16 v[12:15], v[154:157], v[208:211], v[12:15]
	v_mfma_f32_16x16x32_bf16 v[8:11], v[170:173], v[208:211], v[8:11]
	s_setprio 0
	s_barrier
	s_add_i32 s4, s40, s50
	v_lshl_add_u64 v[150:151], v[232:233], 0, s[76:77]
	s_mov_b32 m0, s4
	s_nop 0
	global_load_lds_dwordx4 v[150:151], off
	v_lshl_add_u64 v[150:151], v[234:235], 0, s[76:77]
	s_add_i32 m0, s4, 0x2000
	s_nop 0
	global_load_lds_dwordx4 v[150:151], off
	s_waitcnt vmcnt(6)
	s_barrier
	s_setprio 1
	v_mfma_f32_16x16x32_bf16 v[52:55], v[212:215], v[174:177], v[52:55]
	v_mfma_f32_16x16x32_bf16 v[48:51], v[220:223], v[174:177], v[48:51]
	v_mfma_f32_16x16x32_bf16 v[36:39], v[212:215], v[188:191], v[36:39]
	v_mfma_f32_16x16x32_bf16 v[32:35], v[220:223], v[188:191], v[32:35]
	v_mfma_f32_16x16x32_bf16 v[20:23], v[212:215], v[196:199], v[20:23]
	v_mfma_f32_16x16x32_bf16 v[16:19], v[220:223], v[196:199], v[16:19]
	v_mfma_f32_16x16x32_bf16 v[4:7], v[212:215], v[204:207], v[4:7]
	v_mfma_f32_16x16x32_bf16 v[0:3], v[220:223], v[204:207], v[0:3]
	v_mfma_f32_16x16x32_bf16 v[52:55], v[216:219], v[178:181], v[52:55]
	v_mfma_f32_16x16x32_bf16 v[48:51], v[224:227], v[178:181], v[48:51]
	v_mfma_f32_16x16x32_bf16 v[36:39], v[216:219], v[192:195], v[36:39]
	v_mfma_f32_16x16x32_bf16 v[32:35], v[224:227], v[192:195], v[32:35]
	v_mfma_f32_16x16x32_bf16 v[20:23], v[216:219], v[200:203], v[20:23]
	v_mfma_f32_16x16x32_bf16 v[16:19], v[224:227], v[200:203], v[16:19]
	v_mfma_f32_16x16x32_bf16 v[4:7], v[216:219], v[208:211], v[4:7]
	v_mfma_f32_16x16x32_bf16 v[0:3], v[224:227], v[208:211], v[0:3]
	s_setprio 0
	s_add_u32 s36, s36, 0x100
	s_addc_u32 s37, s37, 0
	s_add_u32 s44, s44, 0x100
	s_addc_u32 s45, s45, 0
	s_cmp_ge_i32 s5, s62
	s_mov_b32 s4, s5
	s_barrier
	s_cbranch_scc0 .LBB0_1598
	s_branch .Lpeel_exit_5

; #define PG8_STAGE(bufoff, gbase, voff) do { _Pragma("unroll") for (int _i = 0; _i < 2; ++_i) \
;         __builtin_amdgcn_global_load_lds((const unsigned*)((const char*)(gbase) + (voff)[_i]), (LAS unsigned*)(lds + (bufoff) + ldsw + _i * 8192), 16, 0, 0); } while (0)
; #define PG8_LDA(dst, b, h) do { _Pragma("unroll") for (int m = 0; m < 4; ++m) _Pragma("unroll") for (int k = 0; k < 2; ++k) dst[m][k] = *(const LAS bf16x8*)(lds + PG8_SA(b, h) + aoff + m * 2048 + k * 1024); } while (0)
; #define PG8_WAIT_V(n) asm volatile("s_waitcnt vmcnt(" #n ")" ::: "memory")
; #define PG8_BAR __builtin_amdgcn_s_barrier()
; template <class Epi>
; DI void gemm_phase(LAS unsigned char* lds, const Gemm g, const StaticOrder& S, const Epi& E) {
;     ...
;         for (int t = 0; t < nt; t += 2) {
;             const bool last = (t == nt - 2);
;             const char* a1 = cA + (size_t)(t + 1) * kstep;
;             const char* a2 = last ? nA : cA + (size_t)(t + 2) * kstep; const char* b2 = last ? nB : cB + (size_t)(t + 2) * kstep;
;             const char* a3 = a2 + kstep; const char* b3 = b2 + kstep;
;             PG8_LDB(B0, 0, 0); PG8_SCHED; PG8_LDA(At, 0, 0); PG8_STAGE(PG8_SA(1, 1), a1 + hstep, voffA);
;             PG8_WAIT_L(8); PG8_BAR; PG8_WAIT_L(0); PG8_MMA(0, 0, At, B0); PG8_BAR; PG8_SCHED;
;             PG8_LDB(B1, 0, 1); PG8_STAGE(PG8_SB(0, 0), b2, voffB);
;             PG8_BAR; PG8_WAIT_L(0); PG8_MMA(0, 1, At, B1); PG8_BAR;
;             PG8_LDA(At, 0, 1); PG8_STAGE(PG8_SA(0, 0), a2, voffA);
;             PG8_BAR; PG8_WAIT_L(0); PG8_MMA(1, 0, At, B0); PG8_BAR; PG8_SCHED;
;             PG8_STAGE(PG8_SB(0, 1), b2 + hstep, voffB);
;             PG8_WAIT_V(6); PG8_BAR; PG8_MMA(1, 1, At, B1); PG8_BAR;
;             PG8_LDB(B0, 1, 0); PG8_SCHED; PG8_LDA(At, 1, 0); PG8_STAGE(PG8_SA(0, 1), a2 + hstep, voffA);
;             PG8_WAIT_L(8); PG8_BAR; PG8_WAIT_L(0); PG8_MMA(0, 0, At, B0); PG8_BAR; PG8_SCHED;
;             PG8_LDB(B1, 1, 1); PG8_STAGE(PG8_SB(1, 0), b3, voffB);
;             PG8_BAR; PG8_WAIT_L(0); PG8_MMA(0, 1, At, B1); PG8_BAR;
;             PG8_LDA(At, 1, 1); PG8_STAGE(PG8_SA(1, 0), a3, voffA);
;             PG8_BAR; PG8_WAIT_L(0); PG8_MMA(1, 0, At, B0); PG8_BAR; PG8_SCHED;
;             PG8_STAGE(PG8_SB(1, 1), b3 + hstep, voffB);
;             PG8_WAIT_V(6); PG8_BAR; PG8_MMA(1, 1, At, B1); PG8_BAR;
;         }
;         E(acc, cur, wr, wc, fr, fq);
.Lpeel_exit_5:
	s_mov_b32 s77, 0x18000
	s_mov_b32 s76, 0x10000
	s_mov_b32 s79, 0x8000
	s_branch .LBB0_1589

; #define PG8_STAGE(bufoff, gbase, voff) do { _Pragma("unroll") for (int _i = 0; _i < 2; ++_i) \
;         __builtin_amdgcn_global_load_lds((const unsigned*)((const char*)(gbase) + (voff)[_i]), (LAS unsigned*)(lds + (bufoff) + ldsw + _i * 8192), 16, 0, 0); } while (0)
; #define PG8_LDA(dst, b, h) do { _Pragma("unroll") for (int m = 0; m < 4; ++m) _Pragma("unroll") for (int k = 0; k < 2; ++k) dst[m][k] = *(const LAS bf16x8*)(lds + PG8_SA(b, h) + aoff + m * 2048 + k * 1024); } while (0)
; #define PG8_LDB(dst, b, h) do { _Pragma("unroll") for (int n = 0; n < 2; ++n) _Pragma("unroll") for (int k = 0; k < 2; ++k) dst[n][k] = *(const LAS bf16x8*)(lds + PG8_SB(b, h) + boff + n * 2048 + k * 1024); } while (0)
; #define PG8_MMA(ai, bj, At, Bt) do { __builtin_amdgcn_s_setprio(1); _Pragma("unroll") for (int m = 0; m < 4; ++m) _Pragma("unroll") for (int n = 0; n < 2; ++n) _Pragma("unroll") for (int k = 0; k < 2; ++k) \
;         acc[ai][bj][m][n] = __builtin_amdgcn_mfma_f32_16x16x32_bf16(Bt[n][k], At[m][k], acc[ai][bj][m][n], 0, 0, 0); __builtin_amdgcn_s_setprio(0); } while (0)
; #define PG8_WAIT_L(n) asm volatile("s_waitcnt lgkmcnt(" #n ")" ::: "memory")
; #define PG8_BAR __builtin_amdgcn_s_barrier()
; #define PG8_SCHED __builtin_amdgcn_sched_barrier(0)
; template <class Epi>
; DI void gemm_phase(LAS unsigned char* lds, const Gemm g, const StaticOrder& S, const Epi& E) {
;     ...
;             const bool last = (t == nt - 2);
;             const char* a1 = cA + (size_t)(t + 1) * kstep;
;             const char* a2 = last ? nA : cA + (size_t)(t + 2) * kstep; const char* b2 = last ? nB : cB + (size_t)(t + 2) * kstep;
;             const char* a3 = a2 + kstep; const char* b3 = b2 + kstep;
;             PG8_LDB(B0, 0, 0); PG8_SCHED; PG8_LDA(At, 0, 0); PG8_STAGE(PG8_SA(1, 1), a1 + hstep, voffA);
;             PG8_WAIT_L(8); PG8_BAR; PG8_WAIT_L(0); PG8_MMA(0, 0, At, B0); PG8_BAR; PG8_SCHED;
;             PG8_LDB(B1, 0, 1); PG8_STAGE(PG8_SB(0, 0), b2, voffB);
;             PG8_BAR; PG8_WAIT_L(0); PG8_MMA(0, 1, At, B1); PG8_BAR;
;             PG8_LDA(At, 0, 1); PG8_STAGE(PG8_SA(0, 0), a2, voffA);
;             PG8_BAR; PG8_WAIT_L(0); PG8_MMA(1, 0, At, B0); PG8_BAR; PG8_SCHED;
.LBB0_1668:
	s_andn2_b64 vcc, exec, s[16:17]
	s_cbranch_vccnz .LBB0_1671
	s_add_u32 s40, s46, 0x80
	s_addc_u32 s41, s47, 0
	s_add_u32 s0, s44, 0x100
	s_addc_u32 s46, s45, 0
	s_mov_b32 s4, 0
	s_mov_b32 s72, 0x10000
	s_mov_b32 s73, 0x14000
	s_mov_b32 s74, 0x18000
	s_mov_b32 s75, 0x1c000
	s_mov_b64 s[76:77], 0x80
	s_add_i32 s5, s4, 2
	s_add_u32 s42, s40, 0x80
	s_addc_u32 s43, s41, 0
	s_add_i32 s47, s72, 0x100
	v_add_u32_e32 v153, s47, v151
	ds_read_b128 v[138:141], v153
	ds_read_b128 v[154:157], v153 offset:1024
	ds_read_b128 v[158:161], v153 offset:2048
	ds_read_b128 v[170:173], v153 offset:3072
	s_cmp_eq_u32 s64, s4
	s_cselect_b32 s43, s19, s43
	s_cselect_b32 s42, s18, s42
	s_cselect_b32 s45, s37, s46
	s_cselect_b32 s44, s36, s0
	v_lshl_add_u64 v[162:163], s[40:41], 0, v[134:135]
	s_add_i32 m0, s54, 0xc000
	ds_read_b128 v[174:177], v152
	ds_read_b128 v[178:181], v152 offset:1024
	ds_read_b128 v[188:191], v152 offset:2048
	ds_read_b128 v[192:195], v152 offset:3072
	ds_read_b128 v[196:199], v152 offset:4096
	ds_read_b128 v[200:203], v152 offset:5120
	ds_read_b128 v[204:207], v152 offset:6144
	ds_read_b128 v[208:211], v152 offset:7168
	global_load_lds_dwordx4 v[162:163], off
	v_lshl_add_u64 v[162:163], s[40:41], 0, v[136:137]
	s_add_i32 m0, s54, 0xe000
	s_nop 0
	global_load_lds_dwordx4 v[162:163], off
	s_waitcnt lgkmcnt(8)
	s_barrier
	s_waitcnt lgkmcnt(0)
	s_setprio 1
	s_waitcnt lgkmcnt(0)
	v_mfma_f32_16x16x32_bf16 v[124:127], v[138:141], v[174:177], 0
	v_mfma_f32_16x16x32_bf16 v[120:123], v[158:161], v[174:177], 0
	v_mfma_f32_16x16x32_bf16 v[108:111], v[138:141], v[188:191], 0
	v_mfma_f32_16x16x32_bf16 v[104:107], v[158:161], v[188:191], 0
	v_mfma_f32_16x16x32_bf16 v[92:95], v[138:141], v[196:199], 0
	v_mfma_f32_16x16x32_bf16 v[88:91], v[158:161], v[196:199], 0
	v_mfma_f32_16x16x32_bf16 v[76:79], v[138:141], v[204:207], 0
	v_mfma_f32_16x16x32_bf16 v[72:75], v[158:161], v[204:207], 0
	v_mfma_f32_16x16x32_bf16 v[124:127], v[154:157], v[178:181], v[124:127]
	v_mfma_f32_16x16x32_bf16 v[120:123], v[170:173], v[178:181], v[120:123]
	v_mfma_f32_16x16x32_bf16 v[108:111], v[154:157], v[192:195], v[108:111]
	v_mfma_f32_16x16x32_bf16 v[104:107], v[170:173], v[192:195], v[104:107]
	v_mfma_f32_16x16x32_bf16 v[92:95], v[154:157], v[200:203], v[92:95]
	v_mfma_f32_16x16x32_bf16 v[88:91], v[170:173], v[200:203], v[88:91]
	v_mfma_f32_16x16x32_bf16 v[76:79], v[154:157], v[208:211], v[76:79]
	v_mfma_f32_16x16x32_bf16 v[72:75], v[170:173], v[208:211], v[72:75]
	s_setprio 0
	s_barrier
	s_add_i32 s4, s73, 0x100
	s_add_i32 s47, s47, s53
	v_add_u32_e32 v153, s4, v151
	v_lshl_add_u64 v[162:163], s[44:45], 0, v[166:167]
	s_mov_b32 m0, s47
	ds_read_b128 v[212:215], v153
	ds_read_b128 v[216:219], v153 offset:1024
	ds_read_b128 v[220:223], v153 offset:2048
	ds_read_b128 v[224:227], v153 offset:3072
	global_load_lds_dwordx4 v[162:163], off
	v_lshl_add_u64 v[182:183], s[44:45], 0, v[132:133]
	s_add_i32 m0, s47, 0x2000
	s_nop 0
	global_load_lds_dwordx4 v[182:183], off
	s_barrier
	s_waitcnt lgkmcnt(0)
	s_setprio 1
	s_waitcnt lgkmcnt(0)
	v_mfma_f32_16x16x32_bf16 v[116:119], v[212:215], v[174:177], 0
	v_mfma_f32_16x16x32_bf16 v[112:115], v[220:223], v[174:177], 0
	v_mfma_f32_16x16x32_bf16 v[100:103], v[212:215], v[188:191], 0
	v_mfma_f32_16x16x32_bf16 v[96:99], v[220:223], v[188:191], 0
	v_mfma_f32_16x16x32_bf16 v[84:87], v[212:215], v[196:199], 0
	v_mfma_f32_16x16x32_bf16 v[80:83], v[220:223], v[196:199], 0
	v_mfma_f32_16x16x32_bf16 v[68:71], v[212:215], v[204:207], 0
	v_mfma_f32_16x16x32_bf16 v[64:67], v[220:223], v[204:207], 0
	v_mfma_f32_16x16x32_bf16 v[116:119], v[216:219], v[178:181], v[116:119]
	v_mfma_f32_16x16x32_bf16 v[112:115], v[224:227], v[178:181], v[112:115]
	v_mfma_f32_16x16x32_bf16 v[100:103], v[216:219], v[192:195], v[100:103]
	v_mfma_f32_16x16x32_bf16 v[96:99], v[224:227], v[192:195], v[96:99]
	v_mfma_f32_16x16x32_bf16 v[84:87], v[216:219], v[200:203], v[84:87]
	v_mfma_f32_16x16x32_bf16 v[80:83], v[224:227], v[200:203], v[80:83]
	v_mfma_f32_16x16x32_bf16 v[68:71], v[216:219], v[208:211], v[68:71]
	v_mfma_f32_16x16x32_bf16 v[64:67], v[224:227], v[208:211], v[64:67]
	s_setprio 0
	s_mov_b32 m0, s54
	v_lshl_add_u64 v[228:229], s[42:43], 0, v[128:129]
	s_barrier
	ds_read_b128 v[174:177], v152 offset:16384
	ds_read_b128 v[178:181], v152 offset:17408
	ds_read_b128 v[188:191], v152 offset:18432
	ds_read_b128 v[192:195], v152 offset:19456
	ds_read_b128 v[196:199], v152 offset:20480
	ds_read_b128 v[200:203], v152 offset:21504
	ds_read_b128 v[204:207], v152 offset:22528
	ds_read_b128 v[208:211], v152 offset:23552
	global_load_lds_dwordx4 v[228:229], off
	v_lshl_add_u64 v[230:231], s[42:43], 0, v[130:131]
	s_mov_b32 m0, s55
	s_nop 0
	global_load_lds_dwordx4 v[230:231], off
	s_barrier
	s_waitcnt lgkmcnt(0)
	s_setprio 1
	s_waitcnt lgkmcnt(0)
	v_mfma_f32_16x16x32_bf16 v[60:63], v[138:141], v[174:177], 0
	v_mfma_f32_16x16x32_bf16 v[56:59], v[158:161], v[174:177], 0
	v_mfma_f32_16x16x32_bf16 v[44:47], v[138:141], v[188:191], 0
	v_mfma_f32_16x16x32_bf16 v[40:43], v[158:161], v[188:191], 0
	v_mfma_f32_16x16x32_bf16 v[28:31], v[138:141], v[196:199], 0
	v_mfma_f32_16x16x32_bf16 v[24:27], v[158:161], v[196:199], 0
	v_mfma_f32_16x16x32_bf16 v[12:15], v[138:141], v[204:207], 0
	v_mfma_f32_16x16x32_bf16 v[8:11], v[158:161], v[204:207], 0
	v_mfma_f32_16x16x32_bf16 v[60:63], v[154:157], v[178:181], v[60:63]
	v_mfma_f32_16x16x32_bf16 v[56:59], v[170:173], v[178:181], v[56:59]
	v_mfma_f32_16x16x32_bf16 v[44:47], v[154:157], v[192:195], v[44:47]
	v_mfma_f32_16x16x32_bf16 v[40:43], v[170:173], v[192:195], v[40:43]
	v_mfma_f32_16x16x32_bf16 v[28:31], v[154:157], v[200:203], v[28:31]
	v_mfma_f32_16x16x32_bf16 v[24:27], v[170:173], v[200:203], v[24:27]
	v_mfma_f32_16x16x32_bf16 v[12:15], v[154:157], v[208:211], v[12:15]
	v_mfma_f32_16x16x32_bf16 v[8:11], v[170:173], v[208:211], v[8:11]
	s_setprio 0
	s_barrier
; #define PG8_STAGE(bufoff, gbase, voff) do { _Pragma("unroll") for (int _i = 0; _i < 2; ++_i) \
;         __builtin_amdgcn_global_load_lds((const unsigned*)((const char*)(gbase) + (voff)[_i]), (LAS unsigned*)(lds + (bufoff) + ldsw + _i * 8192), 16, 0, 0); } while (0)
; #define PG8_LDA(dst, b, h) do { _Pragma("unroll") for (int m = 0; m < 4; ++m) _Pragma("unroll") for (int k = 0; k < 2; ++k) dst[m][k] = *(const LAS bf16x8*)(lds + PG8_SA(b, h) + aoff + m * 2048 + k * 1024); } while (0)
; #define PG8_LDB(dst, b, h) do { _Pragma("unroll") for (int n = 0; n < 2; ++n) _Pragma("unroll") for (int k = 0; k < 2; ++k) dst[n][k] = *(const LAS bf16x8*)(lds + PG8_SB(b, h) + boff + n * 2048 + k * 1024); } while (0)
; #define PG8_MMA(ai, bj, At, Bt) do { __builtin_amdgcn_s_setprio(1); _Pragma("unroll") for (int m = 0; m < 4; ++m) _Pragma("unroll") for (int n = 0; n < 2; ++n) _Pragma("unroll") for (int k = 0; k < 2; ++k) \
;         acc[ai][bj][m][n] = __builtin_amdgcn_mfma_f32_16x16x32_bf16(Bt[n][k], At[m][k], acc[ai][bj][m][n], 0, 0, 0); __builtin_amdgcn_s_setprio(0); } while (0)
; #define PG8_WAIT_V(n) asm volatile("s_waitcnt vmcnt(" #n ")" ::: "memory")
; #define PG8_WAIT_L(n) asm volatile("s_waitcnt lgkmcnt(" #n ")" ::: "memory")
; #define PG8_BAR __builtin_amdgcn_s_barrier()
; #define PG8_SCHED __builtin_amdgcn_sched_barrier(0)
; template <class Epi>
; DI void gemm_phase(LAS unsigned char* lds, const Gemm g, const StaticOrder& S, const Epi& E) {
;     ...
;             PG8_STAGE(PG8_SB(0, 1), b2 + hstep, voffB);
;             PG8_WAIT_V(6); PG8_BAR; PG8_MMA(1, 1, At, B1); PG8_BAR;
;             PG8_LDB(B0, 1, 0); PG8_SCHED; PG8_LDA(At, 1, 0); PG8_STAGE(PG8_SA(0, 1), a2 + hstep, voffA);
;             PG8_WAIT_L(8); PG8_BAR; PG8_WAIT_L(0); PG8_MMA(0, 0, At, B0); PG8_BAR; PG8_SCHED;
;             PG8_LDB(B1, 1, 1); PG8_STAGE(PG8_SB(1, 0), b3, voffB);
	s_add_u32 s44, s44, s12
	s_addc_u32 s45, s45, s13
	s_add_i32 s4, s4, s53
	v_lshl_add_u64 v[232:233], s[44:45], 0, v[166:167]
	s_mov_b32 m0, s4
	v_lshl_add_u64 v[234:235], s[44:45], 0, v[132:133]
	global_load_lds_dwordx4 v[232:233], off
	s_add_i32 m0, s4, 0x2000
	s_nop 0
	global_load_lds_dwordx4 v[234:235], off
	s_waitcnt vmcnt(6)
	s_barrier
	s_setprio 1
	v_mfma_f32_16x16x32_bf16 v[52:55], v[212:215], v[174:177], 0
	v_mfma_f32_16x16x32_bf16 v[48:51], v[220:223], v[174:177], 0
	v_mfma_f32_16x16x32_bf16 v[36:39], v[212:215], v[188:191], 0
	v_mfma_f32_16x16x32_bf16 v[32:35], v[220:223], v[188:191], 0
	v_mfma_f32_16x16x32_bf16 v[20:23], v[212:215], v[196:199], 0
	v_mfma_f32_16x16x32_bf16 v[16:19], v[220:223], v[196:199], 0
	v_mfma_f32_16x16x32_bf16 v[4:7], v[212:215], v[204:207], 0
	v_mfma_f32_16x16x32_bf16 v[0:3], v[220:223], v[204:207], 0
	v_mfma_f32_16x16x32_bf16 v[52:55], v[216:219], v[178:181], v[52:55]
	v_mfma_f32_16x16x32_bf16 v[48:51], v[224:227], v[178:181], v[48:51]
	v_mfma_f32_16x16x32_bf16 v[36:39], v[216:219], v[192:195], v[36:39]
	v_mfma_f32_16x16x32_bf16 v[32:35], v[224:227], v[192:195], v[32:35]
	v_mfma_f32_16x16x32_bf16 v[20:23], v[216:219], v[200:203], v[20:23]
	v_mfma_f32_16x16x32_bf16 v[16:19], v[224:227], v[200:203], v[16:19]
	v_mfma_f32_16x16x32_bf16 v[4:7], v[216:219], v[208:211], v[4:7]
	v_mfma_f32_16x16x32_bf16 v[0:3], v[224:227], v[208:211], v[0:3]
	s_setprio 0
	s_add_i32 s4, s74, 0x100
	v_add_u32_e32 v153, s4, v151
	s_barrier
	ds_read_b128 v[138:141], v153
	ds_read_b128 v[154:157], v153 offset:1024
	ds_read_b128 v[158:161], v153 offset:2048
	ds_read_b128 v[170:173], v153 offset:3072
	s_add_u32 s42, s42, s12
	s_addc_u32 s43, s43, s13
	s_mov_b32 m0, s56
	v_lshl_add_u64 v[212:213], s[42:43], 0, v[128:129]
	ds_read_b128 v[174:177], v152 offset:32768
	ds_read_b128 v[178:181], v152 offset:33792
	ds_read_b128 v[188:191], v152 offset:34816
	ds_read_b128 v[192:195], v152 offset:35840
	ds_read_b128 v[196:199], v152 offset:36864
	ds_read_b128 v[200:203], v152 offset:37888
	ds_read_b128 v[204:207], v152 offset:38912
	ds_read_b128 v[208:211], v152 offset:39936
	global_load_lds_dwordx4 v[212:213], off
	v_lshl_add_u64 v[212:213], s[42:43], 0, v[130:131]
	s_mov_b32 m0, s57
	s_nop 0
	global_load_lds_dwordx4 v[212:213], off
	s_waitcnt lgkmcnt(8)
	s_barrier
	s_waitcnt lgkmcnt(0)
	s_setprio 1
	s_waitcnt lgkmcnt(0)
	v_mfma_f32_16x16x32_bf16 v[124:127], v[138:141], v[174:177], v[124:127]
	v_mfma_f32_16x16x32_bf16 v[120:123], v[158:161], v[174:177], v[120:123]
	v_mfma_f32_16x16x32_bf16 v[108:111], v[138:141], v[188:191], v[108:111]
	v_mfma_f32_16x16x32_bf16 v[104:107], v[158:161], v[188:191], v[104:107]
	v_mfma_f32_16x16x32_bf16 v[92:95], v[138:141], v[196:199], v[92:95]
	v_mfma_f32_16x16x32_bf16 v[88:91], v[158:161], v[196:199], v[88:91]
	v_mfma_f32_16x16x32_bf16 v[76:79], v[138:141], v[204:207], v[76:79]
	v_mfma_f32_16x16x32_bf16 v[72:75], v[158:161], v[204:207], v[72:75]
	v_mfma_f32_16x16x32_bf16 v[124:127], v[154:157], v[178:181], v[124:127]
	v_mfma_f32_16x16x32_bf16 v[120:123], v[170:173], v[178:181], v[120:123]
	v_mfma_f32_16x16x32_bf16 v[108:111], v[154:157], v[192:195], v[108:111]
	v_mfma_f32_16x16x32_bf16 v[104:107], v[170:173], v[192:195], v[104:107]
	v_mfma_f32_16x16x32_bf16 v[92:95], v[154:157], v[200:203], v[92:95]
	v_mfma_f32_16x16x32_bf16 v[88:91], v[170:173], v[200:203], v[88:91]
	v_mfma_f32_16x16x32_bf16 v[76:79], v[154:157], v[208:211], v[76:79]
	v_mfma_f32_16x16x32_bf16 v[72:75], v[170:173], v[208:211], v[72:75]
	s_setprio 0
	s_barrier
	s_add_i32 s42, s75, 0x100
	s_add_i32 s4, s4, s53
	v_add_u32_e32 v153, s42, v151
	v_lshl_add_u64 v[162:163], v[162:163], 0, s[76:77]
	s_mov_b32 m0, s4
	ds_read_b128 v[212:215], v153
	ds_read_b128 v[216:219], v153 offset:1024
	ds_read_b128 v[220:223], v153 offset:2048
	ds_read_b128 v[224:227], v153 offset:3072
	global_load_lds_dwordx4 v[162:163], off
	v_lshl_add_u64 v[162:163], v[182:183], 0, s[76:77]
	s_add_i32 m0, s4, 0x2000
	s_nop 0
	global_load_lds_dwordx4 v[162:163], off
	s_barrier
; #define PG8_STAGE(bufoff, gbase, voff) do { _Pragma("unroll") for (int _i = 0; _i < 2; ++_i) \
;         __builtin_amdgcn_global_load_lds((const unsigned*)((const char*)(gbase) + (voff)[_i]), (LAS unsigned*)(lds + (bufoff) + ldsw + _i * 8192), 16, 0, 0); } while (0)
; #define PG8_LDA(dst, b, h) do { _Pragma("unroll") for (int m = 0; m < 4; ++m) _Pragma("unroll") for (int k = 0; k < 2; ++k) dst[m][k] = *(const LAS bf16x8*)(lds + PG8_SA(b, h) + aoff + m * 2048 + k * 1024); } while (0)
; #define PG8_MMA(ai, bj, At, Bt) do { __builtin_amdgcn_s_setprio(1); _Pragma("unroll") for (int m = 0; m < 4; ++m) _Pragma("unroll") for (int n = 0; n < 2; ++n) _Pragma("unroll") for (int k = 0; k < 2; ++k) \
;         acc[ai][bj][m][n] = __builtin_amdgcn_mfma_f32_16x16x32_bf16(Bt[n][k], At[m][k], acc[ai][bj][m][n], 0, 0, 0); __builtin_amdgcn_s_setprio(0); } while (0)
; #define PG8_WAIT_V(n) asm volatile("s_waitcnt vmcnt(" #n ")" ::: "memory")
; #define PG8_WAIT_L(n) asm volatile("s_waitcnt lgkmcnt(" #n ")" ::: "memory")
; #define PG8_BAR __builtin_amdgcn_s_barrier()
; #define PG8_SCHED __builtin_amdgcn_sched_barrier(0)
; template <class Epi>
; DI void gemm_phase(LAS unsigned char* lds, const Gemm g, const StaticOrder& S, const Epi& E) {
;     ...
;             PG8_BAR; PG8_WAIT_L(0); PG8_MMA(0, 1, At, B1); PG8_BAR;
;             PG8_LDA(At, 1, 1); PG8_STAGE(PG8_SA(1, 0), a3, voffA);
;             PG8_BAR; PG8_WAIT_L(0); PG8_MMA(1, 0, At, B0); PG8_BAR; PG8_SCHED;
;             PG8_STAGE(PG8_SB(1, 1), b3 + hstep, voffB);
;             PG8_WAIT_V(6); PG8_BAR; PG8_MMA(1, 1, At, B1); PG8_BAR;
	s_waitcnt lgkmcnt(0)
	s_setprio 1
	s_waitcnt lgkmcnt(0)
	v_mfma_f32_16x16x32_bf16 v[116:119], v[212:215], v[174:177], v[116:119]
	v_mfma_f32_16x16x32_bf16 v[112:115], v[220:223], v[174:177], v[112:115]
	v_mfma_f32_16x16x32_bf16 v[100:103], v[212:215], v[188:191], v[100:103]
	v_mfma_f32_16x16x32_bf16 v[96:99], v[220:223], v[188:191], v[96:99]
	v_mfma_f32_16x16x32_bf16 v[84:87], v[212:215], v[196:199], v[84:87]
	v_mfma_f32_16x16x32_bf16 v[80:83], v[220:223], v[196:199], v[80:83]
	v_mfma_f32_16x16x32_bf16 v[68:71], v[212:215], v[204:207], v[68:71]
	v_mfma_f32_16x16x32_bf16 v[64:67], v[220:223], v[204:207], v[64:67]
	v_mfma_f32_16x16x32_bf16 v[116:119], v[216:219], v[178:181], v[116:119]
	v_mfma_f32_16x16x32_bf16 v[112:115], v[224:227], v[178:181], v[112:115]
	v_mfma_f32_16x16x32_bf16 v[100:103], v[216:219], v[192:195], v[100:103]
	v_mfma_f32_16x16x32_bf16 v[96:99], v[224:227], v[192:195], v[96:99]
	v_mfma_f32_16x16x32_bf16 v[84:87], v[216:219], v[200:203], v[84:87]
	v_mfma_f32_16x16x32_bf16 v[80:83], v[224:227], v[200:203], v[80:83]
	v_mfma_f32_16x16x32_bf16 v[68:71], v[216:219], v[208:211], v[68:71]
	v_mfma_f32_16x16x32_bf16 v[64:67], v[224:227], v[208:211], v[64:67]
	s_setprio 0
	s_mov_b32 m0, s62
	v_lshl_add_u64 v[162:163], v[228:229], 0, s[76:77]
	s_barrier
	ds_read_b128 v[174:177], v152 offset:49152
	ds_read_b128 v[178:181], v152 offset:50176
	ds_read_b128 v[188:191], v152 offset:51200
	ds_read_b128 v[192:195], v152 offset:52224
	ds_read_b128 v[196:199], v152 offset:53248
	ds_read_b128 v[200:203], v152 offset:54272
	ds_read_b128 v[204:207], v152 offset:55296
	ds_read_b128 v[208:211], v152 offset:56320
	global_load_lds_dwordx4 v[162:163], off
	v_lshl_add_u64 v[162:163], v[230:231], 0, s[76:77]
	s_mov_b32 m0, s63
	s_nop 0
	global_load_lds_dwordx4 v[162:163], off
	s_barrier
	s_waitcnt lgkmcnt(0)
	s_setprio 1
	s_waitcnt lgkmcnt(0)
	v_mfma_f32_16x16x32_bf16 v[60:63], v[138:141], v[174:177], v[60:63]
	v_mfma_f32_16x16x32_bf16 v[56:59], v[158:161], v[174:177], v[56:59]
	v_mfma_f32_16x16x32_bf16 v[44:47], v[138:141], v[188:191], v[44:47]
	v_mfma_f32_16x16x32_bf16 v[40:43], v[158:161], v[188:191], v[40:43]
	v_mfma_f32_16x16x32_bf16 v[28:31], v[138:141], v[196:199], v[28:31]
	v_mfma_f32_16x16x32_bf16 v[24:27], v[158:161], v[196:199], v[24:27]
	v_mfma_f32_16x16x32_bf16 v[12:15], v[138:141], v[204:207], v[12:15]
	v_mfma_f32_16x16x32_bf16 v[8:11], v[158:161], v[204:207], v[8:11]
	v_mfma_f32_16x16x32_bf16 v[60:63], v[154:157], v[178:181], v[60:63]
	v_mfma_f32_16x16x32_bf16 v[56:59], v[170:173], v[178:181], v[56:59]
	v_mfma_f32_16x16x32_bf16 v[44:47], v[154:157], v[192:195], v[44:47]
	v_mfma_f32_16x16x32_bf16 v[40:43], v[170:173], v[192:195], v[40:43]
	v_mfma_f32_16x16x32_bf16 v[28:31], v[154:157], v[200:203], v[28:31]
	v_mfma_f32_16x16x32_bf16 v[24:27], v[170:173], v[200:203], v[24:27]
	v_mfma_f32_16x16x32_bf16 v[12:15], v[154:157], v[208:211], v[12:15]
	v_mfma_f32_16x16x32_bf16 v[8:11], v[170:173], v[208:211], v[8:11]
	s_setprio 0
	s_barrier
	s_add_i32 s4, s42, s53
	v_lshl_add_u64 v[138:139], v[232:233], 0, s[76:77]
	s_mov_b32 m0, s4
	s_nop 0
	global_load_lds_dwordx4 v[138:139], off
	v_lshl_add_u64 v[138:139], v[234:235], 0, s[76:77]
	s_add_i32 m0, s4, 0x2000
	s_nop 0
	global_load_lds_dwordx4 v[138:139], off
	s_waitcnt vmcnt(6)
	s_barrier
	s_setprio 1
	v_mfma_f32_16x16x32_bf16 v[52:55], v[212:215], v[174:177], v[52:55]
	v_mfma_f32_16x16x32_bf16 v[48:51], v[220:223], v[174:177], v[48:51]
	v_mfma_f32_16x16x32_bf16 v[36:39], v[212:215], v[188:191], v[36:39]
	v_mfma_f32_16x16x32_bf16 v[32:35], v[220:223], v[188:191], v[32:35]
	v_mfma_f32_16x16x32_bf16 v[20:23], v[212:215], v[196:199], v[20:23]
	v_mfma_f32_16x16x32_bf16 v[16:19], v[220:223], v[196:199], v[16:19]
	v_mfma_f32_16x16x32_bf16 v[4:7], v[212:215], v[204:207], v[4:7]
	v_mfma_f32_16x16x32_bf16 v[0:3], v[220:223], v[204:207], v[0:3]
	v_mfma_f32_16x16x32_bf16 v[52:55], v[216:219], v[178:181], v[52:55]
	v_mfma_f32_16x16x32_bf16 v[48:51], v[224:227], v[178:181], v[48:51]
	v_mfma_f32_16x16x32_bf16 v[36:39], v[216:219], v[192:195], v[36:39]
	v_mfma_f32_16x16x32_bf16 v[32:35], v[224:227], v[192:195], v[32:35]
	v_mfma_f32_16x16x32_bf16 v[20:23], v[216:219], v[200:203], v[20:23]
	v_mfma_f32_16x16x32_bf16 v[16:19], v[224:227], v[200:203], v[16:19]
	v_mfma_f32_16x16x32_bf16 v[4:7], v[216:219], v[208:211], v[4:7]
	v_mfma_f32_16x16x32_bf16 v[0:3], v[224:227], v[208:211], v[0:3]
	s_setprio 0
	s_add_u32 s40, s40, 0x100
	s_addc_u32 s41, s41, 0
	s_add_u32 s0, s0, 0x100
	s_addc_u32 s46, s46, 0
	s_cmp_ge_i32 s5, s59
	s_mov_b32 s4, s5
	s_barrier
	s_cbranch_scc0 .LBB0_1670
	s_branch .Lpeel_exit_6

; DI float blo(unsigned w) { return __uint_as_float(w << 16); }
; DI float bhi(unsigned w) { return __uint_as_float(w & 0xffff0000u); }
; DI u32x4 pk8(f32x4 a, f32x4 b) { u32x4 r; r.x = pk2(a[0], a[1]); r.y = pk2(a[2], a[3]); r.z = pk2(b[0], b[1]); r.w = pk2(b[2], b[3]); return r; }
;     DI void operator()(const Acc& acc, const pg8::Unit& u, int wr, int wc, int fr, int fq) const {
;         asm volatile("" : "+v"(fr), "+v"(fq));
;         const int row0 = u.pm * 256 + wr * 64 + fr, c0 = u.pn * 256 + wc * 32 + 8 * fq;
; #pragma unroll
;         for (int ai = 0; ai < 2; ++ai)
; #pragma unroll
;             for (int m = 0; m < 4; ++m) { const int row = row0 + ai * 128 + m * 16; float ss = 0.f;
; #pragma unroll
;                 for (int bj = 0; bj < 2; ++bj) { f32x4 v0 = acc[ai][bj][m][0], v1 = acc[ai][bj][m][1]; const size_t off = (size_t)row * 1024 + c0 + bj * 128;
;                     if (gate) { const u32x4 gw = *(const u32x4*)(gate + off);
;                         v0[0] *= blo(gw.x); v0[1] *= bhi(gw.x); v0[2] *= blo(gw.y); v0[3] *= bhi(gw.y); v1[0] *= blo(gw.z); v1[1] *= bhi(gw.z); v1[2] *= blo(gw.w); v1[3] *= bhi(gw.w); }
;                     *(u32x4*)(t + off) = pk8(v0, v1);
;                     ss += v0[0] * v0[0] + v0[1] * v0[1] + v0[2] * v0[2] + v0[3] * v0[3] + v1[0] * v1[0] + v1[1] * v1[1] + v1[2] * v1[2] + v1[3] * v1[3]; }
;                 ss += __shfl_xor(ss, 16); ss += __shfl_xor(ss, 32);
;                 if (fq == 0) ssq[row * 16 + u.pn * 4 + wc] = ss;
;                 asm volatile("" ::: "memory"); }
.Lpeel_exit_6:
.LBB0_1671:
	s_lshl_b32 s0, s89, 8
	v_mov_b32_e32 v138, v150
	v_mov_b32_e32 v141, v149
	s_add_i32 s0, s0, s60
	v_add_u32_e32 v153, 64, v148
	v_cmp_lt_i32_e32 vcc, v146, v153
	v_add_u32_e32 v140, s0, v138
	s_lshl_b32 s0, s88, 8
	s_or_b32 s0, s0, s61
	v_cndmask_b32_e32 v154, v184, v146, vcc
	v_cmp_lt_i32_e32 vcc, v147, v153
	v_lshl_add_u32 v138, v141, 3, s0
	v_ashrrev_i32_e32 v139, 31, v138
	v_cndmask_b32_e32 v153, v184, v147, vcc
	v_cmp_eq_u32_e32 vcc, 0, v141
	v_ashrrev_i32_e32 v141, 31, v140
	v_lshlrev_b64 v[156:157], 10, v[140:141]
	v_lshl_add_u64 v[156:157], v[156:157], 0, v[138:139]
	v_readlane_b32 s4, v237, 44
	v_lshlrev_b64 v[160:161], 1, v[156:157]
	v_readlane_b32 s5, v237, 45
	v_lshlrev_b32_e32 v154, 2, v154
	v_lshlrev_b32_e32 v153, 2, v153
	v_lshl_add_u64 v[162:163], s[4:5], 0, v[160:161]
	s_mov_b32 s100, 0x8000
	s_mov_b32 s101, 0
	s_mov_b32 s98, 0x28000
	s_mov_b32 s99, 0
	global_load_dwordx4 v[172:175], v[162:163], off offset:256
	v_lshl_add_u64 v[252:253], v[162:163], 0, s[100:101]
	global_load_dwordx4 v[176:179], v[252:253], off
	global_load_dwordx4 v[188:191], v[252:253], off offset:256
	v_lshl_add_u64 v[252:253], v[252:253], 0, s[100:101]
	global_load_dwordx4 v[192:195], v[252:253], off
	global_load_dwordx4 v[196:199], v[252:253], off offset:256
	v_lshl_add_u64 v[252:253], v[252:253], 0, s[100:101]
	global_load_dwordx4 v[200:203], v[252:253], off
	global_load_dwordx4 v[204:207], v[252:253], off offset:256
	v_lshl_add_u64 v[252:253], v[252:253], 0, s[98:99]
	global_load_dwordx4 v[208:211], v[252:253], off
	global_load_dwordx4 v[212:215], v[252:253], off offset:256
	v_lshl_add_u64 v[252:253], v[252:253], 0, s[100:101]
	global_load_dwordx4 v[216:219], v[252:253], off
	global_load_dwordx4 v[220:223], v[252:253], off offset:256
	v_lshl_add_u64 v[252:253], v[252:253], 0, s[100:101]
	global_load_dwordx4 v[224:227], v[252:253], off
	global_load_dwordx4 v[240:243], v[252:253], off offset:256
	v_lshl_add_u64 v[252:253], v[252:253], 0, s[100:101]
	global_load_dwordx4 v[244:247], v[252:253], off
	global_load_dwordx4 v[248:251], v[252:253], off offset:256
	global_load_dwordx4 v[156:159], v[162:163], off
	v_lshl_add_u64 v[160:161], s[2:3], 0, v[160:161]
	s_lshl_b32 s0, s88, 2
	s_or_b32 s42, s0, s58
	s_waitcnt vmcnt(0)
	v_lshlrev_b32_e32 v170, 16, v156
	v_and_b32_e32 v171, 0xffff0000, v156
	v_lshlrev_b32_e32 v156, 16, v157
	v_and_b32_e32 v157, 0xffff0000, v157
	v_pk_mul_f32 v[126:127], v[126:127], v[156:157]
	v_lshlrev_b32_e32 v156, 16, v158
	v_and_b32_e32 v157, 0xffff0000, v158
	v_pk_mul_f32 v[156:157], v[120:121], v[156:157]
	v_lshlrev_b32_e32 v120, 16, v159
	v_and_b32_e32 v121, 0xffff0000, v159
	v_pk_mul_f32 v[124:125], v[124:125], v[170:171]
	v_pk_mul_f32 v[158:159], v[122:123], v[120:121]
	v_cvt_pk_bf16_f32 v120, v124, v125
	v_cvt_pk_bf16_f32 v121, v126, v127
	v_cvt_pk_bf16_f32 v122, v156, v157
	v_cvt_pk_bf16_f32 v123, v158, v159
	global_store_dwordx4 v[160:161], v[120:123], off
	v_pk_mul_f32 v[170:171], v[124:125], v[124:125]
	s_nop 1
	v_mov_b32_e32 v122, v172
	v_mov_b32_e32 v123, v173
	v_mov_b32_e32 v124, v174
	v_mov_b32_e32 v125, v175
	v_pk_mul_f32 v[120:121], v[158:159], v[158:159]
	v_pk_mul_f32 v[126:127], v[126:127], v[126:127]
	v_pk_mul_f32 v[156:157], v[156:157], v[156:157]
	v_lshlrev_b32_e32 v158, 16, v122
	v_and_b32_e32 v159, 0xffff0000, v122
	v_lshlrev_b32_e32 v122, 16, v123
	v_and_b32_e32 v123, 0xffff0000, v123
	v_pk_mul_f32 v[118:119], v[118:119], v[122:123]
	v_lshlrev_b32_e32 v122, 16, v124
	v_and_b32_e32 v123, 0xffff0000, v124
	v_pk_mul_f32 v[122:123], v[112:113], v[122:123]
	v_lshlrev_b32_e32 v112, 16, v125
	v_and_b32_e32 v113, 0xffff0000, v125
	v_pk_mul_f32 v[116:117], v[116:117], v[158:159]
	v_pk_mul_f32 v[124:125], v[114:115], v[112:113]
	v_cvt_pk_bf16_f32 v112, v116, v117
	v_cvt_pk_bf16_f32 v113, v118, v119
	v_cvt_pk_bf16_f32 v114, v122, v123
	v_cvt_pk_bf16_f32 v115, v124, v125
	global_store_dwordx4 v[160:161], v[112:115], off offset:256
	s_nop 1
	v_pk_mul_f32 v[112:113], v[116:117], v[116:117]
	v_pk_mul_f32 v[114:115], v[118:119], v[118:119]
	v_pk_mul_f32 v[116:117], v[122:123], v[122:123]
	v_add_f32_e32 v122, v170, v171
	v_add_f32_e32 v112, v112, v113
	v_add_f32_e32 v122, v126, v122
	v_add_f32_e32 v112, v114, v112
	v_add_f32_e32 v122, v127, v122
	v_add_f32_e32 v112, v115, v112
	v_add_f32_e32 v122, v156, v122
	v_add_f32_e32 v112, v116, v112
	v_pk_mul_f32 v[118:119], v[124:125], v[124:125]
	v_add_f32_e32 v122, v157, v122
	v_add_f32_e32 v112, v117, v112
	v_add_f32_e32 v120, v120, v122
	v_add_f32_e32 v112, v118, v112
	v_add_f32_e32 v120, v121, v120
	v_add_f32_e32 v112, v119, v112
	v_add_f32_e32 v112, v120, v112
	ds_bpermute_b32 v113, v154, v112
	s_waitcnt lgkmcnt(0)
	v_add_f32_e32 v112, v112, v113
	ds_bpermute_b32 v113, v153, v112
	s_and_saveexec_b64 s[40:41], vcc
	s_cbranch_execz .LBB0_1673
	v_lshl_add_u32 v114, v140, 4, s42
	v_readlane_b32 s4, v238, 28
	v_ashrrev_i32_e32 v115, 31, v114
	v_readlane_b32 s5, v238, 29
	s_waitcnt lgkmcnt(0)
	v_add_f32_e32 v112, v112, v113
	v_lshl_add_u64 v[114:115], v[114:115], 2, s[4:5]
	global_store_dword v[114:115], v112, off
